# GEMM K-loops (7): back-edge counter/pointer SALU block and exit compare moved in front of the loop-back barrier (7.11 rotation)
# baseline (speedup 1.0000x reference)
; #define PG8_STAGE(bufoff, gbase, voff) do { _Pragma("unroll") for (int _i = 0; _i < 2; ++_i) \
;         __builtin_amdgcn_global_load_lds((const unsigned*)((const char*)(gbase) + (voff)[_i]), (PG8_LAS unsigned*)(lds + (bufoff) + ldsw + _i * 8192), 16, 0, 0); } while (0)
; #define PG8_LDA(dst, b, h) do { _Pragma("unroll") for (int m = 0; m < 4; ++m) _Pragma("unroll") for (int k = 0; k < 2; ++k) dst[m][k] = *(const PG8_LAS bf16x8*)(lds + PG8_SA(b, h) + aoff + m * 2048 + k * 1024); } while (0)
; #define PG8_LDB(dst, b, h) do { _Pragma("unroll") for (int n = 0; n < 2; ++n) _Pragma("unroll") for (int k = 0; k < 2; ++k) dst[n][k] = *(const PG8_LAS bf16x8*)(lds + PG8_SB(b, h) + boff + n * 2048 + k * 1024); } while (0)
; #define PG8_MMA(ai, bj, At, Bt) do { __builtin_amdgcn_s_setprio(1); _Pragma("unroll") for (int m = 0; m < 4; ++m) _Pragma("unroll") for (int n = 0; n < 2; ++n) _Pragma("unroll") for (int k = 0; k < 2; ++k) \
;         acc[ai][bj][m][n] = __builtin_amdgcn_mfma_f32_16x16x32_bf16(Bt[n][k], At[m][k], acc[ai][bj][m][n], 0, 0, 0); __builtin_amdgcn_s_setprio(0); } while (0)
; #define PG8_WAIT_V(n) asm volatile("s_waitcnt vmcnt(" #n ")" ::: "memory")
; #define PG8_WAIT_L(n) asm volatile("s_waitcnt lgkmcnt(" #n ")" ::: "memory")
; #define PG8_BAR __builtin_amdgcn_s_barrier()
; #define PG8_SCHED __builtin_amdgcn_sched_barrier(0)
; template <class Epi, class Sched>
; __device__ __forceinline__ void gemm_phase(PG8_LAS unsigned char* lds, const Gemm g, const Sched& S, const Epi& E) {
;     ...
;         for (int t = 0; t < nt; t += 2) {
;             const bool last = (t == nt - 2);
;             const char* a1 = cA + (size_t)(t + 1) * kstep;
;             const char* a2 = last ? nA : cA + (size_t)(t + 2) * kstep; const char* b2 = last ? nB : cB + (size_t)(t + 2) * kstep;
;             const char* a3 = a2 + kstep; const char* b3 = b2 + kstep;
;             PG8_LDB(B0, 0, 0); PG8_LDB(B1, 0, 1); PG8_SCHED; PG8_LDA(At, 0, 0); PG8_STAGE(PG8_SA(1, 1), a1 + hstepA, voffA);
;             PG8_WAIT_V(8); PG8_WAIT_L(0); PG8_BAR; PG8_MMA(0, 0, At, B0); PG8_MMA(0, 1, At, B1); PG8_BAR; PG8_SCHED;
;             PG8_LDA(At, 0, 1); PG8_STAGE(PG8_SB(0, 0), b2, voffB); PG8_STAGE(PG8_SB(0, 1), b2 + hstepB, voffB); PG8_STAGE(PG8_SA(0, 0), a2, voffA);
;             PG8_WAIT_V(8); PG8_WAIT_L(0); PG8_BAR; PG8_MMA(1, 0, At, B0); PG8_MMA(1, 1, At, B1); PG8_BAR; PG8_SCHED;
.LBB0_127:
	ds_read_b128 v[146:149], v154
	ds_read_b128 v[160:163], v154 offset:1024
	ds_read_b128 v[164:167], v154 offset:2048
	ds_read_b128 v[168:171], v154 offset:3072
	ds_read_b128 v[172:175], v155
	ds_read_b128 v[176:179], v155 offset:1024
	ds_read_b128 v[180:183], v155 offset:2048
	ds_read_b128 v[184:187], v155 offset:3072
	s_add_u32 s30, s28, 0xfff00080
	s_addc_u32 s31, s29, -1
	s_cmp_eq_u32 s94, 60
	s_cselect_b32 s35, s7, s31
	s_cselect_b32 s34, s21, s30
	s_cselect_b32 s31, s19, s93
	s_cselect_b32 s30, s27, s92
	v_lshl_add_u64 v[150:151], s[28:29], 0, v[138:139]
	s_add_i32 m0, s38, 0xc000
	ds_read_b128 v[188:191], v156
	ds_read_b128 v[192:195], v156 offset:1024
	ds_read_b128 v[196:199], v156 offset:2048
	ds_read_b128 v[200:203], v156 offset:3072
	ds_read_b128 v[204:207], v156 offset:4096
	ds_read_b128 v[210:213], v156 offset:5120
	ds_read_b128 v[214:217], v156 offset:6144
	ds_read_b128 v[218:221], v156 offset:7168
	global_load_lds_dwordx4 v[150:151], off
	v_lshl_add_u64 v[150:151], s[28:29], 0, v[140:141]
	s_add_i32 m0, s38, 0xe000
	s_nop 0
	global_load_lds_dwordx4 v[150:151], off
	s_waitcnt vmcnt(8)
	s_waitcnt lgkmcnt(0)
	s_barrier
	s_setprio 1
	s_waitcnt lgkmcnt(0)
	v_mfma_f32_16x16x32_bf16 v[126:129], v[146:149], v[188:191], v[126:129]
	v_mfma_f32_16x16x32_bf16 v[122:125], v[164:167], v[188:191], v[122:125]
	v_mfma_f32_16x16x32_bf16 v[110:113], v[146:149], v[196:199], v[110:113]
	v_mfma_f32_16x16x32_bf16 v[106:109], v[164:167], v[196:199], v[106:109]
	v_mfma_f32_16x16x32_bf16 v[94:97], v[146:149], v[204:207], v[94:97]
	v_mfma_f32_16x16x32_bf16 v[90:93], v[164:167], v[204:207], v[90:93]
	v_mfma_f32_16x16x32_bf16 v[78:81], v[146:149], v[214:217], v[78:81]
	v_mfma_f32_16x16x32_bf16 v[74:77], v[164:167], v[214:217], v[74:77]
	v_mfma_f32_16x16x32_bf16 v[126:129], v[160:163], v[192:195], v[126:129]
	v_mfma_f32_16x16x32_bf16 v[122:125], v[168:171], v[192:195], v[122:125]
	v_mfma_f32_16x16x32_bf16 v[110:113], v[160:163], v[200:203], v[110:113]
	v_mfma_f32_16x16x32_bf16 v[106:109], v[168:171], v[200:203], v[106:109]
	v_mfma_f32_16x16x32_bf16 v[94:97], v[160:163], v[210:213], v[94:97]
	v_mfma_f32_16x16x32_bf16 v[90:93], v[168:171], v[210:213], v[90:93]
	v_mfma_f32_16x16x32_bf16 v[78:81], v[160:163], v[218:221], v[78:81]
	v_mfma_f32_16x16x32_bf16 v[74:77], v[168:171], v[218:221], v[74:77]
	s_setprio 0
	s_setprio 1
	v_mfma_f32_16x16x32_bf16 v[118:121], v[172:175], v[188:191], v[118:121]
	v_mfma_f32_16x16x32_bf16 v[114:117], v[180:183], v[188:191], v[114:117]
	v_mfma_f32_16x16x32_bf16 v[102:105], v[172:175], v[196:199], v[102:105]
	v_mfma_f32_16x16x32_bf16 v[98:101], v[180:183], v[196:199], v[98:101]
	v_mfma_f32_16x16x32_bf16 v[86:89], v[172:175], v[204:207], v[86:89]
	v_mfma_f32_16x16x32_bf16 v[82:85], v[180:183], v[204:207], v[82:85]
	v_mfma_f32_16x16x32_bf16 v[70:73], v[172:175], v[214:217], v[70:73]
	v_mfma_f32_16x16x32_bf16 v[66:69], v[180:183], v[214:217], v[66:69]
	v_mfma_f32_16x16x32_bf16 v[118:121], v[176:179], v[192:195], v[118:121]
	v_mfma_f32_16x16x32_bf16 v[114:117], v[184:187], v[192:195], v[114:117]
	v_mfma_f32_16x16x32_bf16 v[102:105], v[176:179], v[200:203], v[102:105]
	v_mfma_f32_16x16x32_bf16 v[98:101], v[184:187], v[200:203], v[98:101]
	v_mfma_f32_16x16x32_bf16 v[86:89], v[176:179], v[210:213], v[86:89]
	v_mfma_f32_16x16x32_bf16 v[82:85], v[184:187], v[210:213], v[82:85]
	v_mfma_f32_16x16x32_bf16 v[70:73], v[176:179], v[218:221], v[70:73]
	v_mfma_f32_16x16x32_bf16 v[66:69], v[184:187], v[218:221], v[66:69]
	s_setprio 0
	s_barrier
	s_add_i32 s66, s88, s37
	v_lshl_add_u64 v[150:151], s[30:31], 0, v[132:133]
	s_mov_b32 m0, s66
	ds_read_b128 v[188:191], v156 offset:16384
	ds_read_b128 v[192:195], v156 offset:17408
	ds_read_b128 v[196:199], v156 offset:18432
	ds_read_b128 v[200:203], v156 offset:19456
	ds_read_b128 v[204:207], v156 offset:20480
	ds_read_b128 v[210:213], v156 offset:21504
	ds_read_b128 v[214:217], v156 offset:22528
	ds_read_b128 v[218:221], v156 offset:23552
	global_load_lds_dwordx4 v[150:151], off
	s_add_i32 m0, s66, 0x2000
	s_add_u32 s96, s30, 0x100000
	v_lshl_add_u64 v[222:223], s[30:31], 0, v[136:137]
	s_addc_u32 s97, s31, 0
	s_add_i32 s66, s89, s37
	global_load_lds_dwordx4 v[222:223], off
	v_lshl_add_u64 v[224:225], s[96:97], 0, v[132:133]
	s_mov_b32 m0, s66
	v_lshl_add_u64 v[226:227], s[34:35], 0, v[134:135]
	global_load_lds_dwordx4 v[224:225], off
	v_lshl_add_u64 v[224:225], s[96:97], 0, v[136:137]
	s_add_i32 m0, s66, 0x2000
	s_nop 0
	global_load_lds_dwordx4 v[224:225], off
	v_lshl_add_u64 v[224:225], s[34:35], 0, v[130:131]
	s_mov_b32 m0, s38
	s_nop 0
	global_load_lds_dwordx4 v[224:225], off
	s_mov_b32 m0, s39
	s_nop 0
	global_load_lds_dwordx4 v[226:227], off
	s_waitcnt vmcnt(8)
	s_waitcnt lgkmcnt(0)
	s_barrier
; #define PG8_STAGE(bufoff, gbase, voff) do { _Pragma("unroll") for (int _i = 0; _i < 2; ++_i) \
;         __builtin_amdgcn_global_load_lds((const unsigned*)((const char*)(gbase) + (voff)[_i]), (PG8_LAS unsigned*)(lds + (bufoff) + ldsw + _i * 8192), 16, 0, 0); } while (0)
; #define PG8_LDA(dst, b, h) do { _Pragma("unroll") for (int m = 0; m < 4; ++m) _Pragma("unroll") for (int k = 0; k < 2; ++k) dst[m][k] = *(const PG8_LAS bf16x8*)(lds + PG8_SA(b, h) + aoff + m * 2048 + k * 1024); } while (0)
; #define PG8_LDB(dst, b, h) do { _Pragma("unroll") for (int n = 0; n < 2; ++n) _Pragma("unroll") for (int k = 0; k < 2; ++k) dst[n][k] = *(const PG8_LAS bf16x8*)(lds + PG8_SB(b, h) + boff + n * 2048 + k * 1024); } while (0)
; #define PG8_MMA(ai, bj, At, Bt) do { __builtin_amdgcn_s_setprio(1); _Pragma("unroll") for (int m = 0; m < 4; ++m) _Pragma("unroll") for (int n = 0; n < 2; ++n) _Pragma("unroll") for (int k = 0; k < 2; ++k) \
;         acc[ai][bj][m][n] = __builtin_amdgcn_mfma_f32_16x16x32_bf16(Bt[n][k], At[m][k], acc[ai][bj][m][n], 0, 0, 0); __builtin_amdgcn_s_setprio(0); } while (0)
; #define PG8_WAIT_V(n) asm volatile("s_waitcnt vmcnt(" #n ")" ::: "memory")
; #define PG8_WAIT_L(n) asm volatile("s_waitcnt lgkmcnt(" #n ")" ::: "memory")
; #define PG8_BAR __builtin_amdgcn_s_barrier()
; #define PG8_SCHED __builtin_amdgcn_sched_barrier(0)
; template <class Epi, class Sched>
; __device__ __forceinline__ void gemm_phase(PG8_LAS unsigned char* lds, const Gemm g, const Sched& S, const Epi& E) {
;     ...
;             PG8_WAIT_V(8); PG8_WAIT_L(0); PG8_BAR; PG8_MMA(1, 0, At, B0); PG8_MMA(1, 1, At, B1); PG8_BAR; PG8_SCHED;
;             PG8_LDB(B0, 1, 0); PG8_LDB(B1, 1, 1); PG8_SCHED; PG8_LDA(At, 1, 0); PG8_STAGE(PG8_SA(0, 1), a2 + hstepA, voffA);
;             PG8_WAIT_V(8); PG8_WAIT_L(0); PG8_BAR; PG8_MMA(0, 0, At, B0); PG8_MMA(0, 1, At, B1); PG8_BAR; PG8_SCHED;
	s_setprio 1
	s_waitcnt lgkmcnt(0)
	v_mfma_f32_16x16x32_bf16 v[62:65], v[146:149], v[188:191], v[62:65]
	v_mfma_f32_16x16x32_bf16 v[58:61], v[164:167], v[188:191], v[58:61]
	v_mfma_f32_16x16x32_bf16 v[46:49], v[146:149], v[196:199], v[46:49]
	v_mfma_f32_16x16x32_bf16 v[42:45], v[164:167], v[196:199], v[42:45]
	v_mfma_f32_16x16x32_bf16 v[30:33], v[146:149], v[204:207], v[30:33]
	v_mfma_f32_16x16x32_bf16 v[26:29], v[164:167], v[204:207], v[26:29]
	v_mfma_f32_16x16x32_bf16 v[14:17], v[146:149], v[214:217], v[14:17]
	v_mfma_f32_16x16x32_bf16 v[10:13], v[164:167], v[214:217], v[10:13]
	v_mfma_f32_16x16x32_bf16 v[62:65], v[160:163], v[192:195], v[62:65]
	v_mfma_f32_16x16x32_bf16 v[58:61], v[168:171], v[192:195], v[58:61]
	v_mfma_f32_16x16x32_bf16 v[46:49], v[160:163], v[200:203], v[46:49]
	v_mfma_f32_16x16x32_bf16 v[42:45], v[168:171], v[200:203], v[42:45]
	v_mfma_f32_16x16x32_bf16 v[30:33], v[160:163], v[210:213], v[30:33]
	v_mfma_f32_16x16x32_bf16 v[26:29], v[168:171], v[210:213], v[26:29]
	v_mfma_f32_16x16x32_bf16 v[14:17], v[160:163], v[218:221], v[14:17]
	v_mfma_f32_16x16x32_bf16 v[10:13], v[168:171], v[218:221], v[10:13]
	s_setprio 0
	s_setprio 1
	v_mfma_f32_16x16x32_bf16 v[54:57], v[172:175], v[188:191], v[54:57]
	v_mfma_f32_16x16x32_bf16 v[50:53], v[180:183], v[188:191], v[50:53]
	v_mfma_f32_16x16x32_bf16 v[38:41], v[172:175], v[196:199], v[38:41]
	v_mfma_f32_16x16x32_bf16 v[34:37], v[180:183], v[196:199], v[34:37]
	v_mfma_f32_16x16x32_bf16 v[22:25], v[172:175], v[204:207], v[22:25]
	v_mfma_f32_16x16x32_bf16 v[18:21], v[180:183], v[204:207], v[18:21]
	v_mfma_f32_16x16x32_bf16 v[6:9], v[172:175], v[214:217], v[6:9]
	v_mfma_f32_16x16x32_bf16 v[2:5], v[180:183], v[214:217], v[2:5]
	v_mfma_f32_16x16x32_bf16 v[54:57], v[176:179], v[192:195], v[54:57]
	v_mfma_f32_16x16x32_bf16 v[50:53], v[184:187], v[192:195], v[50:53]
	v_mfma_f32_16x16x32_bf16 v[38:41], v[176:179], v[200:203], v[38:41]
	v_mfma_f32_16x16x32_bf16 v[34:37], v[184:187], v[200:203], v[34:37]
	v_mfma_f32_16x16x32_bf16 v[22:25], v[176:179], v[210:213], v[22:25]
	v_mfma_f32_16x16x32_bf16 v[18:21], v[184:187], v[210:213], v[18:21]
	v_mfma_f32_16x16x32_bf16 v[6:9], v[176:179], v[218:221], v[6:9]
	v_mfma_f32_16x16x32_bf16 v[2:5], v[184:187], v[218:221], v[2:5]
	s_setprio 0
	s_barrier
	s_add_i32 s66, 0, 0x18000
	v_add_u32_e32 v159, s66, v152
	s_add_i32 s67, 0, 0x1c000
	ds_read_b128 v[146:149], v159
	ds_read_b128 v[160:163], v159 offset:1024
	ds_read_b128 v[164:167], v159 offset:2048
	ds_read_b128 v[168:171], v159 offset:3072
	v_add_u32_e32 v159, s67, v152
	ds_read_b128 v[172:175], v159
	ds_read_b128 v[176:179], v159 offset:1024
	ds_read_b128 v[180:183], v159 offset:2048
	ds_read_b128 v[184:187], v159 offset:3072
	s_add_u32 s34, s34, 0x100000
	s_addc_u32 s35, s35, 0
	s_mov_b32 m0, s40
	v_lshl_add_u64 v[228:229], s[34:35], 0, v[130:131]
	ds_read_b128 v[188:191], v156 offset:32768
	ds_read_b128 v[192:195], v156 offset:33792
	ds_read_b128 v[196:199], v156 offset:34816
	ds_read_b128 v[200:203], v156 offset:35840
	ds_read_b128 v[204:207], v156 offset:36864
	ds_read_b128 v[210:213], v156 offset:37888
	ds_read_b128 v[214:217], v156 offset:38912
	ds_read_b128 v[218:221], v156 offset:39936
	global_load_lds_dwordx4 v[228:229], off
	v_lshl_add_u64 v[228:229], s[34:35], 0, v[134:135]
	s_mov_b32 m0, s41
	s_nop 0
	global_load_lds_dwordx4 v[228:229], off
	s_waitcnt vmcnt(8)
	s_waitcnt lgkmcnt(0)
	s_barrier
	s_setprio 1
	s_waitcnt lgkmcnt(0)
	v_mfma_f32_16x16x32_bf16 v[126:129], v[146:149], v[188:191], v[126:129]
	v_mfma_f32_16x16x32_bf16 v[122:125], v[164:167], v[188:191], v[122:125]
	v_mfma_f32_16x16x32_bf16 v[110:113], v[146:149], v[196:199], v[110:113]
	v_mfma_f32_16x16x32_bf16 v[106:109], v[164:167], v[196:199], v[106:109]
	v_mfma_f32_16x16x32_bf16 v[94:97], v[146:149], v[204:207], v[94:97]
	v_mfma_f32_16x16x32_bf16 v[90:93], v[164:167], v[204:207], v[90:93]
	v_mfma_f32_16x16x32_bf16 v[78:81], v[146:149], v[214:217], v[78:81]
	v_mfma_f32_16x16x32_bf16 v[74:77], v[164:167], v[214:217], v[74:77]
	v_mfma_f32_16x16x32_bf16 v[126:129], v[160:163], v[192:195], v[126:129]
	v_mfma_f32_16x16x32_bf16 v[122:125], v[168:171], v[192:195], v[122:125]
	v_mfma_f32_16x16x32_bf16 v[110:113], v[160:163], v[200:203], v[110:113]
	v_mfma_f32_16x16x32_bf16 v[106:109], v[168:171], v[200:203], v[106:109]
	v_mfma_f32_16x16x32_bf16 v[94:97], v[160:163], v[210:213], v[94:97]
	v_mfma_f32_16x16x32_bf16 v[90:93], v[168:171], v[210:213], v[90:93]
	v_mfma_f32_16x16x32_bf16 v[78:81], v[160:163], v[218:221], v[78:81]
	v_mfma_f32_16x16x32_bf16 v[74:77], v[168:171], v[218:221], v[74:77]
	s_setprio 0
	s_setprio 1
	v_mfma_f32_16x16x32_bf16 v[118:121], v[172:175], v[188:191], v[118:121]
	v_mfma_f32_16x16x32_bf16 v[114:117], v[180:183], v[188:191], v[114:117]
	v_mfma_f32_16x16x32_bf16 v[102:105], v[172:175], v[196:199], v[102:105]
	v_mfma_f32_16x16x32_bf16 v[98:101], v[180:183], v[196:199], v[98:101]
	v_mfma_f32_16x16x32_bf16 v[86:89], v[172:175], v[204:207], v[86:89]
	v_mfma_f32_16x16x32_bf16 v[82:85], v[180:183], v[204:207], v[82:85]
	v_mfma_f32_16x16x32_bf16 v[70:73], v[172:175], v[214:217], v[70:73]
	v_mfma_f32_16x16x32_bf16 v[66:69], v[180:183], v[214:217], v[66:69]
	v_mfma_f32_16x16x32_bf16 v[118:121], v[176:179], v[192:195], v[118:121]
	v_mfma_f32_16x16x32_bf16 v[114:117], v[184:187], v[192:195], v[114:117]
	v_mfma_f32_16x16x32_bf16 v[102:105], v[176:179], v[200:203], v[102:105]
	v_mfma_f32_16x16x32_bf16 v[98:101], v[184:187], v[200:203], v[98:101]
	v_mfma_f32_16x16x32_bf16 v[86:89], v[176:179], v[210:213], v[86:89]
	v_mfma_f32_16x16x32_bf16 v[82:85], v[184:187], v[210:213], v[82:85]
	v_mfma_f32_16x16x32_bf16 v[70:73], v[176:179], v[218:221], v[70:73]
	v_mfma_f32_16x16x32_bf16 v[66:69], v[184:187], v[218:221], v[66:69]
	s_setprio 0
	s_barrier
; #define PG8_STAGE(bufoff, gbase, voff) do { _Pragma("unroll") for (int _i = 0; _i < 2; ++_i) \
;         __builtin_amdgcn_global_load_lds((const unsigned*)((const char*)(gbase) + (voff)[_i]), (PG8_LAS unsigned*)(lds + (bufoff) + ldsw + _i * 8192), 16, 0, 0); } while (0)
; #define PG8_LDA(dst, b, h) do { _Pragma("unroll") for (int m = 0; m < 4; ++m) _Pragma("unroll") for (int k = 0; k < 2; ++k) dst[m][k] = *(const PG8_LAS bf16x8*)(lds + PG8_SA(b, h) + aoff + m * 2048 + k * 1024); } while (0)
; #define PG8_MMA(ai, bj, At, Bt) do { __builtin_amdgcn_s_setprio(1); _Pragma("unroll") for (int m = 0; m < 4; ++m) _Pragma("unroll") for (int n = 0; n < 2; ++n) _Pragma("unroll") for (int k = 0; k < 2; ++k) \
;         acc[ai][bj][m][n] = __builtin_amdgcn_mfma_f32_16x16x32_bf16(Bt[n][k], At[m][k], acc[ai][bj][m][n], 0, 0, 0); __builtin_amdgcn_s_setprio(0); } while (0)
; #define PG8_WAIT_V(n) asm volatile("s_waitcnt vmcnt(" #n ")" ::: "memory")
; #define PG8_WAIT_L(n) asm volatile("s_waitcnt lgkmcnt(" #n ")" ::: "memory")
; #define PG8_BAR __builtin_amdgcn_s_barrier()
; #define PG8_SCHED __builtin_amdgcn_sched_barrier(0)
; template <class Epi, class Sched>
; __device__ __forceinline__ void gemm_phase(PG8_LAS unsigned char* lds, const Gemm g, const Sched& S, const Epi& E) {
;     ...
;         for (int t = 0; t < nt; t += 2) {
;     ...
;             PG8_LDA(At, 1, 1); PG8_STAGE(PG8_SB(1, 0), b3, voffB); PG8_STAGE(PG8_SB(1, 1), b3 + hstepB, voffB); PG8_STAGE(PG8_SA(1, 0), a3, voffA);
;             PG8_WAIT_V(8); PG8_WAIT_L(0); PG8_BAR; PG8_MMA(1, 0, At, B0); PG8_MMA(1, 1, At, B1); PG8_BAR; PG8_SCHED;
;         }
;         if (wr == 0) PG8_BAR;
	s_add_i32 s34, s66, s37
	v_lshl_add_u64 v[150:151], v[150:151], 0, s[14:15]
	s_mov_b32 m0, s34
	ds_read_b128 v[188:191], v156 offset:49152
	ds_read_b128 v[192:195], v156 offset:50176
	ds_read_b128 v[196:199], v156 offset:51200
	ds_read_b128 v[200:203], v156 offset:52224
	ds_read_b128 v[204:207], v156 offset:53248
	ds_read_b128 v[210:213], v156 offset:54272
	ds_read_b128 v[214:217], v156 offset:55296
	ds_read_b128 v[218:221], v156 offset:56320
	global_load_lds_dwordx4 v[150:151], off
	s_add_i32 m0, s34, 0x2000
	s_add_u32 s30, s30, 0x100080
	v_lshl_add_u64 v[150:151], v[222:223], 0, s[14:15]
	s_addc_u32 s31, s31, 0
	s_add_i32 s34, s67, s37
	global_load_lds_dwordx4 v[150:151], off
	v_lshl_add_u64 v[150:151], s[30:31], 0, v[132:133]
	s_mov_b32 m0, s34
	s_nop 0
	global_load_lds_dwordx4 v[150:151], off
	v_lshl_add_u64 v[150:151], s[30:31], 0, v[136:137]
	s_add_i32 m0, s34, 0x2000
	s_nop 0
	global_load_lds_dwordx4 v[150:151], off
	v_lshl_add_u64 v[150:151], v[224:225], 0, s[14:15]
	s_mov_b32 m0, s50
	s_nop 0
	global_load_lds_dwordx4 v[150:151], off
	v_lshl_add_u64 v[150:151], v[226:227], 0, s[14:15]
	s_mov_b32 m0, s51
	s_nop 0
	global_load_lds_dwordx4 v[150:151], off
	s_waitcnt vmcnt(8)
	s_waitcnt lgkmcnt(0)
	s_barrier
	s_setprio 1
	s_waitcnt lgkmcnt(0)
	v_mfma_f32_16x16x32_bf16 v[62:65], v[146:149], v[188:191], v[62:65]
	v_mfma_f32_16x16x32_bf16 v[58:61], v[164:167], v[188:191], v[58:61]
	v_mfma_f32_16x16x32_bf16 v[46:49], v[146:149], v[196:199], v[46:49]
	v_mfma_f32_16x16x32_bf16 v[42:45], v[164:167], v[196:199], v[42:45]
	v_mfma_f32_16x16x32_bf16 v[30:33], v[146:149], v[204:207], v[30:33]
	v_mfma_f32_16x16x32_bf16 v[26:29], v[164:167], v[204:207], v[26:29]
	v_mfma_f32_16x16x32_bf16 v[14:17], v[146:149], v[214:217], v[14:17]
	v_mfma_f32_16x16x32_bf16 v[10:13], v[164:167], v[214:217], v[10:13]
	v_mfma_f32_16x16x32_bf16 v[62:65], v[160:163], v[192:195], v[62:65]
	v_mfma_f32_16x16x32_bf16 v[58:61], v[168:171], v[192:195], v[58:61]
	v_mfma_f32_16x16x32_bf16 v[46:49], v[160:163], v[200:203], v[46:49]
	v_mfma_f32_16x16x32_bf16 v[42:45], v[168:171], v[200:203], v[42:45]
	v_mfma_f32_16x16x32_bf16 v[30:33], v[160:163], v[210:213], v[30:33]
	v_mfma_f32_16x16x32_bf16 v[26:29], v[168:171], v[210:213], v[26:29]
	v_mfma_f32_16x16x32_bf16 v[14:17], v[160:163], v[218:221], v[14:17]
	v_mfma_f32_16x16x32_bf16 v[10:13], v[168:171], v[218:221], v[10:13]
	s_setprio 0
	s_setprio 1
	v_mfma_f32_16x16x32_bf16 v[54:57], v[172:175], v[188:191], v[54:57]
	v_mfma_f32_16x16x32_bf16 v[50:53], v[180:183], v[188:191], v[50:53]
	v_mfma_f32_16x16x32_bf16 v[38:41], v[172:175], v[196:199], v[38:41]
	v_mfma_f32_16x16x32_bf16 v[34:37], v[180:183], v[196:199], v[34:37]
	v_mfma_f32_16x16x32_bf16 v[22:25], v[172:175], v[204:207], v[22:25]
	v_mfma_f32_16x16x32_bf16 v[18:21], v[180:183], v[204:207], v[18:21]
	v_mfma_f32_16x16x32_bf16 v[6:9], v[172:175], v[214:217], v[6:9]
	v_mfma_f32_16x16x32_bf16 v[2:5], v[180:183], v[214:217], v[2:5]
	v_mfma_f32_16x16x32_bf16 v[54:57], v[176:179], v[192:195], v[54:57]
	v_mfma_f32_16x16x32_bf16 v[50:53], v[184:187], v[192:195], v[50:53]
	v_mfma_f32_16x16x32_bf16 v[38:41], v[176:179], v[200:203], v[38:41]
	v_mfma_f32_16x16x32_bf16 v[34:37], v[184:187], v[200:203], v[34:37]
	v_mfma_f32_16x16x32_bf16 v[22:25], v[176:179], v[210:213], v[22:25]
	v_mfma_f32_16x16x32_bf16 v[18:21], v[184:187], v[210:213], v[18:21]
	v_mfma_f32_16x16x32_bf16 v[6:9], v[176:179], v[218:221], v[6:9]
	v_mfma_f32_16x16x32_bf16 v[2:5], v[184:187], v[218:221], v[2:5]
	s_setprio 0
	s_add_i32 s94, s94, 2
	s_add_u32 s28, s28, 0x100
	s_addc_u32 s29, s29, 0
	s_add_u32 s92, s92, 0x100
	s_addc_u32 s93, s93, 0
	s_cmp_gt_u32 s94, 61
	s_barrier
	s_cbranch_scc0 .LBB0_127
	s_and_b64 vcc, exec, s[16:17]
	s_cbranch_vccz .LBB0_130
	s_barrier

; #define PG8_STAGE(bufoff, gbase, voff) do { _Pragma("unroll") for (int _i = 0; _i < 2; ++_i) \
;         __builtin_amdgcn_global_load_lds((const unsigned*)((const char*)(gbase) + (voff)[_i]), (PG8_LAS unsigned*)(lds + (bufoff) + ldsw + _i * 8192), 16, 0, 0); } while (0)
; #define PG8_LDA(dst, b, h) do { _Pragma("unroll") for (int m = 0; m < 4; ++m) _Pragma("unroll") for (int k = 0; k < 2; ++k) dst[m][k] = *(const PG8_LAS bf16x8*)(lds + PG8_SA(b, h) + aoff + m * 2048 + k * 1024); } while (0)
; #define PG8_LDB(dst, b, h) do { _Pragma("unroll") for (int n = 0; n < 2; ++n) _Pragma("unroll") for (int k = 0; k < 2; ++k) dst[n][k] = *(const PG8_LAS bf16x8*)(lds + PG8_SB(b, h) + boff + n * 2048 + k * 1024); } while (0)
; #define PG8_MMA(ai, bj, At, Bt) do { __builtin_amdgcn_s_setprio(1); _Pragma("unroll") for (int m = 0; m < 4; ++m) _Pragma("unroll") for (int n = 0; n < 2; ++n) _Pragma("unroll") for (int k = 0; k < 2; ++k) \
;         acc[ai][bj][m][n] = __builtin_amdgcn_mfma_f32_16x16x32_bf16(Bt[n][k], At[m][k], acc[ai][bj][m][n], 0, 0, 0); __builtin_amdgcn_s_setprio(0); } while (0)
; #define PG8_WAIT_V(n) asm volatile("s_waitcnt vmcnt(" #n ")" ::: "memory")
; #define PG8_WAIT_L(n) asm volatile("s_waitcnt lgkmcnt(" #n ")" ::: "memory")
; #define PG8_BAR __builtin_amdgcn_s_barrier()
; #define PG8_SCHED __builtin_amdgcn_sched_barrier(0)
; template <class Epi, class Sched>
; __device__ __forceinline__ void gemm_phase(PG8_LAS unsigned char* lds, const Gemm g, const Sched& S, const Epi& E) {
;     ...
;         for (int t = 0; t < nt; t += 2) {
;             const bool last = (t == nt - 2);
;             const char* a1 = cA + (size_t)(t + 1) * kstep;
;             const char* a2 = last ? nA : cA + (size_t)(t + 2) * kstep; const char* b2 = last ? nB : cB + (size_t)(t + 2) * kstep;
;             const char* a3 = a2 + kstep; const char* b3 = b2 + kstep;
;             PG8_LDB(B0, 0, 0); PG8_LDB(B1, 0, 1); PG8_SCHED; PG8_LDA(At, 0, 0); PG8_STAGE(PG8_SA(1, 1), a1 + hstepA, voffA);
;             PG8_WAIT_V(8); PG8_WAIT_L(0); PG8_BAR; PG8_MMA(0, 0, At, B0); PG8_MMA(0, 1, At, B1); PG8_BAR; PG8_SCHED;
;             PG8_LDA(At, 0, 1); PG8_STAGE(PG8_SB(0, 0), b2, voffB); PG8_STAGE(PG8_SB(0, 1), b2 + hstepB, voffB); PG8_STAGE(PG8_SA(0, 0), a2, voffA);
;             PG8_WAIT_V(8); PG8_WAIT_L(0); PG8_BAR; PG8_MMA(1, 0, At, B0); PG8_MMA(1, 1, At, B1); PG8_BAR; PG8_SCHED;
.LBB0_324:
	ds_read_b128 v[146:149], v171
	ds_read_b128 v[150:153], v171 offset:1024
	ds_read_b128 v[176:179], v171 offset:2048
	ds_read_b128 v[180:183], v171 offset:3072
	ds_read_b128 v[184:187], v172
	ds_read_b128 v[188:191], v172 offset:1024
	ds_read_b128 v[192:195], v172 offset:2048
	ds_read_b128 v[196:199], v172 offset:3072
	s_add_u32 s22, s20, 0xffda0080
	s_addc_u32 s23, s21, -1
	s_cmp_eq_u32 s64, 8
	s_cselect_b32 s25, s5, s23
	s_cselect_b32 s24, s4, s22
	s_cselect_b32 s23, s19, s51
	s_cselect_b32 s22, s18, s50
	v_lshl_add_u64 v[234:235], s[20:21], 0, v[138:139]
	s_add_i32 m0, s30, 0xc000
	ds_read_b128 v[200:203], v173
	ds_read_b128 v[204:207], v173 offset:1024
	ds_read_b128 v[210:213], v173 offset:2048
	ds_read_b128 v[214:217], v173 offset:3072
	ds_read_b128 v[218:221], v173 offset:4096
	ds_read_b128 v[222:225], v173 offset:5120
	ds_read_b128 v[226:229], v173 offset:6144
	ds_read_b128 v[230:233], v173 offset:7168
	global_load_lds_dwordx4 v[234:235], off
	v_lshl_add_u64 v[234:235], s[20:21], 0, v[140:141]
	s_add_i32 m0, s30, 0xe000
	s_nop 0
	global_load_lds_dwordx4 v[234:235], off
	s_waitcnt vmcnt(8)
	s_waitcnt lgkmcnt(0)
	s_barrier
	s_setprio 1
	s_waitcnt lgkmcnt(0)
	v_mfma_f32_16x16x32_bf16 v[126:129], v[146:149], v[200:203], v[126:129]
	v_mfma_f32_16x16x32_bf16 v[122:125], v[176:179], v[200:203], v[122:125]
	v_mfma_f32_16x16x32_bf16 v[110:113], v[146:149], v[210:213], v[110:113]
	v_mfma_f32_16x16x32_bf16 v[106:109], v[176:179], v[210:213], v[106:109]
	v_mfma_f32_16x16x32_bf16 v[94:97], v[146:149], v[218:221], v[94:97]
	v_mfma_f32_16x16x32_bf16 v[90:93], v[176:179], v[218:221], v[90:93]
	v_mfma_f32_16x16x32_bf16 v[86:89], v[146:149], v[226:229], v[86:89]
	v_mfma_f32_16x16x32_bf16 v[74:77], v[176:179], v[226:229], v[74:77]
	v_mfma_f32_16x16x32_bf16 v[126:129], v[150:153], v[204:207], v[126:129]
	v_mfma_f32_16x16x32_bf16 v[122:125], v[180:183], v[204:207], v[122:125]
	v_mfma_f32_16x16x32_bf16 v[110:113], v[150:153], v[214:217], v[110:113]
	v_mfma_f32_16x16x32_bf16 v[106:109], v[180:183], v[214:217], v[106:109]
	v_mfma_f32_16x16x32_bf16 v[94:97], v[150:153], v[222:225], v[94:97]
	v_mfma_f32_16x16x32_bf16 v[90:93], v[180:183], v[222:225], v[90:93]
	v_mfma_f32_16x16x32_bf16 v[86:89], v[150:153], v[230:233], v[86:89]
	v_mfma_f32_16x16x32_bf16 v[74:77], v[180:183], v[230:233], v[74:77]
	s_setprio 0
	s_setprio 1
	v_mfma_f32_16x16x32_bf16 v[118:121], v[184:187], v[200:203], v[118:121]
	v_mfma_f32_16x16x32_bf16 v[114:117], v[192:195], v[200:203], v[114:117]
	v_mfma_f32_16x16x32_bf16 v[102:105], v[184:187], v[210:213], v[102:105]
	v_mfma_f32_16x16x32_bf16 v[98:101], v[192:195], v[210:213], v[98:101]
	v_mfma_f32_16x16x32_bf16 v[82:85], v[184:187], v[218:221], v[82:85]
	v_mfma_f32_16x16x32_bf16 v[78:81], v[192:195], v[218:221], v[78:81]
	v_mfma_f32_16x16x32_bf16 v[70:73], v[184:187], v[226:229], v[70:73]
	v_mfma_f32_16x16x32_bf16 v[66:69], v[192:195], v[226:229], v[66:69]
	v_mfma_f32_16x16x32_bf16 v[118:121], v[188:191], v[204:207], v[118:121]
	v_mfma_f32_16x16x32_bf16 v[114:117], v[196:199], v[204:207], v[114:117]
	v_mfma_f32_16x16x32_bf16 v[102:105], v[188:191], v[214:217], v[102:105]
	v_mfma_f32_16x16x32_bf16 v[98:101], v[196:199], v[214:217], v[98:101]
	v_mfma_f32_16x16x32_bf16 v[82:85], v[188:191], v[222:225], v[82:85]
	v_mfma_f32_16x16x32_bf16 v[78:81], v[196:199], v[222:225], v[78:81]
	v_mfma_f32_16x16x32_bf16 v[70:73], v[188:191], v[230:233], v[70:73]
	v_mfma_f32_16x16x32_bf16 v[66:69], v[196:199], v[230:233], v[66:69]
	s_setprio 0
	s_barrier
	s_add_i32 s65, s40, s28
	v_lshl_add_u64 v[234:235], s[22:23], 0, v[136:137]
	s_mov_b32 m0, s65
	ds_read_b128 v[200:203], v173 offset:16384
	ds_read_b128 v[204:207], v173 offset:17408
	ds_read_b128 v[210:213], v173 offset:18432
	ds_read_b128 v[214:217], v173 offset:19456
	ds_read_b128 v[218:221], v173 offset:20480
	ds_read_b128 v[222:225], v173 offset:21504
	ds_read_b128 v[226:229], v173 offset:22528
	ds_read_b128 v[230:233], v173 offset:23552
	global_load_lds_dwordx4 v[234:235], off
	s_add_i32 m0, s65, 0x2000
	s_add_u32 s88, s22, 0x30000
	v_lshl_add_u64 v[236:237], s[22:23], 0, v[134:135]
	s_addc_u32 s89, s23, 0
	s_add_i32 s65, s41, s28
	global_load_lds_dwordx4 v[236:237], off
	v_lshl_add_u64 v[238:239], s[88:89], 0, v[136:137]
	s_mov_b32 m0, s65
	v_lshl_add_u64 v[240:241], s[24:25], 0, v[132:133]
	global_load_lds_dwordx4 v[238:239], off
	v_lshl_add_u64 v[238:239], s[88:89], 0, v[134:135]
	s_add_i32 m0, s65, 0x2000
	s_nop 0
	global_load_lds_dwordx4 v[238:239], off
	v_lshl_add_u64 v[238:239], s[24:25], 0, v[130:131]
	s_mov_b32 m0, s30
	s_nop 0
	global_load_lds_dwordx4 v[238:239], off
	s_mov_b32 m0, s31
	s_nop 0
	global_load_lds_dwordx4 v[240:241], off
	s_waitcnt vmcnt(8)
	s_waitcnt lgkmcnt(0)
	s_barrier
; #define PG8_STAGE(bufoff, gbase, voff) do { _Pragma("unroll") for (int _i = 0; _i < 2; ++_i) \
;         __builtin_amdgcn_global_load_lds((const unsigned*)((const char*)(gbase) + (voff)[_i]), (PG8_LAS unsigned*)(lds + (bufoff) + ldsw + _i * 8192), 16, 0, 0); } while (0)
; #define PG8_LDA(dst, b, h) do { _Pragma("unroll") for (int m = 0; m < 4; ++m) _Pragma("unroll") for (int k = 0; k < 2; ++k) dst[m][k] = *(const PG8_LAS bf16x8*)(lds + PG8_SA(b, h) + aoff + m * 2048 + k * 1024); } while (0)
; #define PG8_LDB(dst, b, h) do { _Pragma("unroll") for (int n = 0; n < 2; ++n) _Pragma("unroll") for (int k = 0; k < 2; ++k) dst[n][k] = *(const PG8_LAS bf16x8*)(lds + PG8_SB(b, h) + boff + n * 2048 + k * 1024); } while (0)
; #define PG8_MMA(ai, bj, At, Bt) do { __builtin_amdgcn_s_setprio(1); _Pragma("unroll") for (int m = 0; m < 4; ++m) _Pragma("unroll") for (int n = 0; n < 2; ++n) _Pragma("unroll") for (int k = 0; k < 2; ++k) \
;         acc[ai][bj][m][n] = __builtin_amdgcn_mfma_f32_16x16x32_bf16(Bt[n][k], At[m][k], acc[ai][bj][m][n], 0, 0, 0); __builtin_amdgcn_s_setprio(0); } while (0)
; #define PG8_WAIT_V(n) asm volatile("s_waitcnt vmcnt(" #n ")" ::: "memory")
; #define PG8_WAIT_L(n) asm volatile("s_waitcnt lgkmcnt(" #n ")" ::: "memory")
; #define PG8_BAR __builtin_amdgcn_s_barrier()
; #define PG8_SCHED __builtin_amdgcn_sched_barrier(0)
; template <class Epi, class Sched>
; __device__ __forceinline__ void gemm_phase(PG8_LAS unsigned char* lds, const Gemm g, const Sched& S, const Epi& E) {
;     ...
;             PG8_WAIT_V(8); PG8_WAIT_L(0); PG8_BAR; PG8_MMA(1, 0, At, B0); PG8_MMA(1, 1, At, B1); PG8_BAR; PG8_SCHED;
;             PG8_LDB(B0, 1, 0); PG8_LDB(B1, 1, 1); PG8_SCHED; PG8_LDA(At, 1, 0); PG8_STAGE(PG8_SA(0, 1), a2 + hstepA, voffA);
;             PG8_WAIT_V(8); PG8_WAIT_L(0); PG8_BAR; PG8_MMA(0, 0, At, B0); PG8_MMA(0, 1, At, B1); PG8_BAR; PG8_SCHED;
	s_setprio 1
	s_waitcnt lgkmcnt(0)
	v_mfma_f32_16x16x32_bf16 v[62:65], v[146:149], v[200:203], v[62:65]
	v_mfma_f32_16x16x32_bf16 v[58:61], v[176:179], v[200:203], v[58:61]
	v_mfma_f32_16x16x32_bf16 v[50:53], v[146:149], v[210:213], v[50:53]
	v_mfma_f32_16x16x32_bf16 v[42:45], v[176:179], v[210:213], v[42:45]
	v_mfma_f32_16x16x32_bf16 v[34:37], v[146:149], v[218:221], v[34:37]
	v_mfma_f32_16x16x32_bf16 v[26:29], v[176:179], v[218:221], v[26:29]
	v_mfma_f32_16x16x32_bf16 v[14:17], v[146:149], v[226:229], v[14:17]
	v_mfma_f32_16x16x32_bf16 v[10:13], v[176:179], v[226:229], v[10:13]
	v_mfma_f32_16x16x32_bf16 v[62:65], v[150:153], v[204:207], v[62:65]
	v_mfma_f32_16x16x32_bf16 v[58:61], v[180:183], v[204:207], v[58:61]
	v_mfma_f32_16x16x32_bf16 v[50:53], v[150:153], v[214:217], v[50:53]
	v_mfma_f32_16x16x32_bf16 v[42:45], v[180:183], v[214:217], v[42:45]
	v_mfma_f32_16x16x32_bf16 v[34:37], v[150:153], v[222:225], v[34:37]
	v_mfma_f32_16x16x32_bf16 v[26:29], v[180:183], v[222:225], v[26:29]
	v_mfma_f32_16x16x32_bf16 v[14:17], v[150:153], v[230:233], v[14:17]
	v_mfma_f32_16x16x32_bf16 v[10:13], v[180:183], v[230:233], v[10:13]
	s_setprio 0
	s_setprio 1
	v_mfma_f32_16x16x32_bf16 v[54:57], v[184:187], v[200:203], v[54:57]
	v_mfma_f32_16x16x32_bf16 v[46:49], v[192:195], v[200:203], v[46:49]
	v_mfma_f32_16x16x32_bf16 v[38:41], v[184:187], v[210:213], v[38:41]
	v_mfma_f32_16x16x32_bf16 v[30:33], v[192:195], v[210:213], v[30:33]
	v_mfma_f32_16x16x32_bf16 v[22:25], v[184:187], v[218:221], v[22:25]
	v_mfma_f32_16x16x32_bf16 v[18:21], v[192:195], v[218:221], v[18:21]
	v_mfma_f32_16x16x32_bf16 v[6:9], v[184:187], v[226:229], v[6:9]
	v_mfma_f32_16x16x32_bf16 v[2:5], v[192:195], v[226:229], v[2:5]
	v_mfma_f32_16x16x32_bf16 v[54:57], v[188:191], v[204:207], v[54:57]
	v_mfma_f32_16x16x32_bf16 v[46:49], v[196:199], v[204:207], v[46:49]
	v_mfma_f32_16x16x32_bf16 v[38:41], v[188:191], v[214:217], v[38:41]
	v_mfma_f32_16x16x32_bf16 v[30:33], v[196:199], v[214:217], v[30:33]
	v_mfma_f32_16x16x32_bf16 v[22:25], v[188:191], v[222:225], v[22:25]
	v_mfma_f32_16x16x32_bf16 v[18:21], v[196:199], v[222:225], v[18:21]
	v_mfma_f32_16x16x32_bf16 v[6:9], v[188:191], v[230:233], v[6:9]
	v_mfma_f32_16x16x32_bf16 v[2:5], v[196:199], v[230:233], v[2:5]
	s_setprio 0
	s_barrier
	s_add_i32 s65, 0, 0x18000
	v_add_u32_e32 v175, s65, v167
	s_add_i32 s66, 0, 0x1c000
	ds_read_b128 v[146:149], v175
	ds_read_b128 v[150:153], v175 offset:1024
	ds_read_b128 v[176:179], v175 offset:2048
	ds_read_b128 v[180:183], v175 offset:3072
	v_add_u32_e32 v175, s66, v167
	ds_read_b128 v[184:187], v175
	ds_read_b128 v[188:191], v175 offset:1024
	ds_read_b128 v[192:195], v175 offset:2048
	ds_read_b128 v[196:199], v175 offset:3072
	s_add_u32 s24, s24, 0x260000
	s_addc_u32 s25, s25, 0
	s_mov_b32 m0, s33
	v_lshl_add_u64 v[242:243], s[24:25], 0, v[130:131]
	ds_read_b128 v[200:203], v173 offset:32768
	ds_read_b128 v[204:207], v173 offset:33792
	ds_read_b128 v[210:213], v173 offset:34816
	ds_read_b128 v[214:217], v173 offset:35840
	ds_read_b128 v[218:221], v173 offset:36864
	ds_read_b128 v[222:225], v173 offset:37888
	ds_read_b128 v[226:229], v173 offset:38912
	ds_read_b128 v[230:233], v173 offset:39936
	global_load_lds_dwordx4 v[242:243], off
	v_lshl_add_u64 v[242:243], s[24:25], 0, v[132:133]
	s_mov_b32 m0, s34
	s_nop 0
	global_load_lds_dwordx4 v[242:243], off
	s_waitcnt vmcnt(8)
	s_waitcnt lgkmcnt(0)
	s_barrier
	s_setprio 1
	s_waitcnt lgkmcnt(0)
	v_mfma_f32_16x16x32_bf16 v[126:129], v[146:149], v[200:203], v[126:129]
	v_mfma_f32_16x16x32_bf16 v[122:125], v[176:179], v[200:203], v[122:125]
	v_mfma_f32_16x16x32_bf16 v[110:113], v[146:149], v[210:213], v[110:113]
	v_mfma_f32_16x16x32_bf16 v[106:109], v[176:179], v[210:213], v[106:109]
	v_mfma_f32_16x16x32_bf16 v[94:97], v[146:149], v[218:221], v[94:97]
	v_mfma_f32_16x16x32_bf16 v[90:93], v[176:179], v[218:221], v[90:93]
	v_mfma_f32_16x16x32_bf16 v[86:89], v[146:149], v[226:229], v[86:89]
	v_mfma_f32_16x16x32_bf16 v[74:77], v[176:179], v[226:229], v[74:77]
	v_mfma_f32_16x16x32_bf16 v[126:129], v[150:153], v[204:207], v[126:129]
	v_mfma_f32_16x16x32_bf16 v[122:125], v[180:183], v[204:207], v[122:125]
	v_mfma_f32_16x16x32_bf16 v[110:113], v[150:153], v[214:217], v[110:113]
	v_mfma_f32_16x16x32_bf16 v[106:109], v[180:183], v[214:217], v[106:109]
	v_mfma_f32_16x16x32_bf16 v[94:97], v[150:153], v[222:225], v[94:97]
	v_mfma_f32_16x16x32_bf16 v[90:93], v[180:183], v[222:225], v[90:93]
	v_mfma_f32_16x16x32_bf16 v[86:89], v[150:153], v[230:233], v[86:89]
	v_mfma_f32_16x16x32_bf16 v[74:77], v[180:183], v[230:233], v[74:77]
	s_setprio 0
	s_setprio 1
	v_mfma_f32_16x16x32_bf16 v[118:121], v[184:187], v[200:203], v[118:121]
	v_mfma_f32_16x16x32_bf16 v[114:117], v[192:195], v[200:203], v[114:117]
	v_mfma_f32_16x16x32_bf16 v[102:105], v[184:187], v[210:213], v[102:105]
	v_mfma_f32_16x16x32_bf16 v[98:101], v[192:195], v[210:213], v[98:101]
	v_mfma_f32_16x16x32_bf16 v[82:85], v[184:187], v[218:221], v[82:85]
	v_mfma_f32_16x16x32_bf16 v[78:81], v[192:195], v[218:221], v[78:81]
	v_mfma_f32_16x16x32_bf16 v[70:73], v[184:187], v[226:229], v[70:73]
	v_mfma_f32_16x16x32_bf16 v[66:69], v[192:195], v[226:229], v[66:69]
	v_mfma_f32_16x16x32_bf16 v[118:121], v[188:191], v[204:207], v[118:121]
	v_mfma_f32_16x16x32_bf16 v[114:117], v[196:199], v[204:207], v[114:117]
	v_mfma_f32_16x16x32_bf16 v[102:105], v[188:191], v[214:217], v[102:105]
	v_mfma_f32_16x16x32_bf16 v[98:101], v[196:199], v[214:217], v[98:101]
	v_mfma_f32_16x16x32_bf16 v[82:85], v[188:191], v[222:225], v[82:85]
	v_mfma_f32_16x16x32_bf16 v[78:81], v[196:199], v[222:225], v[78:81]
	v_mfma_f32_16x16x32_bf16 v[70:73], v[188:191], v[230:233], v[70:73]
	v_mfma_f32_16x16x32_bf16 v[66:69], v[196:199], v[230:233], v[66:69]
	s_setprio 0
	s_barrier
; #define PG8_STAGE(bufoff, gbase, voff) do { _Pragma("unroll") for (int _i = 0; _i < 2; ++_i) \
;         __builtin_amdgcn_global_load_lds((const unsigned*)((const char*)(gbase) + (voff)[_i]), (PG8_LAS unsigned*)(lds + (bufoff) + ldsw + _i * 8192), 16, 0, 0); } while (0)
; #define PG8_LDA(dst, b, h) do { _Pragma("unroll") for (int m = 0; m < 4; ++m) _Pragma("unroll") for (int k = 0; k < 2; ++k) dst[m][k] = *(const PG8_LAS bf16x8*)(lds + PG8_SA(b, h) + aoff + m * 2048 + k * 1024); } while (0)
; #define PG8_MMA(ai, bj, At, Bt) do { __builtin_amdgcn_s_setprio(1); _Pragma("unroll") for (int m = 0; m < 4; ++m) _Pragma("unroll") for (int n = 0; n < 2; ++n) _Pragma("unroll") for (int k = 0; k < 2; ++k) \
;         acc[ai][bj][m][n] = __builtin_amdgcn_mfma_f32_16x16x32_bf16(Bt[n][k], At[m][k], acc[ai][bj][m][n], 0, 0, 0); __builtin_amdgcn_s_setprio(0); } while (0)
; #define PG8_WAIT_V(n) asm volatile("s_waitcnt vmcnt(" #n ")" ::: "memory")
; #define PG8_WAIT_L(n) asm volatile("s_waitcnt lgkmcnt(" #n ")" ::: "memory")
; #define PG8_BAR __builtin_amdgcn_s_barrier()
; #define PG8_SCHED __builtin_amdgcn_sched_barrier(0)
; template <class Epi, class Sched>
; __device__ __forceinline__ void gemm_phase(PG8_LAS unsigned char* lds, const Gemm g, const Sched& S, const Epi& E) {
;     ...
;         for (int t = 0; t < nt; t += 2) {
;     ...
;             PG8_LDA(At, 1, 1); PG8_STAGE(PG8_SB(1, 0), b3, voffB); PG8_STAGE(PG8_SB(1, 1), b3 + hstepB, voffB); PG8_STAGE(PG8_SA(1, 0), a3, voffA);
;             PG8_WAIT_V(8); PG8_WAIT_L(0); PG8_BAR; PG8_MMA(1, 0, At, B0); PG8_MMA(1, 1, At, B1); PG8_BAR; PG8_SCHED;
;         }
;         if (wr == 0) PG8_BAR;
	s_add_i32 s24, s65, s28
	v_lshl_add_u64 v[234:235], v[234:235], 0, s[14:15]
	s_mov_b32 m0, s24
	ds_read_b128 v[200:203], v173 offset:49152
	ds_read_b128 v[204:207], v173 offset:50176
	ds_read_b128 v[210:213], v173 offset:51200
	ds_read_b128 v[214:217], v173 offset:52224
	ds_read_b128 v[218:221], v173 offset:53248
	ds_read_b128 v[222:225], v173 offset:54272
	ds_read_b128 v[226:229], v173 offset:55296
	ds_read_b128 v[230:233], v173 offset:56320
	global_load_lds_dwordx4 v[234:235], off
	s_add_i32 m0, s24, 0x2000
	s_add_u32 s22, s22, 0x30080
	v_lshl_add_u64 v[234:235], v[236:237], 0, s[14:15]
	s_addc_u32 s23, s23, 0
	s_add_i32 s24, s66, s28
	global_load_lds_dwordx4 v[234:235], off
	v_lshl_add_u64 v[234:235], s[22:23], 0, v[136:137]
	s_mov_b32 m0, s24
	s_nop 0
	global_load_lds_dwordx4 v[234:235], off
	v_lshl_add_u64 v[234:235], s[22:23], 0, v[134:135]
	s_add_i32 m0, s24, 0x2000
	s_nop 0
	global_load_lds_dwordx4 v[234:235], off
	v_lshl_add_u64 v[234:235], v[238:239], 0, s[14:15]
	s_mov_b32 m0, s36
	s_nop 0
	global_load_lds_dwordx4 v[234:235], off
	v_lshl_add_u64 v[234:235], v[240:241], 0, s[14:15]
	s_mov_b32 m0, s37
	s_nop 0
	global_load_lds_dwordx4 v[234:235], off
	s_waitcnt vmcnt(8)
	s_waitcnt lgkmcnt(0)
	s_barrier
	s_setprio 1
	s_waitcnt lgkmcnt(0)
	v_mfma_f32_16x16x32_bf16 v[62:65], v[146:149], v[200:203], v[62:65]
	v_mfma_f32_16x16x32_bf16 v[58:61], v[176:179], v[200:203], v[58:61]
	v_mfma_f32_16x16x32_bf16 v[50:53], v[146:149], v[210:213], v[50:53]
	v_mfma_f32_16x16x32_bf16 v[42:45], v[176:179], v[210:213], v[42:45]
	v_mfma_f32_16x16x32_bf16 v[34:37], v[146:149], v[218:221], v[34:37]
	v_mfma_f32_16x16x32_bf16 v[26:29], v[176:179], v[218:221], v[26:29]
	v_mfma_f32_16x16x32_bf16 v[14:17], v[146:149], v[226:229], v[14:17]
	v_mfma_f32_16x16x32_bf16 v[10:13], v[176:179], v[226:229], v[10:13]
	v_mfma_f32_16x16x32_bf16 v[62:65], v[150:153], v[204:207], v[62:65]
	v_mfma_f32_16x16x32_bf16 v[58:61], v[180:183], v[204:207], v[58:61]
	v_mfma_f32_16x16x32_bf16 v[50:53], v[150:153], v[214:217], v[50:53]
	v_mfma_f32_16x16x32_bf16 v[42:45], v[180:183], v[214:217], v[42:45]
	v_mfma_f32_16x16x32_bf16 v[34:37], v[150:153], v[222:225], v[34:37]
	v_mfma_f32_16x16x32_bf16 v[26:29], v[180:183], v[222:225], v[26:29]
	v_mfma_f32_16x16x32_bf16 v[14:17], v[150:153], v[230:233], v[14:17]
	v_mfma_f32_16x16x32_bf16 v[10:13], v[180:183], v[230:233], v[10:13]
	s_setprio 0
	s_setprio 1
	v_mfma_f32_16x16x32_bf16 v[54:57], v[184:187], v[200:203], v[54:57]
	v_mfma_f32_16x16x32_bf16 v[46:49], v[192:195], v[200:203], v[46:49]
	v_mfma_f32_16x16x32_bf16 v[38:41], v[184:187], v[210:213], v[38:41]
	v_mfma_f32_16x16x32_bf16 v[30:33], v[192:195], v[210:213], v[30:33]
	v_mfma_f32_16x16x32_bf16 v[22:25], v[184:187], v[218:221], v[22:25]
	v_mfma_f32_16x16x32_bf16 v[18:21], v[192:195], v[218:221], v[18:21]
	v_mfma_f32_16x16x32_bf16 v[6:9], v[184:187], v[226:229], v[6:9]
	v_mfma_f32_16x16x32_bf16 v[2:5], v[192:195], v[226:229], v[2:5]
	v_mfma_f32_16x16x32_bf16 v[54:57], v[188:191], v[204:207], v[54:57]
	v_mfma_f32_16x16x32_bf16 v[46:49], v[196:199], v[204:207], v[46:49]
	v_mfma_f32_16x16x32_bf16 v[38:41], v[188:191], v[214:217], v[38:41]
	v_mfma_f32_16x16x32_bf16 v[30:33], v[196:199], v[214:217], v[30:33]
	v_mfma_f32_16x16x32_bf16 v[22:25], v[188:191], v[222:225], v[22:25]
	v_mfma_f32_16x16x32_bf16 v[18:21], v[196:199], v[222:225], v[18:21]
	v_mfma_f32_16x16x32_bf16 v[6:9], v[188:191], v[230:233], v[6:9]
	v_mfma_f32_16x16x32_bf16 v[2:5], v[196:199], v[230:233], v[2:5]
	s_setprio 0
	s_add_i32 s64, s64, 2
	s_add_u32 s20, s20, 0x100
	s_addc_u32 s21, s21, 0
	s_add_u32 s50, s50, 0x100
	s_addc_u32 s51, s51, 0
	s_cmp_gt_u32 s64, 9
	s_barrier
	s_cbranch_scc0 .LBB0_324
	s_and_b64 vcc, exec, s[16:17]
	s_cbranch_vccz .LBB0_327
	s_barrier

; #define PG8_STAGE(bufoff, gbase, voff) do { _Pragma("unroll") for (int _i = 0; _i < 2; ++_i) \
;         __builtin_amdgcn_global_load_lds((const unsigned*)((const char*)(gbase) + (voff)[_i]), (PG8_LAS unsigned*)(lds + (bufoff) + ldsw + _i * 8192), 16, 0, 0); } while (0)
; #define PG8_LDA(dst, b, h) do { _Pragma("unroll") for (int m = 0; m < 4; ++m) _Pragma("unroll") for (int k = 0; k < 2; ++k) dst[m][k] = *(const PG8_LAS bf16x8*)(lds + PG8_SA(b, h) + aoff + m * 2048 + k * 1024); } while (0)
; #define PG8_LDB(dst, b, h) do { _Pragma("unroll") for (int n = 0; n < 2; ++n) _Pragma("unroll") for (int k = 0; k < 2; ++k) dst[n][k] = *(const PG8_LAS bf16x8*)(lds + PG8_SB(b, h) + boff + n * 2048 + k * 1024); } while (0)
; #define PG8_MMA(ai, bj, At, Bt) do { __builtin_amdgcn_s_setprio(1); _Pragma("unroll") for (int m = 0; m < 4; ++m) _Pragma("unroll") for (int n = 0; n < 2; ++n) _Pragma("unroll") for (int k = 0; k < 2; ++k) \
;         acc[ai][bj][m][n] = __builtin_amdgcn_mfma_f32_16x16x32_bf16(Bt[n][k], At[m][k], acc[ai][bj][m][n], 0, 0, 0); __builtin_amdgcn_s_setprio(0); } while (0)
; #define PG8_WAIT_V(n) asm volatile("s_waitcnt vmcnt(" #n ")" ::: "memory")
; #define PG8_WAIT_L(n) asm volatile("s_waitcnt lgkmcnt(" #n ")" ::: "memory")
; #define PG8_BAR __builtin_amdgcn_s_barrier()
; #define PG8_SCHED __builtin_amdgcn_sched_barrier(0)
; template <class Epi, class Sched>
; __device__ __forceinline__ void gemm_phase(PG8_LAS unsigned char* lds, const Gemm g, const Sched& S, const Epi& E) {
;     ...
;         for (int t = 0; t < nt; t += 2) {
;             const bool last = (t == nt - 2);
;             const char* a1 = cA + (size_t)(t + 1) * kstep;
;             const char* a2 = last ? nA : cA + (size_t)(t + 2) * kstep; const char* b2 = last ? nB : cB + (size_t)(t + 2) * kstep;
;             const char* a3 = a2 + kstep; const char* b3 = b2 + kstep;
;             PG8_LDB(B0, 0, 0); PG8_LDB(B1, 0, 1); PG8_SCHED; PG8_LDA(At, 0, 0); PG8_STAGE(PG8_SA(1, 1), a1 + hstepA, voffA);
;             PG8_WAIT_V(8); PG8_WAIT_L(0); PG8_BAR; PG8_MMA(0, 0, At, B0); PG8_MMA(0, 1, At, B1); PG8_BAR; PG8_SCHED;
;             PG8_LDA(At, 0, 1); PG8_STAGE(PG8_SB(0, 0), b2, voffB); PG8_STAGE(PG8_SB(0, 1), b2 + hstepB, voffB); PG8_STAGE(PG8_SA(0, 0), a2, voffA);
;             PG8_WAIT_V(8); PG8_WAIT_L(0); PG8_BAR; PG8_MMA(1, 0, At, B0); PG8_MMA(1, 1, At, B1); PG8_BAR; PG8_SCHED;
.LBB0_350:
	ds_read_b128 v[146:149], v169
	ds_read_b128 v[150:153], v169 offset:1024
	ds_read_b128 v[174:177], v169 offset:2048
	ds_read_b128 v[178:181], v169 offset:3072
	ds_read_b128 v[182:185], v170
	ds_read_b128 v[186:189], v170 offset:1024
	ds_read_b128 v[190:193], v170 offset:2048
	ds_read_b128 v[194:197], v170 offset:3072
	s_add_u32 s4, s0, 0xffda0080
	s_addc_u32 s5, s1, -1
	s_cmp_eq_u32 s91, 4
	s_cselect_b32 s29, s25, s5
	s_cselect_b32 s28, s24, s4
	s_cselect_b32 s5, s23, s89
	s_cselect_b32 s4, s65, s88
	v_lshl_add_u64 v[206:207], s[0:1], 0, v[138:139]
	s_add_i32 m0, s37, 0xc000
	ds_read_b128 v[198:201], v171
	ds_read_b128 v[202:205], v171 offset:1024
	ds_read_b128 v[210:213], v171 offset:2048
	ds_read_b128 v[214:217], v171 offset:3072
	ds_read_b128 v[218:221], v171 offset:4096
	ds_read_b128 v[222:225], v171 offset:5120
	ds_read_b128 v[226:229], v171 offset:6144
	ds_read_b128 v[230:233], v171 offset:7168
	global_load_lds_dwordx4 v[206:207], off
	v_lshl_add_u64 v[206:207], s[0:1], 0, v[140:141]
	s_add_i32 m0, s37, 0xe000
	s_nop 0
	global_load_lds_dwordx4 v[206:207], off
	s_waitcnt vmcnt(8)
	s_waitcnt lgkmcnt(0)
	s_barrier
	s_setprio 1
	s_waitcnt lgkmcnt(0)
	v_mfma_f32_16x16x32_bf16 v[126:129], v[146:149], v[198:201], v[126:129]
	v_mfma_f32_16x16x32_bf16 v[122:125], v[174:177], v[198:201], v[122:125]
	v_mfma_f32_16x16x32_bf16 v[110:113], v[146:149], v[210:213], v[110:113]
	v_mfma_f32_16x16x32_bf16 v[106:109], v[174:177], v[210:213], v[106:109]
	v_mfma_f32_16x16x32_bf16 v[94:97], v[146:149], v[218:221], v[94:97]
	v_mfma_f32_16x16x32_bf16 v[90:93], v[174:177], v[218:221], v[90:93]
	v_mfma_f32_16x16x32_bf16 v[78:81], v[146:149], v[226:229], v[78:81]
	v_mfma_f32_16x16x32_bf16 v[74:77], v[174:177], v[226:229], v[74:77]
	v_mfma_f32_16x16x32_bf16 v[126:129], v[150:153], v[202:205], v[126:129]
	v_mfma_f32_16x16x32_bf16 v[122:125], v[178:181], v[202:205], v[122:125]
	v_mfma_f32_16x16x32_bf16 v[110:113], v[150:153], v[214:217], v[110:113]
	v_mfma_f32_16x16x32_bf16 v[106:109], v[178:181], v[214:217], v[106:109]
	v_mfma_f32_16x16x32_bf16 v[94:97], v[150:153], v[222:225], v[94:97]
	v_mfma_f32_16x16x32_bf16 v[90:93], v[178:181], v[222:225], v[90:93]
	v_mfma_f32_16x16x32_bf16 v[78:81], v[150:153], v[230:233], v[78:81]
	v_mfma_f32_16x16x32_bf16 v[74:77], v[178:181], v[230:233], v[74:77]
	s_setprio 0
	s_setprio 1
	v_mfma_f32_16x16x32_bf16 v[118:121], v[182:185], v[198:201], v[118:121]
	v_mfma_f32_16x16x32_bf16 v[114:117], v[190:193], v[198:201], v[114:117]
	v_mfma_f32_16x16x32_bf16 v[102:105], v[182:185], v[210:213], v[102:105]
	v_mfma_f32_16x16x32_bf16 v[98:101], v[190:193], v[210:213], v[98:101]
	v_mfma_f32_16x16x32_bf16 v[86:89], v[182:185], v[218:221], v[86:89]
	v_mfma_f32_16x16x32_bf16 v[82:85], v[190:193], v[218:221], v[82:85]
	v_mfma_f32_16x16x32_bf16 v[70:73], v[182:185], v[226:229], v[70:73]
	v_mfma_f32_16x16x32_bf16 v[66:69], v[190:193], v[226:229], v[66:69]
	v_mfma_f32_16x16x32_bf16 v[118:121], v[186:189], v[202:205], v[118:121]
	v_mfma_f32_16x16x32_bf16 v[114:117], v[194:197], v[202:205], v[114:117]
	v_mfma_f32_16x16x32_bf16 v[102:105], v[186:189], v[214:217], v[102:105]
	v_mfma_f32_16x16x32_bf16 v[98:101], v[194:197], v[214:217], v[98:101]
	v_mfma_f32_16x16x32_bf16 v[86:89], v[186:189], v[222:225], v[86:89]
	v_mfma_f32_16x16x32_bf16 v[82:85], v[194:197], v[222:225], v[82:85]
	v_mfma_f32_16x16x32_bf16 v[70:73], v[186:189], v[230:233], v[70:73]
	v_mfma_f32_16x16x32_bf16 v[66:69], v[194:197], v[230:233], v[66:69]
	s_setprio 0
	s_barrier
	s_add_i32 s66, s45, s36
	v_lshl_add_u64 v[206:207], s[4:5], 0, v[134:135]
	s_mov_b32 m0, s66
	ds_read_b128 v[198:201], v171 offset:16384
	ds_read_b128 v[202:205], v171 offset:17408
	ds_read_b128 v[210:213], v171 offset:18432
	ds_read_b128 v[214:217], v171 offset:19456
	ds_read_b128 v[218:221], v171 offset:20480
	ds_read_b128 v[222:225], v171 offset:21504
	ds_read_b128 v[226:229], v171 offset:22528
	ds_read_b128 v[230:233], v171 offset:23552
	global_load_lds_dwordx4 v[206:207], off
	s_add_i32 m0, s66, 0x2000
	s_add_u32 s92, s4, 0x20000
	v_lshl_add_u64 v[234:235], s[4:5], 0, v[136:137]
	s_addc_u32 s93, s5, 0
	s_add_i32 s66, s47, s36
	global_load_lds_dwordx4 v[234:235], off
	v_lshl_add_u64 v[236:237], s[92:93], 0, v[134:135]
	s_mov_b32 m0, s66
	v_lshl_add_u64 v[238:239], s[28:29], 0, v[132:133]
	global_load_lds_dwordx4 v[236:237], off
	v_lshl_add_u64 v[236:237], s[92:93], 0, v[136:137]
	s_add_i32 m0, s66, 0x2000
	s_nop 0
	global_load_lds_dwordx4 v[236:237], off
	v_lshl_add_u64 v[236:237], s[28:29], 0, v[130:131]
	s_mov_b32 m0, s37
	s_nop 0
	global_load_lds_dwordx4 v[236:237], off
	s_mov_b32 m0, s38
	s_nop 0
	global_load_lds_dwordx4 v[238:239], off
	s_waitcnt vmcnt(8)
	s_waitcnt lgkmcnt(0)
	s_barrier
; #define PG8_STAGE(bufoff, gbase, voff) do { _Pragma("unroll") for (int _i = 0; _i < 2; ++_i) \
;         __builtin_amdgcn_global_load_lds((const unsigned*)((const char*)(gbase) + (voff)[_i]), (PG8_LAS unsigned*)(lds + (bufoff) + ldsw + _i * 8192), 16, 0, 0); } while (0)
; #define PG8_LDA(dst, b, h) do { _Pragma("unroll") for (int m = 0; m < 4; ++m) _Pragma("unroll") for (int k = 0; k < 2; ++k) dst[m][k] = *(const PG8_LAS bf16x8*)(lds + PG8_SA(b, h) + aoff + m * 2048 + k * 1024); } while (0)
; #define PG8_LDB(dst, b, h) do { _Pragma("unroll") for (int n = 0; n < 2; ++n) _Pragma("unroll") for (int k = 0; k < 2; ++k) dst[n][k] = *(const PG8_LAS bf16x8*)(lds + PG8_SB(b, h) + boff + n * 2048 + k * 1024); } while (0)
; #define PG8_MMA(ai, bj, At, Bt) do { __builtin_amdgcn_s_setprio(1); _Pragma("unroll") for (int m = 0; m < 4; ++m) _Pragma("unroll") for (int n = 0; n < 2; ++n) _Pragma("unroll") for (int k = 0; k < 2; ++k) \
;         acc[ai][bj][m][n] = __builtin_amdgcn_mfma_f32_16x16x32_bf16(Bt[n][k], At[m][k], acc[ai][bj][m][n], 0, 0, 0); __builtin_amdgcn_s_setprio(0); } while (0)
; #define PG8_WAIT_V(n) asm volatile("s_waitcnt vmcnt(" #n ")" ::: "memory")
; #define PG8_WAIT_L(n) asm volatile("s_waitcnt lgkmcnt(" #n ")" ::: "memory")
; #define PG8_BAR __builtin_amdgcn_s_barrier()
; #define PG8_SCHED __builtin_amdgcn_sched_barrier(0)
; template <class Epi, class Sched>
; __device__ __forceinline__ void gemm_phase(PG8_LAS unsigned char* lds, const Gemm g, const Sched& S, const Epi& E) {
;     ...
;             PG8_WAIT_V(8); PG8_WAIT_L(0); PG8_BAR; PG8_MMA(1, 0, At, B0); PG8_MMA(1, 1, At, B1); PG8_BAR; PG8_SCHED;
;             PG8_LDB(B0, 1, 0); PG8_LDB(B1, 1, 1); PG8_SCHED; PG8_LDA(At, 1, 0); PG8_STAGE(PG8_SA(0, 1), a2 + hstepA, voffA);
;             PG8_WAIT_V(8); PG8_WAIT_L(0); PG8_BAR; PG8_MMA(0, 0, At, B0); PG8_MMA(0, 1, At, B1); PG8_BAR; PG8_SCHED;
	s_setprio 1
	s_waitcnt lgkmcnt(0)
	v_mfma_f32_16x16x32_bf16 v[62:65], v[146:149], v[198:201], v[62:65]
	v_mfma_f32_16x16x32_bf16 v[58:61], v[174:177], v[198:201], v[58:61]
	v_mfma_f32_16x16x32_bf16 v[46:49], v[146:149], v[210:213], v[46:49]
	v_mfma_f32_16x16x32_bf16 v[42:45], v[174:177], v[210:213], v[42:45]
	v_mfma_f32_16x16x32_bf16 v[30:33], v[146:149], v[218:221], v[30:33]
	v_mfma_f32_16x16x32_bf16 v[26:29], v[174:177], v[218:221], v[26:29]
	v_mfma_f32_16x16x32_bf16 v[14:17], v[146:149], v[226:229], v[14:17]
	v_mfma_f32_16x16x32_bf16 v[10:13], v[174:177], v[226:229], v[10:13]
	v_mfma_f32_16x16x32_bf16 v[62:65], v[150:153], v[202:205], v[62:65]
	v_mfma_f32_16x16x32_bf16 v[58:61], v[178:181], v[202:205], v[58:61]
	v_mfma_f32_16x16x32_bf16 v[46:49], v[150:153], v[214:217], v[46:49]
	v_mfma_f32_16x16x32_bf16 v[42:45], v[178:181], v[214:217], v[42:45]
	v_mfma_f32_16x16x32_bf16 v[30:33], v[150:153], v[222:225], v[30:33]
	v_mfma_f32_16x16x32_bf16 v[26:29], v[178:181], v[222:225], v[26:29]
	v_mfma_f32_16x16x32_bf16 v[14:17], v[150:153], v[230:233], v[14:17]
	v_mfma_f32_16x16x32_bf16 v[10:13], v[178:181], v[230:233], v[10:13]
	s_setprio 0
	s_setprio 1
	v_mfma_f32_16x16x32_bf16 v[54:57], v[182:185], v[198:201], v[54:57]
	v_mfma_f32_16x16x32_bf16 v[50:53], v[190:193], v[198:201], v[50:53]
	v_mfma_f32_16x16x32_bf16 v[38:41], v[182:185], v[210:213], v[38:41]
	v_mfma_f32_16x16x32_bf16 v[34:37], v[190:193], v[210:213], v[34:37]
	v_mfma_f32_16x16x32_bf16 v[22:25], v[182:185], v[218:221], v[22:25]
	v_mfma_f32_16x16x32_bf16 v[18:21], v[190:193], v[218:221], v[18:21]
	v_mfma_f32_16x16x32_bf16 v[6:9], v[182:185], v[226:229], v[6:9]
	v_mfma_f32_16x16x32_bf16 v[2:5], v[190:193], v[226:229], v[2:5]
	v_mfma_f32_16x16x32_bf16 v[54:57], v[186:189], v[202:205], v[54:57]
	v_mfma_f32_16x16x32_bf16 v[50:53], v[194:197], v[202:205], v[50:53]
	v_mfma_f32_16x16x32_bf16 v[38:41], v[186:189], v[214:217], v[38:41]
	v_mfma_f32_16x16x32_bf16 v[34:37], v[194:197], v[214:217], v[34:37]
	v_mfma_f32_16x16x32_bf16 v[22:25], v[186:189], v[222:225], v[22:25]
	v_mfma_f32_16x16x32_bf16 v[18:21], v[194:197], v[222:225], v[18:21]
	v_mfma_f32_16x16x32_bf16 v[6:9], v[186:189], v[230:233], v[6:9]
	v_mfma_f32_16x16x32_bf16 v[2:5], v[194:197], v[230:233], v[2:5]
	s_setprio 0
	s_barrier
	s_add_i32 s66, 0, 0x18000
	v_add_u32_e32 v173, s66, v167
	s_add_i32 s67, 0, 0x1c000
	ds_read_b128 v[146:149], v173
	ds_read_b128 v[150:153], v173 offset:1024
	ds_read_b128 v[174:177], v173 offset:2048
	ds_read_b128 v[178:181], v173 offset:3072
	v_add_u32_e32 v173, s67, v167
	ds_read_b128 v[182:185], v173
	ds_read_b128 v[186:189], v173 offset:1024
	ds_read_b128 v[190:193], v173 offset:2048
	ds_read_b128 v[194:197], v173 offset:3072
	s_add_u32 s28, s28, 0x260000
	s_addc_u32 s29, s29, 0
	s_mov_b32 m0, s39
	v_lshl_add_u64 v[240:241], s[28:29], 0, v[130:131]
	ds_read_b128 v[198:201], v171 offset:32768
	ds_read_b128 v[202:205], v171 offset:33792
	ds_read_b128 v[210:213], v171 offset:34816
	ds_read_b128 v[214:217], v171 offset:35840
	ds_read_b128 v[218:221], v171 offset:36864
	ds_read_b128 v[222:225], v171 offset:37888
	ds_read_b128 v[226:229], v171 offset:38912
	ds_read_b128 v[230:233], v171 offset:39936
	global_load_lds_dwordx4 v[240:241], off
	v_lshl_add_u64 v[240:241], s[28:29], 0, v[132:133]
	s_mov_b32 m0, s40
	s_nop 0
	global_load_lds_dwordx4 v[240:241], off
	s_waitcnt vmcnt(8)
	s_waitcnt lgkmcnt(0)
	s_barrier
	s_setprio 1
	s_waitcnt lgkmcnt(0)
	v_mfma_f32_16x16x32_bf16 v[126:129], v[146:149], v[198:201], v[126:129]
	v_mfma_f32_16x16x32_bf16 v[122:125], v[174:177], v[198:201], v[122:125]
	v_mfma_f32_16x16x32_bf16 v[110:113], v[146:149], v[210:213], v[110:113]
	v_mfma_f32_16x16x32_bf16 v[106:109], v[174:177], v[210:213], v[106:109]
	v_mfma_f32_16x16x32_bf16 v[94:97], v[146:149], v[218:221], v[94:97]
	v_mfma_f32_16x16x32_bf16 v[90:93], v[174:177], v[218:221], v[90:93]
	v_mfma_f32_16x16x32_bf16 v[78:81], v[146:149], v[226:229], v[78:81]
	v_mfma_f32_16x16x32_bf16 v[74:77], v[174:177], v[226:229], v[74:77]
	v_mfma_f32_16x16x32_bf16 v[126:129], v[150:153], v[202:205], v[126:129]
	v_mfma_f32_16x16x32_bf16 v[122:125], v[178:181], v[202:205], v[122:125]
	v_mfma_f32_16x16x32_bf16 v[110:113], v[150:153], v[214:217], v[110:113]
	v_mfma_f32_16x16x32_bf16 v[106:109], v[178:181], v[214:217], v[106:109]
	v_mfma_f32_16x16x32_bf16 v[94:97], v[150:153], v[222:225], v[94:97]
	v_mfma_f32_16x16x32_bf16 v[90:93], v[178:181], v[222:225], v[90:93]
	v_mfma_f32_16x16x32_bf16 v[78:81], v[150:153], v[230:233], v[78:81]
	v_mfma_f32_16x16x32_bf16 v[74:77], v[178:181], v[230:233], v[74:77]
	s_setprio 0
	s_setprio 1
	v_mfma_f32_16x16x32_bf16 v[118:121], v[182:185], v[198:201], v[118:121]
	v_mfma_f32_16x16x32_bf16 v[114:117], v[190:193], v[198:201], v[114:117]
	v_mfma_f32_16x16x32_bf16 v[102:105], v[182:185], v[210:213], v[102:105]
	v_mfma_f32_16x16x32_bf16 v[98:101], v[190:193], v[210:213], v[98:101]
	v_mfma_f32_16x16x32_bf16 v[86:89], v[182:185], v[218:221], v[86:89]
	v_mfma_f32_16x16x32_bf16 v[82:85], v[190:193], v[218:221], v[82:85]
	v_mfma_f32_16x16x32_bf16 v[70:73], v[182:185], v[226:229], v[70:73]
	v_mfma_f32_16x16x32_bf16 v[66:69], v[190:193], v[226:229], v[66:69]
	v_mfma_f32_16x16x32_bf16 v[118:121], v[186:189], v[202:205], v[118:121]
	v_mfma_f32_16x16x32_bf16 v[114:117], v[194:197], v[202:205], v[114:117]
	v_mfma_f32_16x16x32_bf16 v[102:105], v[186:189], v[214:217], v[102:105]
	v_mfma_f32_16x16x32_bf16 v[98:101], v[194:197], v[214:217], v[98:101]
	v_mfma_f32_16x16x32_bf16 v[86:89], v[186:189], v[222:225], v[86:89]
	v_mfma_f32_16x16x32_bf16 v[82:85], v[194:197], v[222:225], v[82:85]
	v_mfma_f32_16x16x32_bf16 v[70:73], v[186:189], v[230:233], v[70:73]
	v_mfma_f32_16x16x32_bf16 v[66:69], v[194:197], v[230:233], v[66:69]
	s_setprio 0
	s_barrier
; #define PG8_STAGE(bufoff, gbase, voff) do { _Pragma("unroll") for (int _i = 0; _i < 2; ++_i) \
;         __builtin_amdgcn_global_load_lds((const unsigned*)((const char*)(gbase) + (voff)[_i]), (PG8_LAS unsigned*)(lds + (bufoff) + ldsw + _i * 8192), 16, 0, 0); } while (0)
; #define PG8_LDA(dst, b, h) do { _Pragma("unroll") for (int m = 0; m < 4; ++m) _Pragma("unroll") for (int k = 0; k < 2; ++k) dst[m][k] = *(const PG8_LAS bf16x8*)(lds + PG8_SA(b, h) + aoff + m * 2048 + k * 1024); } while (0)
; #define PG8_MMA(ai, bj, At, Bt) do { __builtin_amdgcn_s_setprio(1); _Pragma("unroll") for (int m = 0; m < 4; ++m) _Pragma("unroll") for (int n = 0; n < 2; ++n) _Pragma("unroll") for (int k = 0; k < 2; ++k) \
;         acc[ai][bj][m][n] = __builtin_amdgcn_mfma_f32_16x16x32_bf16(Bt[n][k], At[m][k], acc[ai][bj][m][n], 0, 0, 0); __builtin_amdgcn_s_setprio(0); } while (0)
; #define PG8_WAIT_V(n) asm volatile("s_waitcnt vmcnt(" #n ")" ::: "memory")
; #define PG8_WAIT_L(n) asm volatile("s_waitcnt lgkmcnt(" #n ")" ::: "memory")
; #define PG8_BAR __builtin_amdgcn_s_barrier()
; #define PG8_SCHED __builtin_amdgcn_sched_barrier(0)
; template <class Epi, class Sched>
; __device__ __forceinline__ void gemm_phase(PG8_LAS unsigned char* lds, const Gemm g, const Sched& S, const Epi& E) {
;     ...
;         for (int t = 0; t < nt; t += 2) {
;     ...
;             PG8_LDA(At, 1, 1); PG8_STAGE(PG8_SB(1, 0), b3, voffB); PG8_STAGE(PG8_SB(1, 1), b3 + hstepB, voffB); PG8_STAGE(PG8_SA(1, 0), a3, voffA);
;             PG8_WAIT_V(8); PG8_WAIT_L(0); PG8_BAR; PG8_MMA(1, 0, At, B0); PG8_MMA(1, 1, At, B1); PG8_BAR; PG8_SCHED;
;         }
;         if (wr == 0) PG8_BAR;
	s_add_i32 s28, s66, s36
	v_lshl_add_u64 v[206:207], v[206:207], 0, s[18:19]
	s_mov_b32 m0, s28
	ds_read_b128 v[198:201], v171 offset:49152
	ds_read_b128 v[202:205], v171 offset:50176
	ds_read_b128 v[210:213], v171 offset:51200
	ds_read_b128 v[214:217], v171 offset:52224
	ds_read_b128 v[218:221], v171 offset:53248
	ds_read_b128 v[222:225], v171 offset:54272
	ds_read_b128 v[226:229], v171 offset:55296
	ds_read_b128 v[230:233], v171 offset:56320
	global_load_lds_dwordx4 v[206:207], off
	s_add_i32 m0, s28, 0x2000
	s_add_u32 s4, s4, 0x20080
	v_lshl_add_u64 v[206:207], v[234:235], 0, s[18:19]
	s_addc_u32 s5, s5, 0
	s_add_i32 s28, s67, s36
	global_load_lds_dwordx4 v[206:207], off
	v_lshl_add_u64 v[206:207], s[4:5], 0, v[134:135]
	s_mov_b32 m0, s28
	s_nop 0
	global_load_lds_dwordx4 v[206:207], off
	v_lshl_add_u64 v[206:207], s[4:5], 0, v[136:137]
	s_add_i32 m0, s28, 0x2000
	s_nop 0
	global_load_lds_dwordx4 v[206:207], off
	v_lshl_add_u64 v[206:207], v[236:237], 0, s[18:19]
	s_mov_b32 m0, s42
	s_nop 0
	global_load_lds_dwordx4 v[206:207], off
	v_lshl_add_u64 v[206:207], v[238:239], 0, s[18:19]
	s_mov_b32 m0, s43
	s_nop 0
	global_load_lds_dwordx4 v[206:207], off
	s_waitcnt vmcnt(8)
	s_waitcnt lgkmcnt(0)
	s_barrier
	s_setprio 1
	s_waitcnt lgkmcnt(0)
	v_mfma_f32_16x16x32_bf16 v[62:65], v[146:149], v[198:201], v[62:65]
	v_mfma_f32_16x16x32_bf16 v[58:61], v[174:177], v[198:201], v[58:61]
	v_mfma_f32_16x16x32_bf16 v[46:49], v[146:149], v[210:213], v[46:49]
	v_mfma_f32_16x16x32_bf16 v[42:45], v[174:177], v[210:213], v[42:45]
	v_mfma_f32_16x16x32_bf16 v[30:33], v[146:149], v[218:221], v[30:33]
	v_mfma_f32_16x16x32_bf16 v[26:29], v[174:177], v[218:221], v[26:29]
	v_mfma_f32_16x16x32_bf16 v[14:17], v[146:149], v[226:229], v[14:17]
	v_mfma_f32_16x16x32_bf16 v[10:13], v[174:177], v[226:229], v[10:13]
	v_mfma_f32_16x16x32_bf16 v[62:65], v[150:153], v[202:205], v[62:65]
	v_mfma_f32_16x16x32_bf16 v[58:61], v[178:181], v[202:205], v[58:61]
	v_mfma_f32_16x16x32_bf16 v[46:49], v[150:153], v[214:217], v[46:49]
	v_mfma_f32_16x16x32_bf16 v[42:45], v[178:181], v[214:217], v[42:45]
	v_mfma_f32_16x16x32_bf16 v[30:33], v[150:153], v[222:225], v[30:33]
	v_mfma_f32_16x16x32_bf16 v[26:29], v[178:181], v[222:225], v[26:29]
	v_mfma_f32_16x16x32_bf16 v[14:17], v[150:153], v[230:233], v[14:17]
	v_mfma_f32_16x16x32_bf16 v[10:13], v[178:181], v[230:233], v[10:13]
	s_setprio 0
	s_setprio 1
	v_mfma_f32_16x16x32_bf16 v[54:57], v[182:185], v[198:201], v[54:57]
	v_mfma_f32_16x16x32_bf16 v[50:53], v[190:193], v[198:201], v[50:53]
	v_mfma_f32_16x16x32_bf16 v[38:41], v[182:185], v[210:213], v[38:41]
	v_mfma_f32_16x16x32_bf16 v[34:37], v[190:193], v[210:213], v[34:37]
	v_mfma_f32_16x16x32_bf16 v[22:25], v[182:185], v[218:221], v[22:25]
	v_mfma_f32_16x16x32_bf16 v[18:21], v[190:193], v[218:221], v[18:21]
	v_mfma_f32_16x16x32_bf16 v[6:9], v[182:185], v[226:229], v[6:9]
	v_mfma_f32_16x16x32_bf16 v[2:5], v[190:193], v[226:229], v[2:5]
	v_mfma_f32_16x16x32_bf16 v[54:57], v[186:189], v[202:205], v[54:57]
	v_mfma_f32_16x16x32_bf16 v[50:53], v[194:197], v[202:205], v[50:53]
	v_mfma_f32_16x16x32_bf16 v[38:41], v[186:189], v[214:217], v[38:41]
	v_mfma_f32_16x16x32_bf16 v[34:37], v[194:197], v[214:217], v[34:37]
	v_mfma_f32_16x16x32_bf16 v[22:25], v[186:189], v[222:225], v[22:25]
	v_mfma_f32_16x16x32_bf16 v[18:21], v[194:197], v[222:225], v[18:21]
	v_mfma_f32_16x16x32_bf16 v[6:9], v[186:189], v[230:233], v[6:9]
	v_mfma_f32_16x16x32_bf16 v[2:5], v[194:197], v[230:233], v[2:5]
	s_setprio 0
	s_add_i32 s91, s91, 2
	s_add_u32 s0, s0, 0x100
	s_addc_u32 s1, s1, 0
	s_add_u32 s88, s88, 0x100
	s_addc_u32 s89, s89, 0
	s_cmp_gt_u32 s91, 5
	s_barrier
	s_cbranch_scc0 .LBB0_350
	s_and_b64 vcc, exec, s[20:21]
	s_cbranch_vccz .LBB0_353
	s_barrier

; #define PG8_STAGE(bufoff, gbase, voff) do { _Pragma("unroll") for (int _i = 0; _i < 2; ++_i) \
;         __builtin_amdgcn_global_load_lds((const unsigned*)((const char*)(gbase) + (voff)[_i]), (PG8_LAS unsigned*)(lds + (bufoff) + ldsw + _i * 8192), 16, 0, 0); } while (0)
; #define PG8_LDA(dst, b, h) do { _Pragma("unroll") for (int m = 0; m < 4; ++m) _Pragma("unroll") for (int k = 0; k < 2; ++k) dst[m][k] = *(const PG8_LAS bf16x8*)(lds + PG8_SA(b, h) + aoff + m * 2048 + k * 1024); } while (0)
; #define PG8_LDB(dst, b, h) do { _Pragma("unroll") for (int n = 0; n < 2; ++n) _Pragma("unroll") for (int k = 0; k < 2; ++k) dst[n][k] = *(const PG8_LAS bf16x8*)(lds + PG8_SB(b, h) + boff + n * 2048 + k * 1024); } while (0)
; #define PG8_MMA(ai, bj, At, Bt) do { __builtin_amdgcn_s_setprio(1); _Pragma("unroll") for (int m = 0; m < 4; ++m) _Pragma("unroll") for (int n = 0; n < 2; ++n) _Pragma("unroll") for (int k = 0; k < 2; ++k) \
;         acc[ai][bj][m][n] = __builtin_amdgcn_mfma_f32_16x16x32_bf16(Bt[n][k], At[m][k], acc[ai][bj][m][n], 0, 0, 0); __builtin_amdgcn_s_setprio(0); } while (0)
; #define PG8_WAIT_V(n) asm volatile("s_waitcnt vmcnt(" #n ")" ::: "memory")
; #define PG8_WAIT_L(n) asm volatile("s_waitcnt lgkmcnt(" #n ")" ::: "memory")
; #define PG8_BAR __builtin_amdgcn_s_barrier()
; #define PG8_SCHED __builtin_amdgcn_sched_barrier(0)
; template <class Epi, class Sched>
; __device__ __forceinline__ void gemm_phase(PG8_LAS unsigned char* lds, const Gemm g, const Sched& S, const Epi& E) {
;     ...
;         for (int t = 0; t < nt; t += 2) {
;             const bool last = (t == nt - 2);
;             const char* a1 = cA + (size_t)(t + 1) * kstep;
;             const char* a2 = last ? nA : cA + (size_t)(t + 2) * kstep; const char* b2 = last ? nB : cB + (size_t)(t + 2) * kstep;
;             const char* a3 = a2 + kstep; const char* b3 = b2 + kstep;
;             PG8_LDB(B0, 0, 0); PG8_LDB(B1, 0, 1); PG8_SCHED; PG8_LDA(At, 0, 0); PG8_STAGE(PG8_SA(1, 1), a1 + hstepA, voffA);
;             PG8_WAIT_V(8); PG8_WAIT_L(0); PG8_BAR; PG8_MMA(0, 0, At, B0); PG8_MMA(0, 1, At, B1); PG8_BAR; PG8_SCHED;
;             PG8_LDA(At, 0, 1); PG8_STAGE(PG8_SB(0, 0), b2, voffB); PG8_STAGE(PG8_SB(0, 1), b2 + hstepB, voffB); PG8_STAGE(PG8_SA(0, 0), a2, voffA);
;             PG8_WAIT_V(8); PG8_WAIT_L(0); PG8_BAR; PG8_MMA(1, 0, At, B0); PG8_MMA(1, 1, At, B1); PG8_BAR; PG8_SCHED;
.LBB0_376:
	ds_read_b128 v[146:149], v1
	ds_read_b128 v[150:153], v1 offset:1024
	ds_read_b128 v[154:157], v1 offset:2048
	ds_read_b128 v[166:169], v1 offset:3072
	ds_read_b128 v[170:173], v163
	ds_read_b128 v[174:177], v163 offset:1024
	ds_read_b128 v[178:181], v163 offset:2048
	ds_read_b128 v[182:185], v163 offset:3072
	s_add_u32 s26, s4, 0xfffe0080
	s_addc_u32 s27, s5, -1
	s_cmp_eq_u32 s89, 4
	s_cselect_b32 s29, s19, s27
	s_cselect_b32 s28, s64, s26
	s_cselect_b32 s27, s21, s88
	s_cselect_b32 s26, s20, s65
	v_lshl_add_u64 v[158:159], s[4:5], 0, v[138:139]
	s_add_i32 m0, s25, 0xc000
	ds_read_b128 v[186:189], v164
	ds_read_b128 v[190:193], v164 offset:1024
	ds_read_b128 v[194:197], v164 offset:2048
	ds_read_b128 v[198:201], v164 offset:3072
	ds_read_b128 v[202:205], v164 offset:4096
	ds_read_b128 v[210:213], v164 offset:5120
	ds_read_b128 v[214:217], v164 offset:6144
	ds_read_b128 v[218:221], v164 offset:7168
	global_load_lds_dwordx4 v[158:159], off
	v_lshl_add_u64 v[158:159], s[4:5], 0, v[140:141]
	s_add_i32 m0, s25, 0xe000
	s_nop 0
	global_load_lds_dwordx4 v[158:159], off
	s_waitcnt vmcnt(8)
	s_waitcnt lgkmcnt(0)
	s_barrier
	s_setprio 1
	s_waitcnt lgkmcnt(0)
	v_mfma_f32_16x16x32_bf16 v[126:129], v[146:149], v[186:189], v[126:129]
	v_mfma_f32_16x16x32_bf16 v[122:125], v[154:157], v[186:189], v[122:125]
	v_mfma_f32_16x16x32_bf16 v[118:121], v[146:149], v[194:197], v[118:121]
	v_mfma_f32_16x16x32_bf16 v[114:117], v[154:157], v[194:197], v[114:117]
	v_mfma_f32_16x16x32_bf16 v[98:101], v[146:149], v[202:205], v[98:101]
	v_mfma_f32_16x16x32_bf16 v[90:93], v[154:157], v[202:205], v[90:93]
	v_mfma_f32_16x16x32_bf16 v[86:89], v[146:149], v[214:217], v[86:89]
	v_mfma_f32_16x16x32_bf16 v[78:81], v[154:157], v[214:217], v[78:81]
	v_mfma_f32_16x16x32_bf16 v[126:129], v[150:153], v[190:193], v[126:129]
	v_mfma_f32_16x16x32_bf16 v[122:125], v[166:169], v[190:193], v[122:125]
	v_mfma_f32_16x16x32_bf16 v[118:121], v[150:153], v[198:201], v[118:121]
	v_mfma_f32_16x16x32_bf16 v[114:117], v[166:169], v[198:201], v[114:117]
	v_mfma_f32_16x16x32_bf16 v[98:101], v[150:153], v[210:213], v[98:101]
	v_mfma_f32_16x16x32_bf16 v[90:93], v[166:169], v[210:213], v[90:93]
	v_mfma_f32_16x16x32_bf16 v[86:89], v[150:153], v[218:221], v[86:89]
	v_mfma_f32_16x16x32_bf16 v[78:81], v[166:169], v[218:221], v[78:81]
	s_setprio 0
	s_setprio 1
	v_mfma_f32_16x16x32_bf16 v[110:113], v[170:173], v[186:189], v[110:113]
	v_mfma_f32_16x16x32_bf16 v[106:109], v[178:181], v[186:189], v[106:109]
	v_mfma_f32_16x16x32_bf16 v[102:105], v[170:173], v[194:197], v[102:105]
	v_mfma_f32_16x16x32_bf16 v[94:97], v[178:181], v[194:197], v[94:97]
	v_mfma_f32_16x16x32_bf16 v[82:85], v[170:173], v[202:205], v[82:85]
	v_mfma_f32_16x16x32_bf16 v[74:77], v[178:181], v[202:205], v[74:77]
	v_mfma_f32_16x16x32_bf16 v[70:73], v[170:173], v[214:217], v[70:73]
	v_mfma_f32_16x16x32_bf16 v[66:69], v[178:181], v[214:217], v[66:69]
	v_mfma_f32_16x16x32_bf16 v[110:113], v[174:177], v[190:193], v[110:113]
	v_mfma_f32_16x16x32_bf16 v[106:109], v[182:185], v[190:193], v[106:109]
	v_mfma_f32_16x16x32_bf16 v[102:105], v[174:177], v[198:201], v[102:105]
	v_mfma_f32_16x16x32_bf16 v[94:97], v[182:185], v[198:201], v[94:97]
	v_mfma_f32_16x16x32_bf16 v[82:85], v[174:177], v[210:213], v[82:85]
	v_mfma_f32_16x16x32_bf16 v[74:77], v[182:185], v[210:213], v[74:77]
	v_mfma_f32_16x16x32_bf16 v[70:73], v[174:177], v[218:221], v[70:73]
	v_mfma_f32_16x16x32_bf16 v[66:69], v[182:185], v[218:221], v[66:69]
	s_setprio 0
	s_barrier
	s_add_i32 s66, s44, s36
	v_lshl_add_u64 v[158:159], s[26:27], 0, v[132:133]
	s_mov_b32 m0, s66
	ds_read_b128 v[186:189], v164 offset:16384
	ds_read_b128 v[190:193], v164 offset:17408
	ds_read_b128 v[194:197], v164 offset:18432
	ds_read_b128 v[198:201], v164 offset:19456
	ds_read_b128 v[202:205], v164 offset:20480
	ds_read_b128 v[210:213], v164 offset:21504
	ds_read_b128 v[214:217], v164 offset:22528
	ds_read_b128 v[218:221], v164 offset:23552
	global_load_lds_dwordx4 v[158:159], off
	s_add_i32 m0, s66, 0x2000
	s_add_u32 s92, s26, 0x260000
	v_lshl_add_u64 v[206:207], s[26:27], 0, v[136:137]
	s_addc_u32 s93, s27, 0
	s_add_i32 s66, s45, s36
	global_load_lds_dwordx4 v[206:207], off
	v_lshl_add_u64 v[222:223], s[92:93], 0, v[132:133]
	s_mov_b32 m0, s66
	v_lshl_add_u64 v[224:225], s[28:29], 0, v[134:135]
	global_load_lds_dwordx4 v[222:223], off
	v_lshl_add_u64 v[222:223], s[92:93], 0, v[136:137]
	s_add_i32 m0, s66, 0x2000
	s_nop 0
	global_load_lds_dwordx4 v[222:223], off
	v_lshl_add_u64 v[222:223], s[28:29], 0, v[130:131]
	s_mov_b32 m0, s25
	s_nop 0
	global_load_lds_dwordx4 v[222:223], off
	s_mov_b32 m0, s37
	s_nop 0
	global_load_lds_dwordx4 v[224:225], off
	s_waitcnt vmcnt(8)
	s_waitcnt lgkmcnt(0)
	s_barrier
; #define PG8_STAGE(bufoff, gbase, voff) do { _Pragma("unroll") for (int _i = 0; _i < 2; ++_i) \
;         __builtin_amdgcn_global_load_lds((const unsigned*)((const char*)(gbase) + (voff)[_i]), (PG8_LAS unsigned*)(lds + (bufoff) + ldsw + _i * 8192), 16, 0, 0); } while (0)
; #define PG8_LDA(dst, b, h) do { _Pragma("unroll") for (int m = 0; m < 4; ++m) _Pragma("unroll") for (int k = 0; k < 2; ++k) dst[m][k] = *(const PG8_LAS bf16x8*)(lds + PG8_SA(b, h) + aoff + m * 2048 + k * 1024); } while (0)
; #define PG8_LDB(dst, b, h) do { _Pragma("unroll") for (int n = 0; n < 2; ++n) _Pragma("unroll") for (int k = 0; k < 2; ++k) dst[n][k] = *(const PG8_LAS bf16x8*)(lds + PG8_SB(b, h) + boff + n * 2048 + k * 1024); } while (0)
; #define PG8_MMA(ai, bj, At, Bt) do { __builtin_amdgcn_s_setprio(1); _Pragma("unroll") for (int m = 0; m < 4; ++m) _Pragma("unroll") for (int n = 0; n < 2; ++n) _Pragma("unroll") for (int k = 0; k < 2; ++k) \
;         acc[ai][bj][m][n] = __builtin_amdgcn_mfma_f32_16x16x32_bf16(Bt[n][k], At[m][k], acc[ai][bj][m][n], 0, 0, 0); __builtin_amdgcn_s_setprio(0); } while (0)
; #define PG8_WAIT_V(n) asm volatile("s_waitcnt vmcnt(" #n ")" ::: "memory")
; #define PG8_WAIT_L(n) asm volatile("s_waitcnt lgkmcnt(" #n ")" ::: "memory")
; #define PG8_BAR __builtin_amdgcn_s_barrier()
; #define PG8_SCHED __builtin_amdgcn_sched_barrier(0)
; template <class Epi, class Sched>
; __device__ __forceinline__ void gemm_phase(PG8_LAS unsigned char* lds, const Gemm g, const Sched& S, const Epi& E) {
;     ...
;             PG8_WAIT_V(8); PG8_WAIT_L(0); PG8_BAR; PG8_MMA(1, 0, At, B0); PG8_MMA(1, 1, At, B1); PG8_BAR; PG8_SCHED;
;             PG8_LDB(B0, 1, 0); PG8_LDB(B1, 1, 1); PG8_SCHED; PG8_LDA(At, 1, 0); PG8_STAGE(PG8_SA(0, 1), a2 + hstepA, voffA);
;             PG8_WAIT_V(8); PG8_WAIT_L(0); PG8_BAR; PG8_MMA(0, 0, At, B0); PG8_MMA(0, 1, At, B1); PG8_BAR; PG8_SCHED;
	s_setprio 1
	s_waitcnt lgkmcnt(0)
	v_mfma_f32_16x16x32_bf16 v[62:65], v[146:149], v[186:189], v[62:65]
	v_mfma_f32_16x16x32_bf16 v[58:61], v[154:157], v[186:189], v[58:61]
	v_mfma_f32_16x16x32_bf16 v[54:57], v[146:149], v[194:197], v[54:57]
	v_mfma_f32_16x16x32_bf16 v[46:49], v[154:157], v[194:197], v[46:49]
	v_mfma_f32_16x16x32_bf16 v[38:41], v[146:149], v[202:205], v[38:41]
	v_mfma_f32_16x16x32_bf16 v[30:33], v[154:157], v[202:205], v[30:33]
	v_mfma_f32_16x16x32_bf16 v[22:25], v[146:149], v[214:217], v[22:25]
	v_mfma_f32_16x16x32_bf16 v[14:17], v[154:157], v[214:217], v[14:17]
	v_mfma_f32_16x16x32_bf16 v[62:65], v[150:153], v[190:193], v[62:65]
	v_mfma_f32_16x16x32_bf16 v[58:61], v[166:169], v[190:193], v[58:61]
	v_mfma_f32_16x16x32_bf16 v[54:57], v[150:153], v[198:201], v[54:57]
	v_mfma_f32_16x16x32_bf16 v[46:49], v[166:169], v[198:201], v[46:49]
	v_mfma_f32_16x16x32_bf16 v[38:41], v[150:153], v[210:213], v[38:41]
	v_mfma_f32_16x16x32_bf16 v[30:33], v[166:169], v[210:213], v[30:33]
	v_mfma_f32_16x16x32_bf16 v[22:25], v[150:153], v[218:221], v[22:25]
	v_mfma_f32_16x16x32_bf16 v[14:17], v[166:169], v[218:221], v[14:17]
	s_setprio 0
	s_setprio 1
	v_mfma_f32_16x16x32_bf16 v[50:53], v[170:173], v[186:189], v[50:53]
	v_mfma_f32_16x16x32_bf16 v[42:45], v[178:181], v[186:189], v[42:45]
	v_mfma_f32_16x16x32_bf16 v[34:37], v[170:173], v[194:197], v[34:37]
	v_mfma_f32_16x16x32_bf16 v[26:29], v[178:181], v[194:197], v[26:29]
	v_mfma_f32_16x16x32_bf16 v[18:21], v[170:173], v[202:205], v[18:21]
	v_mfma_f32_16x16x32_bf16 v[10:13], v[178:181], v[202:205], v[10:13]
	v_mfma_f32_16x16x32_bf16 v[6:9], v[170:173], v[214:217], v[6:9]
	v_mfma_f32_16x16x32_bf16 v[2:5], v[178:181], v[214:217], v[2:5]
	v_mfma_f32_16x16x32_bf16 v[50:53], v[174:177], v[190:193], v[50:53]
	v_mfma_f32_16x16x32_bf16 v[42:45], v[182:185], v[190:193], v[42:45]
	v_mfma_f32_16x16x32_bf16 v[34:37], v[174:177], v[198:201], v[34:37]
	v_mfma_f32_16x16x32_bf16 v[26:29], v[182:185], v[198:201], v[26:29]
	v_mfma_f32_16x16x32_bf16 v[18:21], v[174:177], v[210:213], v[18:21]
	v_mfma_f32_16x16x32_bf16 v[10:13], v[182:185], v[210:213], v[10:13]
	v_mfma_f32_16x16x32_bf16 v[6:9], v[174:177], v[218:221], v[6:9]
	v_mfma_f32_16x16x32_bf16 v[2:5], v[182:185], v[218:221], v[2:5]
	s_setprio 0
	s_barrier
	s_add_i32 s66, 0, 0x18000
	s_add_i32 s67, 0, 0x1c000
	v_add_u32_e32 v166, s66, v160
	v_add_u32_e32 v182, s67, v160
	ds_read_b128 v[146:149], v166
	ds_read_b128 v[150:153], v166 offset:1024
	ds_read_b128 v[154:157], v166 offset:2048
	ds_read_b128 v[166:169], v166 offset:3072
	ds_read_b128 v[170:173], v182
	ds_read_b128 v[174:177], v182 offset:1024
	ds_read_b128 v[178:181], v182 offset:2048
	ds_read_b128 v[182:185], v182 offset:3072
	s_add_u32 s28, s28, 0x20000
	s_addc_u32 s29, s29, 0
	s_mov_b32 m0, s38
	v_lshl_add_u64 v[226:227], s[28:29], 0, v[130:131]
	ds_read_b128 v[186:189], v164 offset:32768
	ds_read_b128 v[190:193], v164 offset:33792
	ds_read_b128 v[194:197], v164 offset:34816
	ds_read_b128 v[198:201], v164 offset:35840
	ds_read_b128 v[202:205], v164 offset:36864
	ds_read_b128 v[210:213], v164 offset:37888
	ds_read_b128 v[214:217], v164 offset:38912
	ds_read_b128 v[218:221], v164 offset:39936
	global_load_lds_dwordx4 v[226:227], off
	v_lshl_add_u64 v[226:227], s[28:29], 0, v[134:135]
	s_mov_b32 m0, s39
	s_nop 0
	global_load_lds_dwordx4 v[226:227], off
	s_waitcnt vmcnt(8)
	s_waitcnt lgkmcnt(0)
	s_barrier
	s_setprio 1
	s_waitcnt lgkmcnt(0)
	v_mfma_f32_16x16x32_bf16 v[126:129], v[146:149], v[186:189], v[126:129]
	v_mfma_f32_16x16x32_bf16 v[122:125], v[154:157], v[186:189], v[122:125]
	v_mfma_f32_16x16x32_bf16 v[118:121], v[146:149], v[194:197], v[118:121]
	v_mfma_f32_16x16x32_bf16 v[114:117], v[154:157], v[194:197], v[114:117]
	v_mfma_f32_16x16x32_bf16 v[98:101], v[146:149], v[202:205], v[98:101]
	v_mfma_f32_16x16x32_bf16 v[90:93], v[154:157], v[202:205], v[90:93]
	v_mfma_f32_16x16x32_bf16 v[86:89], v[146:149], v[214:217], v[86:89]
	v_mfma_f32_16x16x32_bf16 v[78:81], v[154:157], v[214:217], v[78:81]
	v_mfma_f32_16x16x32_bf16 v[126:129], v[150:153], v[190:193], v[126:129]
	v_mfma_f32_16x16x32_bf16 v[122:125], v[166:169], v[190:193], v[122:125]
	v_mfma_f32_16x16x32_bf16 v[118:121], v[150:153], v[198:201], v[118:121]
	v_mfma_f32_16x16x32_bf16 v[114:117], v[166:169], v[198:201], v[114:117]
	v_mfma_f32_16x16x32_bf16 v[98:101], v[150:153], v[210:213], v[98:101]
	v_mfma_f32_16x16x32_bf16 v[90:93], v[166:169], v[210:213], v[90:93]
	v_mfma_f32_16x16x32_bf16 v[86:89], v[150:153], v[218:221], v[86:89]
	v_mfma_f32_16x16x32_bf16 v[78:81], v[166:169], v[218:221], v[78:81]
	s_setprio 0
	s_setprio 1
	v_mfma_f32_16x16x32_bf16 v[110:113], v[170:173], v[186:189], v[110:113]
	v_mfma_f32_16x16x32_bf16 v[106:109], v[178:181], v[186:189], v[106:109]
	v_mfma_f32_16x16x32_bf16 v[102:105], v[170:173], v[194:197], v[102:105]
	v_mfma_f32_16x16x32_bf16 v[94:97], v[178:181], v[194:197], v[94:97]
	v_mfma_f32_16x16x32_bf16 v[82:85], v[170:173], v[202:205], v[82:85]
	v_mfma_f32_16x16x32_bf16 v[74:77], v[178:181], v[202:205], v[74:77]
	v_mfma_f32_16x16x32_bf16 v[70:73], v[170:173], v[214:217], v[70:73]
	v_mfma_f32_16x16x32_bf16 v[66:69], v[178:181], v[214:217], v[66:69]
	v_mfma_f32_16x16x32_bf16 v[110:113], v[174:177], v[190:193], v[110:113]
	v_mfma_f32_16x16x32_bf16 v[106:109], v[182:185], v[190:193], v[106:109]
	v_mfma_f32_16x16x32_bf16 v[102:105], v[174:177], v[198:201], v[102:105]
	v_mfma_f32_16x16x32_bf16 v[94:97], v[182:185], v[198:201], v[94:97]
	v_mfma_f32_16x16x32_bf16 v[82:85], v[174:177], v[210:213], v[82:85]
	v_mfma_f32_16x16x32_bf16 v[74:77], v[182:185], v[210:213], v[74:77]
	v_mfma_f32_16x16x32_bf16 v[70:73], v[174:177], v[218:221], v[70:73]
	v_mfma_f32_16x16x32_bf16 v[66:69], v[182:185], v[218:221], v[66:69]
	s_setprio 0
	s_barrier
; #define PG8_STAGE(bufoff, gbase, voff) do { _Pragma("unroll") for (int _i = 0; _i < 2; ++_i) \
;         __builtin_amdgcn_global_load_lds((const unsigned*)((const char*)(gbase) + (voff)[_i]), (PG8_LAS unsigned*)(lds + (bufoff) + ldsw + _i * 8192), 16, 0, 0); } while (0)
; #define PG8_LDA(dst, b, h) do { _Pragma("unroll") for (int m = 0; m < 4; ++m) _Pragma("unroll") for (int k = 0; k < 2; ++k) dst[m][k] = *(const PG8_LAS bf16x8*)(lds + PG8_SA(b, h) + aoff + m * 2048 + k * 1024); } while (0)
; #define PG8_MMA(ai, bj, At, Bt) do { __builtin_amdgcn_s_setprio(1); _Pragma("unroll") for (int m = 0; m < 4; ++m) _Pragma("unroll") for (int n = 0; n < 2; ++n) _Pragma("unroll") for (int k = 0; k < 2; ++k) \
;         acc[ai][bj][m][n] = __builtin_amdgcn_mfma_f32_16x16x32_bf16(Bt[n][k], At[m][k], acc[ai][bj][m][n], 0, 0, 0); __builtin_amdgcn_s_setprio(0); } while (0)
; #define PG8_WAIT_V(n) asm volatile("s_waitcnt vmcnt(" #n ")" ::: "memory")
; #define PG8_WAIT_L(n) asm volatile("s_waitcnt lgkmcnt(" #n ")" ::: "memory")
; #define PG8_BAR __builtin_amdgcn_s_barrier()
; #define PG8_SCHED __builtin_amdgcn_sched_barrier(0)
; template <class Epi, class Sched>
; __device__ __forceinline__ void gemm_phase(PG8_LAS unsigned char* lds, const Gemm g, const Sched& S, const Epi& E) {
;     ...
;         for (int t = 0; t < nt; t += 2) {
;     ...
;             PG8_LDA(At, 1, 1); PG8_STAGE(PG8_SB(1, 0), b3, voffB); PG8_STAGE(PG8_SB(1, 1), b3 + hstepB, voffB); PG8_STAGE(PG8_SA(1, 0), a3, voffA);
;             PG8_WAIT_V(8); PG8_WAIT_L(0); PG8_BAR; PG8_MMA(1, 0, At, B0); PG8_MMA(1, 1, At, B1); PG8_BAR; PG8_SCHED;
;         }
;         if (wr == 0) PG8_BAR;
	s_add_i32 s28, s66, s36
	v_lshl_add_u64 v[158:159], v[158:159], 0, s[14:15]
	s_mov_b32 m0, s28
	ds_read_b128 v[186:189], v164 offset:49152
	ds_read_b128 v[190:193], v164 offset:50176
	ds_read_b128 v[194:197], v164 offset:51200
	ds_read_b128 v[198:201], v164 offset:52224
	ds_read_b128 v[202:205], v164 offset:53248
	ds_read_b128 v[210:213], v164 offset:54272
	ds_read_b128 v[214:217], v164 offset:55296
	ds_read_b128 v[218:221], v164 offset:56320
	global_load_lds_dwordx4 v[158:159], off
	s_add_i32 m0, s28, 0x2000
	s_add_u32 s26, s26, 0x260080
	v_lshl_add_u64 v[158:159], v[206:207], 0, s[14:15]
	s_addc_u32 s27, s27, 0
	s_add_i32 s28, s67, s36
	global_load_lds_dwordx4 v[158:159], off
	v_lshl_add_u64 v[158:159], s[26:27], 0, v[132:133]
	s_mov_b32 m0, s28
	s_nop 0
	global_load_lds_dwordx4 v[158:159], off
	v_lshl_add_u64 v[158:159], s[26:27], 0, v[136:137]
	s_add_i32 m0, s28, 0x2000
	s_nop 0
	global_load_lds_dwordx4 v[158:159], off
	v_lshl_add_u64 v[158:159], v[222:223], 0, s[14:15]
	s_mov_b32 m0, s41
	s_nop 0
	global_load_lds_dwordx4 v[158:159], off
	v_lshl_add_u64 v[158:159], v[224:225], 0, s[14:15]
	s_mov_b32 m0, s42
	s_nop 0
	global_load_lds_dwordx4 v[158:159], off
	s_waitcnt vmcnt(8)
	s_waitcnt lgkmcnt(0)
	s_barrier
	s_setprio 1
	s_waitcnt lgkmcnt(0)
	v_mfma_f32_16x16x32_bf16 v[62:65], v[146:149], v[186:189], v[62:65]
	v_mfma_f32_16x16x32_bf16 v[58:61], v[154:157], v[186:189], v[58:61]
	v_mfma_f32_16x16x32_bf16 v[54:57], v[146:149], v[194:197], v[54:57]
	v_mfma_f32_16x16x32_bf16 v[46:49], v[154:157], v[194:197], v[46:49]
	v_mfma_f32_16x16x32_bf16 v[38:41], v[146:149], v[202:205], v[38:41]
	v_mfma_f32_16x16x32_bf16 v[30:33], v[154:157], v[202:205], v[30:33]
	v_mfma_f32_16x16x32_bf16 v[22:25], v[146:149], v[214:217], v[22:25]
	v_mfma_f32_16x16x32_bf16 v[14:17], v[154:157], v[214:217], v[14:17]
	v_mfma_f32_16x16x32_bf16 v[62:65], v[150:153], v[190:193], v[62:65]
	v_mfma_f32_16x16x32_bf16 v[58:61], v[166:169], v[190:193], v[58:61]
	v_mfma_f32_16x16x32_bf16 v[54:57], v[150:153], v[198:201], v[54:57]
	v_mfma_f32_16x16x32_bf16 v[46:49], v[166:169], v[198:201], v[46:49]
	v_mfma_f32_16x16x32_bf16 v[38:41], v[150:153], v[210:213], v[38:41]
	v_mfma_f32_16x16x32_bf16 v[30:33], v[166:169], v[210:213], v[30:33]
	v_mfma_f32_16x16x32_bf16 v[22:25], v[150:153], v[218:221], v[22:25]
	v_mfma_f32_16x16x32_bf16 v[14:17], v[166:169], v[218:221], v[14:17]
	s_setprio 0
	s_setprio 1
	v_mfma_f32_16x16x32_bf16 v[50:53], v[170:173], v[186:189], v[50:53]
	v_mfma_f32_16x16x32_bf16 v[42:45], v[178:181], v[186:189], v[42:45]
	v_mfma_f32_16x16x32_bf16 v[34:37], v[170:173], v[194:197], v[34:37]
	v_mfma_f32_16x16x32_bf16 v[26:29], v[178:181], v[194:197], v[26:29]
	v_mfma_f32_16x16x32_bf16 v[18:21], v[170:173], v[202:205], v[18:21]
	v_mfma_f32_16x16x32_bf16 v[10:13], v[178:181], v[202:205], v[10:13]
	v_mfma_f32_16x16x32_bf16 v[6:9], v[170:173], v[214:217], v[6:9]
	v_mfma_f32_16x16x32_bf16 v[2:5], v[178:181], v[214:217], v[2:5]
	v_mfma_f32_16x16x32_bf16 v[50:53], v[174:177], v[190:193], v[50:53]
	v_mfma_f32_16x16x32_bf16 v[42:45], v[182:185], v[190:193], v[42:45]
	v_mfma_f32_16x16x32_bf16 v[34:37], v[174:177], v[198:201], v[34:37]
	v_mfma_f32_16x16x32_bf16 v[26:29], v[182:185], v[198:201], v[26:29]
	v_mfma_f32_16x16x32_bf16 v[18:21], v[174:177], v[210:213], v[18:21]
	v_mfma_f32_16x16x32_bf16 v[10:13], v[182:185], v[210:213], v[10:13]
	v_mfma_f32_16x16x32_bf16 v[6:9], v[174:177], v[218:221], v[6:9]
	v_mfma_f32_16x16x32_bf16 v[2:5], v[182:185], v[218:221], v[2:5]
	s_setprio 0
	s_add_i32 s89, s89, 2
	s_add_u32 s4, s4, 0x100
	s_addc_u32 s5, s5, 0
	s_add_u32 s65, s65, 0x100
	s_addc_u32 s88, s88, 0
	s_cmp_gt_u32 s89, 5
	s_barrier
	s_cbranch_scc0 .LBB0_376
	s_and_b64 vcc, exec, s[16:17]
	s_cbranch_vccz .LBB0_379
	s_barrier

; #define PG8_STAGE(bufoff, gbase, voff) do { _Pragma("unroll") for (int _i = 0; _i < 2; ++_i) \
;         __builtin_amdgcn_global_load_lds((const unsigned*)((const char*)(gbase) + (voff)[_i]), (PG8_LAS unsigned*)(lds + (bufoff) + ldsw + _i * 8192), 16, 0, 0); } while (0)
; #define PG8_LDA(dst, b, h) do { _Pragma("unroll") for (int m = 0; m < 4; ++m) _Pragma("unroll") for (int k = 0; k < 2; ++k) dst[m][k] = *(const PG8_LAS bf16x8*)(lds + PG8_SA(b, h) + aoff + m * 2048 + k * 1024); } while (0)
; #define PG8_LDB(dst, b, h) do { _Pragma("unroll") for (int n = 0; n < 2; ++n) _Pragma("unroll") for (int k = 0; k < 2; ++k) dst[n][k] = *(const PG8_LAS bf16x8*)(lds + PG8_SB(b, h) + boff + n * 2048 + k * 1024); } while (0)
; #define PG8_MMA(ai, bj, At, Bt) do { __builtin_amdgcn_s_setprio(1); _Pragma("unroll") for (int m = 0; m < 4; ++m) _Pragma("unroll") for (int n = 0; n < 2; ++n) _Pragma("unroll") for (int k = 0; k < 2; ++k) \
;         acc[ai][bj][m][n] = __builtin_amdgcn_mfma_f32_16x16x32_bf16(Bt[n][k], At[m][k], acc[ai][bj][m][n], 0, 0, 0); __builtin_amdgcn_s_setprio(0); } while (0)
; #define PG8_WAIT_V(n) asm volatile("s_waitcnt vmcnt(" #n ")" ::: "memory")
; #define PG8_WAIT_L(n) asm volatile("s_waitcnt lgkmcnt(" #n ")" ::: "memory")
; #define PG8_BAR __builtin_amdgcn_s_barrier()
; #define PG8_SCHED __builtin_amdgcn_sched_barrier(0)
; template <class Epi, class Sched>
; __device__ __forceinline__ void gemm_phase(PG8_LAS unsigned char* lds, const Gemm g, const Sched& S, const Epi& E) {
;     ...
;         for (int t = 0; t < nt; t += 2) {
;             const bool last = (t == nt - 2);
;             const char* a1 = cA + (size_t)(t + 1) * kstep;
;             const char* a2 = last ? nA : cA + (size_t)(t + 2) * kstep; const char* b2 = last ? nB : cB + (size_t)(t + 2) * kstep;
;             const char* a3 = a2 + kstep; const char* b3 = b2 + kstep;
;             PG8_LDB(B0, 0, 0); PG8_LDB(B1, 0, 1); PG8_SCHED; PG8_LDA(At, 0, 0); PG8_STAGE(PG8_SA(1, 1), a1 + hstepA, voffA);
;             PG8_WAIT_V(8); PG8_WAIT_L(0); PG8_BAR; PG8_MMA(0, 0, At, B0); PG8_MMA(0, 1, At, B1); PG8_BAR; PG8_SCHED;
;             PG8_LDA(At, 0, 1); PG8_STAGE(PG8_SB(0, 0), b2, voffB); PG8_STAGE(PG8_SB(0, 1), b2 + hstepB, voffB); PG8_STAGE(PG8_SA(0, 0), a2, voffA);
;             PG8_WAIT_V(8); PG8_WAIT_L(0); PG8_BAR; PG8_MMA(1, 0, At, B0); PG8_MMA(1, 1, At, B1); PG8_BAR; PG8_SCHED;
.LBB0_591:
	ds_read_b128 v[146:149], v154
	ds_read_b128 v[158:161], v154 offset:1024
	ds_read_b128 v[162:165], v154 offset:2048
	ds_read_b128 v[166:169], v154 offset:3072
	ds_read_b128 v[170:173], v155
	ds_read_b128 v[174:177], v155 offset:1024
	ds_read_b128 v[178:181], v155 offset:2048
	ds_read_b128 v[182:185], v155 offset:3072
	s_add_u32 s34, s30, 0xfff00080
	s_addc_u32 s35, s31, -1
	s_cmp_eq_u32 s66, 60
	s_cselect_b32 s37, s21, s35
	s_cselect_b32 s36, s27, s34
	s_cselect_b32 s35, s19, s65
	s_cselect_b32 s34, s53, s64
	v_lshl_add_u64 v[150:151], s[30:31], 0, v[138:139]
	s_add_i32 m0, s29, 0xc000
	ds_read_b128 v[186:189], v156
	ds_read_b128 v[190:193], v156 offset:1024
	ds_read_b128 v[194:197], v156 offset:2048
	ds_read_b128 v[198:201], v156 offset:3072
	ds_read_b128 v[202:205], v156 offset:4096
	ds_read_b128 v[210:213], v156 offset:5120
	ds_read_b128 v[214:217], v156 offset:6144
	ds_read_b128 v[218:221], v156 offset:7168
	global_load_lds_dwordx4 v[150:151], off
	v_lshl_add_u64 v[150:151], s[30:31], 0, v[140:141]
	s_add_i32 m0, s29, 0xe000
	s_nop 0
	global_load_lds_dwordx4 v[150:151], off
	s_waitcnt vmcnt(8)
	s_waitcnt lgkmcnt(0)
	s_barrier
	s_setprio 1
	s_waitcnt lgkmcnt(0)
	v_mfma_f32_16x16x32_bf16 v[126:129], v[146:149], v[186:189], v[126:129]
	v_mfma_f32_16x16x32_bf16 v[122:125], v[162:165], v[186:189], v[122:125]
	v_mfma_f32_16x16x32_bf16 v[110:113], v[146:149], v[194:197], v[110:113]
	v_mfma_f32_16x16x32_bf16 v[106:109], v[162:165], v[194:197], v[106:109]
	v_mfma_f32_16x16x32_bf16 v[94:97], v[146:149], v[202:205], v[94:97]
	v_mfma_f32_16x16x32_bf16 v[90:93], v[162:165], v[202:205], v[90:93]
	v_mfma_f32_16x16x32_bf16 v[78:81], v[146:149], v[214:217], v[78:81]
	v_mfma_f32_16x16x32_bf16 v[74:77], v[162:165], v[214:217], v[74:77]
	v_mfma_f32_16x16x32_bf16 v[126:129], v[158:161], v[190:193], v[126:129]
	v_mfma_f32_16x16x32_bf16 v[122:125], v[166:169], v[190:193], v[122:125]
	v_mfma_f32_16x16x32_bf16 v[110:113], v[158:161], v[198:201], v[110:113]
	v_mfma_f32_16x16x32_bf16 v[106:109], v[166:169], v[198:201], v[106:109]
	v_mfma_f32_16x16x32_bf16 v[94:97], v[158:161], v[210:213], v[94:97]
	v_mfma_f32_16x16x32_bf16 v[90:93], v[166:169], v[210:213], v[90:93]
	v_mfma_f32_16x16x32_bf16 v[78:81], v[158:161], v[218:221], v[78:81]
	v_mfma_f32_16x16x32_bf16 v[74:77], v[166:169], v[218:221], v[74:77]
	s_setprio 0
	s_setprio 1
	v_mfma_f32_16x16x32_bf16 v[118:121], v[170:173], v[186:189], v[118:121]
	v_mfma_f32_16x16x32_bf16 v[114:117], v[178:181], v[186:189], v[114:117]
	v_mfma_f32_16x16x32_bf16 v[102:105], v[170:173], v[194:197], v[102:105]
	v_mfma_f32_16x16x32_bf16 v[98:101], v[178:181], v[194:197], v[98:101]
	v_mfma_f32_16x16x32_bf16 v[86:89], v[170:173], v[202:205], v[86:89]
	v_mfma_f32_16x16x32_bf16 v[82:85], v[178:181], v[202:205], v[82:85]
	v_mfma_f32_16x16x32_bf16 v[70:73], v[170:173], v[214:217], v[70:73]
	v_mfma_f32_16x16x32_bf16 v[66:69], v[178:181], v[214:217], v[66:69]
	v_mfma_f32_16x16x32_bf16 v[118:121], v[174:177], v[190:193], v[118:121]
	v_mfma_f32_16x16x32_bf16 v[114:117], v[182:185], v[190:193], v[114:117]
	v_mfma_f32_16x16x32_bf16 v[102:105], v[174:177], v[198:201], v[102:105]
	v_mfma_f32_16x16x32_bf16 v[98:101], v[182:185], v[198:201], v[98:101]
	v_mfma_f32_16x16x32_bf16 v[86:89], v[174:177], v[210:213], v[86:89]
	v_mfma_f32_16x16x32_bf16 v[82:85], v[182:185], v[210:213], v[82:85]
	v_mfma_f32_16x16x32_bf16 v[70:73], v[174:177], v[218:221], v[70:73]
	v_mfma_f32_16x16x32_bf16 v[66:69], v[182:185], v[218:221], v[66:69]
	s_setprio 0
	s_barrier
	s_add_i32 s67, s51, s41
	v_lshl_add_u64 v[150:151], s[34:35], 0, v[132:133]
	s_mov_b32 m0, s67
	ds_read_b128 v[186:189], v156 offset:16384
	ds_read_b128 v[190:193], v156 offset:17408
	ds_read_b128 v[194:197], v156 offset:18432
	ds_read_b128 v[198:201], v156 offset:19456
	ds_read_b128 v[202:205], v156 offset:20480
	ds_read_b128 v[210:213], v156 offset:21504
	ds_read_b128 v[214:217], v156 offset:22528
	ds_read_b128 v[218:221], v156 offset:23552
	global_load_lds_dwordx4 v[150:151], off
	s_add_i32 m0, s67, 0x2000
	s_add_u32 s88, s34, 0x100000
	v_lshl_add_u64 v[206:207], s[34:35], 0, v[136:137]
	s_addc_u32 s89, s35, 0
	s_add_i32 s67, s52, s41
	global_load_lds_dwordx4 v[206:207], off
	v_lshl_add_u64 v[222:223], s[88:89], 0, v[132:133]
	s_mov_b32 m0, s67
	v_lshl_add_u64 v[224:225], s[36:37], 0, v[134:135]
	global_load_lds_dwordx4 v[222:223], off
	v_lshl_add_u64 v[222:223], s[88:89], 0, v[136:137]
	s_add_i32 m0, s67, 0x2000
	s_nop 0
	global_load_lds_dwordx4 v[222:223], off
	v_lshl_add_u64 v[222:223], s[36:37], 0, v[130:131]
	s_mov_b32 m0, s29
	s_nop 0
	global_load_lds_dwordx4 v[222:223], off
	s_mov_b32 m0, s42
	s_nop 0
	global_load_lds_dwordx4 v[224:225], off
	s_waitcnt vmcnt(8)
	s_waitcnt lgkmcnt(0)
	s_barrier
; #define PG8_STAGE(bufoff, gbase, voff) do { _Pragma("unroll") for (int _i = 0; _i < 2; ++_i) \
;         __builtin_amdgcn_global_load_lds((const unsigned*)((const char*)(gbase) + (voff)[_i]), (PG8_LAS unsigned*)(lds + (bufoff) + ldsw + _i * 8192), 16, 0, 0); } while (0)
; #define PG8_LDA(dst, b, h) do { _Pragma("unroll") for (int m = 0; m < 4; ++m) _Pragma("unroll") for (int k = 0; k < 2; ++k) dst[m][k] = *(const PG8_LAS bf16x8*)(lds + PG8_SA(b, h) + aoff + m * 2048 + k * 1024); } while (0)
; #define PG8_LDB(dst, b, h) do { _Pragma("unroll") for (int n = 0; n < 2; ++n) _Pragma("unroll") for (int k = 0; k < 2; ++k) dst[n][k] = *(const PG8_LAS bf16x8*)(lds + PG8_SB(b, h) + boff + n * 2048 + k * 1024); } while (0)
; #define PG8_MMA(ai, bj, At, Bt) do { __builtin_amdgcn_s_setprio(1); _Pragma("unroll") for (int m = 0; m < 4; ++m) _Pragma("unroll") for (int n = 0; n < 2; ++n) _Pragma("unroll") for (int k = 0; k < 2; ++k) \
;         acc[ai][bj][m][n] = __builtin_amdgcn_mfma_f32_16x16x32_bf16(Bt[n][k], At[m][k], acc[ai][bj][m][n], 0, 0, 0); __builtin_amdgcn_s_setprio(0); } while (0)
; #define PG8_WAIT_V(n) asm volatile("s_waitcnt vmcnt(" #n ")" ::: "memory")
; #define PG8_WAIT_L(n) asm volatile("s_waitcnt lgkmcnt(" #n ")" ::: "memory")
; #define PG8_BAR __builtin_amdgcn_s_barrier()
; #define PG8_SCHED __builtin_amdgcn_sched_barrier(0)
; template <class Epi, class Sched>
; __device__ __forceinline__ void gemm_phase(PG8_LAS unsigned char* lds, const Gemm g, const Sched& S, const Epi& E) {
;     ...
;             PG8_WAIT_V(8); PG8_WAIT_L(0); PG8_BAR; PG8_MMA(1, 0, At, B0); PG8_MMA(1, 1, At, B1); PG8_BAR; PG8_SCHED;
;             PG8_LDB(B0, 1, 0); PG8_LDB(B1, 1, 1); PG8_SCHED; PG8_LDA(At, 1, 0); PG8_STAGE(PG8_SA(0, 1), a2 + hstepA, voffA);
;             PG8_WAIT_V(8); PG8_WAIT_L(0); PG8_BAR; PG8_MMA(0, 0, At, B0); PG8_MMA(0, 1, At, B1); PG8_BAR; PG8_SCHED;
	s_setprio 1
	s_waitcnt lgkmcnt(0)
	v_mfma_f32_16x16x32_bf16 v[62:65], v[146:149], v[186:189], v[62:65]
	v_mfma_f32_16x16x32_bf16 v[58:61], v[162:165], v[186:189], v[58:61]
	v_mfma_f32_16x16x32_bf16 v[46:49], v[146:149], v[194:197], v[46:49]
	v_mfma_f32_16x16x32_bf16 v[42:45], v[162:165], v[194:197], v[42:45]
	v_mfma_f32_16x16x32_bf16 v[30:33], v[146:149], v[202:205], v[30:33]
	v_mfma_f32_16x16x32_bf16 v[26:29], v[162:165], v[202:205], v[26:29]
	v_mfma_f32_16x16x32_bf16 v[14:17], v[146:149], v[214:217], v[14:17]
	v_mfma_f32_16x16x32_bf16 v[10:13], v[162:165], v[214:217], v[10:13]
	v_mfma_f32_16x16x32_bf16 v[62:65], v[158:161], v[190:193], v[62:65]
	v_mfma_f32_16x16x32_bf16 v[58:61], v[166:169], v[190:193], v[58:61]
	v_mfma_f32_16x16x32_bf16 v[46:49], v[158:161], v[198:201], v[46:49]
	v_mfma_f32_16x16x32_bf16 v[42:45], v[166:169], v[198:201], v[42:45]
	v_mfma_f32_16x16x32_bf16 v[30:33], v[158:161], v[210:213], v[30:33]
	v_mfma_f32_16x16x32_bf16 v[26:29], v[166:169], v[210:213], v[26:29]
	v_mfma_f32_16x16x32_bf16 v[14:17], v[158:161], v[218:221], v[14:17]
	v_mfma_f32_16x16x32_bf16 v[10:13], v[166:169], v[218:221], v[10:13]
	s_setprio 0
	s_setprio 1
	v_mfma_f32_16x16x32_bf16 v[54:57], v[170:173], v[186:189], v[54:57]
	v_mfma_f32_16x16x32_bf16 v[50:53], v[178:181], v[186:189], v[50:53]
	v_mfma_f32_16x16x32_bf16 v[38:41], v[170:173], v[194:197], v[38:41]
	v_mfma_f32_16x16x32_bf16 v[34:37], v[178:181], v[194:197], v[34:37]
	v_mfma_f32_16x16x32_bf16 v[22:25], v[170:173], v[202:205], v[22:25]
	v_mfma_f32_16x16x32_bf16 v[18:21], v[178:181], v[202:205], v[18:21]
	v_mfma_f32_16x16x32_bf16 v[6:9], v[170:173], v[214:217], v[6:9]
	v_mfma_f32_16x16x32_bf16 v[2:5], v[178:181], v[214:217], v[2:5]
	v_mfma_f32_16x16x32_bf16 v[54:57], v[174:177], v[190:193], v[54:57]
	v_mfma_f32_16x16x32_bf16 v[50:53], v[182:185], v[190:193], v[50:53]
	v_mfma_f32_16x16x32_bf16 v[38:41], v[174:177], v[198:201], v[38:41]
	v_mfma_f32_16x16x32_bf16 v[34:37], v[182:185], v[198:201], v[34:37]
	v_mfma_f32_16x16x32_bf16 v[22:25], v[174:177], v[210:213], v[22:25]
	v_mfma_f32_16x16x32_bf16 v[18:21], v[182:185], v[210:213], v[18:21]
	v_mfma_f32_16x16x32_bf16 v[6:9], v[174:177], v[218:221], v[6:9]
	v_mfma_f32_16x16x32_bf16 v[2:5], v[182:185], v[218:221], v[2:5]
	s_setprio 0
	s_barrier
	s_add_i32 s67, 0, 0x18000
	s_add_i32 s68, 0, 0x1c000
	v_add_u32_e32 v166, s67, v152
	v_add_u32_e32 v182, s68, v152
	ds_read_b128 v[146:149], v166
	ds_read_b128 v[158:161], v166 offset:1024
	ds_read_b128 v[162:165], v166 offset:2048
	ds_read_b128 v[166:169], v166 offset:3072
	ds_read_b128 v[170:173], v182
	ds_read_b128 v[174:177], v182 offset:1024
	ds_read_b128 v[178:181], v182 offset:2048
	ds_read_b128 v[182:185], v182 offset:3072
	s_add_u32 s36, s36, 0x100000
	s_addc_u32 s37, s37, 0
	s_mov_b32 m0, s43
	v_lshl_add_u64 v[226:227], s[36:37], 0, v[130:131]
	ds_read_b128 v[186:189], v156 offset:32768
	ds_read_b128 v[190:193], v156 offset:33792
	ds_read_b128 v[194:197], v156 offset:34816
	ds_read_b128 v[198:201], v156 offset:35840
	ds_read_b128 v[202:205], v156 offset:36864
	ds_read_b128 v[210:213], v156 offset:37888
	ds_read_b128 v[214:217], v156 offset:38912
	ds_read_b128 v[218:221], v156 offset:39936
	global_load_lds_dwordx4 v[226:227], off
	v_lshl_add_u64 v[226:227], s[36:37], 0, v[134:135]
	s_mov_b32 m0, s44
	s_nop 0
	global_load_lds_dwordx4 v[226:227], off
	s_waitcnt vmcnt(8)
	s_waitcnt lgkmcnt(0)
	s_barrier
	s_setprio 1
	s_waitcnt lgkmcnt(0)
	v_mfma_f32_16x16x32_bf16 v[126:129], v[146:149], v[186:189], v[126:129]
	v_mfma_f32_16x16x32_bf16 v[122:125], v[162:165], v[186:189], v[122:125]
	v_mfma_f32_16x16x32_bf16 v[110:113], v[146:149], v[194:197], v[110:113]
	v_mfma_f32_16x16x32_bf16 v[106:109], v[162:165], v[194:197], v[106:109]
	v_mfma_f32_16x16x32_bf16 v[94:97], v[146:149], v[202:205], v[94:97]
	v_mfma_f32_16x16x32_bf16 v[90:93], v[162:165], v[202:205], v[90:93]
	v_mfma_f32_16x16x32_bf16 v[78:81], v[146:149], v[214:217], v[78:81]
	v_mfma_f32_16x16x32_bf16 v[74:77], v[162:165], v[214:217], v[74:77]
	v_mfma_f32_16x16x32_bf16 v[126:129], v[158:161], v[190:193], v[126:129]
	v_mfma_f32_16x16x32_bf16 v[122:125], v[166:169], v[190:193], v[122:125]
	v_mfma_f32_16x16x32_bf16 v[110:113], v[158:161], v[198:201], v[110:113]
	v_mfma_f32_16x16x32_bf16 v[106:109], v[166:169], v[198:201], v[106:109]
	v_mfma_f32_16x16x32_bf16 v[94:97], v[158:161], v[210:213], v[94:97]
	v_mfma_f32_16x16x32_bf16 v[90:93], v[166:169], v[210:213], v[90:93]
	v_mfma_f32_16x16x32_bf16 v[78:81], v[158:161], v[218:221], v[78:81]
	v_mfma_f32_16x16x32_bf16 v[74:77], v[166:169], v[218:221], v[74:77]
	s_setprio 0
	s_setprio 1
	v_mfma_f32_16x16x32_bf16 v[118:121], v[170:173], v[186:189], v[118:121]
	v_mfma_f32_16x16x32_bf16 v[114:117], v[178:181], v[186:189], v[114:117]
	v_mfma_f32_16x16x32_bf16 v[102:105], v[170:173], v[194:197], v[102:105]
	v_mfma_f32_16x16x32_bf16 v[98:101], v[178:181], v[194:197], v[98:101]
	v_mfma_f32_16x16x32_bf16 v[86:89], v[170:173], v[202:205], v[86:89]
	v_mfma_f32_16x16x32_bf16 v[82:85], v[178:181], v[202:205], v[82:85]
	v_mfma_f32_16x16x32_bf16 v[70:73], v[170:173], v[214:217], v[70:73]
	v_mfma_f32_16x16x32_bf16 v[66:69], v[178:181], v[214:217], v[66:69]
	v_mfma_f32_16x16x32_bf16 v[118:121], v[174:177], v[190:193], v[118:121]
	v_mfma_f32_16x16x32_bf16 v[114:117], v[182:185], v[190:193], v[114:117]
	v_mfma_f32_16x16x32_bf16 v[102:105], v[174:177], v[198:201], v[102:105]
	v_mfma_f32_16x16x32_bf16 v[98:101], v[182:185], v[198:201], v[98:101]
	v_mfma_f32_16x16x32_bf16 v[86:89], v[174:177], v[210:213], v[86:89]
	v_mfma_f32_16x16x32_bf16 v[82:85], v[182:185], v[210:213], v[82:85]
	v_mfma_f32_16x16x32_bf16 v[70:73], v[174:177], v[218:221], v[70:73]
	v_mfma_f32_16x16x32_bf16 v[66:69], v[182:185], v[218:221], v[66:69]
	s_setprio 0
	s_barrier
; #define PG8_STAGE(bufoff, gbase, voff) do { _Pragma("unroll") for (int _i = 0; _i < 2; ++_i) \
;         __builtin_amdgcn_global_load_lds((const unsigned*)((const char*)(gbase) + (voff)[_i]), (PG8_LAS unsigned*)(lds + (bufoff) + ldsw + _i * 8192), 16, 0, 0); } while (0)
; #define PG8_LDA(dst, b, h) do { _Pragma("unroll") for (int m = 0; m < 4; ++m) _Pragma("unroll") for (int k = 0; k < 2; ++k) dst[m][k] = *(const PG8_LAS bf16x8*)(lds + PG8_SA(b, h) + aoff + m * 2048 + k * 1024); } while (0)
; #define PG8_MMA(ai, bj, At, Bt) do { __builtin_amdgcn_s_setprio(1); _Pragma("unroll") for (int m = 0; m < 4; ++m) _Pragma("unroll") for (int n = 0; n < 2; ++n) _Pragma("unroll") for (int k = 0; k < 2; ++k) \
;         acc[ai][bj][m][n] = __builtin_amdgcn_mfma_f32_16x16x32_bf16(Bt[n][k], At[m][k], acc[ai][bj][m][n], 0, 0, 0); __builtin_amdgcn_s_setprio(0); } while (0)
; #define PG8_WAIT_V(n) asm volatile("s_waitcnt vmcnt(" #n ")" ::: "memory")
; #define PG8_WAIT_L(n) asm volatile("s_waitcnt lgkmcnt(" #n ")" ::: "memory")
; #define PG8_BAR __builtin_amdgcn_s_barrier()
; #define PG8_SCHED __builtin_amdgcn_sched_barrier(0)
; template <class Epi, class Sched>
; __device__ __forceinline__ void gemm_phase(PG8_LAS unsigned char* lds, const Gemm g, const Sched& S, const Epi& E) {
;     ...
;         for (int t = 0; t < nt; t += 2) {
;     ...
;             PG8_LDA(At, 1, 1); PG8_STAGE(PG8_SB(1, 0), b3, voffB); PG8_STAGE(PG8_SB(1, 1), b3 + hstepB, voffB); PG8_STAGE(PG8_SA(1, 0), a3, voffA);
;             PG8_WAIT_V(8); PG8_WAIT_L(0); PG8_BAR; PG8_MMA(1, 0, At, B0); PG8_MMA(1, 1, At, B1); PG8_BAR; PG8_SCHED;
;         }
;         if (wr == 0) PG8_BAR;
	s_add_i32 s36, s67, s41
	v_lshl_add_u64 v[150:151], v[150:151], 0, s[14:15]
	s_mov_b32 m0, s36
	ds_read_b128 v[186:189], v156 offset:49152
	ds_read_b128 v[190:193], v156 offset:50176
	ds_read_b128 v[194:197], v156 offset:51200
	ds_read_b128 v[198:201], v156 offset:52224
	ds_read_b128 v[202:205], v156 offset:53248
	ds_read_b128 v[210:213], v156 offset:54272
	ds_read_b128 v[214:217], v156 offset:55296
	ds_read_b128 v[218:221], v156 offset:56320
	global_load_lds_dwordx4 v[150:151], off
	s_add_i32 m0, s36, 0x2000
	s_add_u32 s34, s34, 0x100080
	v_lshl_add_u64 v[150:151], v[206:207], 0, s[14:15]
	s_addc_u32 s35, s35, 0
	s_add_i32 s36, s68, s41
	global_load_lds_dwordx4 v[150:151], off
	v_lshl_add_u64 v[150:151], s[34:35], 0, v[132:133]
	s_mov_b32 m0, s36
	s_nop 0
	global_load_lds_dwordx4 v[150:151], off
	v_lshl_add_u64 v[150:151], s[34:35], 0, v[136:137]
	s_add_i32 m0, s36, 0x2000
	s_nop 0
	global_load_lds_dwordx4 v[150:151], off
	v_lshl_add_u64 v[150:151], v[222:223], 0, s[14:15]
	s_mov_b32 m0, s47
	s_nop 0
	global_load_lds_dwordx4 v[150:151], off
	v_lshl_add_u64 v[150:151], v[224:225], 0, s[14:15]
	s_mov_b32 m0, s48
	s_nop 0
	global_load_lds_dwordx4 v[150:151], off
	s_waitcnt vmcnt(8)
	s_waitcnt lgkmcnt(0)
	s_barrier
	s_setprio 1
	s_waitcnt lgkmcnt(0)
	v_mfma_f32_16x16x32_bf16 v[62:65], v[146:149], v[186:189], v[62:65]
	v_mfma_f32_16x16x32_bf16 v[58:61], v[162:165], v[186:189], v[58:61]
	v_mfma_f32_16x16x32_bf16 v[46:49], v[146:149], v[194:197], v[46:49]
	v_mfma_f32_16x16x32_bf16 v[42:45], v[162:165], v[194:197], v[42:45]
	v_mfma_f32_16x16x32_bf16 v[30:33], v[146:149], v[202:205], v[30:33]
	v_mfma_f32_16x16x32_bf16 v[26:29], v[162:165], v[202:205], v[26:29]
	v_mfma_f32_16x16x32_bf16 v[14:17], v[146:149], v[214:217], v[14:17]
	v_mfma_f32_16x16x32_bf16 v[10:13], v[162:165], v[214:217], v[10:13]
	v_mfma_f32_16x16x32_bf16 v[62:65], v[158:161], v[190:193], v[62:65]
	v_mfma_f32_16x16x32_bf16 v[58:61], v[166:169], v[190:193], v[58:61]
	v_mfma_f32_16x16x32_bf16 v[46:49], v[158:161], v[198:201], v[46:49]
	v_mfma_f32_16x16x32_bf16 v[42:45], v[166:169], v[198:201], v[42:45]
	v_mfma_f32_16x16x32_bf16 v[30:33], v[158:161], v[210:213], v[30:33]
	v_mfma_f32_16x16x32_bf16 v[26:29], v[166:169], v[210:213], v[26:29]
	v_mfma_f32_16x16x32_bf16 v[14:17], v[158:161], v[218:221], v[14:17]
	v_mfma_f32_16x16x32_bf16 v[10:13], v[166:169], v[218:221], v[10:13]
	s_setprio 0
	s_setprio 1
	v_mfma_f32_16x16x32_bf16 v[54:57], v[170:173], v[186:189], v[54:57]
	v_mfma_f32_16x16x32_bf16 v[50:53], v[178:181], v[186:189], v[50:53]
	v_mfma_f32_16x16x32_bf16 v[38:41], v[170:173], v[194:197], v[38:41]
	v_mfma_f32_16x16x32_bf16 v[34:37], v[178:181], v[194:197], v[34:37]
	v_mfma_f32_16x16x32_bf16 v[22:25], v[170:173], v[202:205], v[22:25]
	v_mfma_f32_16x16x32_bf16 v[18:21], v[178:181], v[202:205], v[18:21]
	v_mfma_f32_16x16x32_bf16 v[6:9], v[170:173], v[214:217], v[6:9]
	v_mfma_f32_16x16x32_bf16 v[2:5], v[178:181], v[214:217], v[2:5]
	v_mfma_f32_16x16x32_bf16 v[54:57], v[174:177], v[190:193], v[54:57]
	v_mfma_f32_16x16x32_bf16 v[50:53], v[182:185], v[190:193], v[50:53]
	v_mfma_f32_16x16x32_bf16 v[38:41], v[174:177], v[198:201], v[38:41]
	v_mfma_f32_16x16x32_bf16 v[34:37], v[182:185], v[198:201], v[34:37]
	v_mfma_f32_16x16x32_bf16 v[22:25], v[174:177], v[210:213], v[22:25]
	v_mfma_f32_16x16x32_bf16 v[18:21], v[182:185], v[210:213], v[18:21]
	v_mfma_f32_16x16x32_bf16 v[6:9], v[174:177], v[218:221], v[6:9]
	v_mfma_f32_16x16x32_bf16 v[2:5], v[182:185], v[218:221], v[2:5]
	s_setprio 0
	s_add_i32 s66, s66, 2
	s_add_u32 s30, s30, 0x100
	s_addc_u32 s31, s31, 0
	s_add_u32 s64, s64, 0x100
	s_addc_u32 s65, s65, 0
	s_cmp_gt_u32 s66, 61
	s_barrier
	s_cbranch_scc0 .LBB0_591
	s_and_b64 vcc, exec, s[16:17]
	s_cbranch_vccz .LBB0_594
	s_barrier

; #define PG8_STAGE(bufoff, gbase, voff) do { _Pragma("unroll") for (int _i = 0; _i < 2; ++_i) \
;         __builtin_amdgcn_global_load_lds((const unsigned*)((const char*)(gbase) + (voff)[_i]), (PG8_LAS unsigned*)(lds + (bufoff) + ldsw + _i * 8192), 16, 0, 0); } while (0)
; #define PG8_LDA(dst, b, h) do { _Pragma("unroll") for (int m = 0; m < 4; ++m) _Pragma("unroll") for (int k = 0; k < 2; ++k) dst[m][k] = *(const PG8_LAS bf16x8*)(lds + PG8_SA(b, h) + aoff + m * 2048 + k * 1024); } while (0)
; #define PG8_LDB(dst, b, h) do { _Pragma("unroll") for (int n = 0; n < 2; ++n) _Pragma("unroll") for (int k = 0; k < 2; ++k) dst[n][k] = *(const PG8_LAS bf16x8*)(lds + PG8_SB(b, h) + boff + n * 2048 + k * 1024); } while (0)
; #define PG8_MMA(ai, bj, At, Bt) do { __builtin_amdgcn_s_setprio(1); _Pragma("unroll") for (int m = 0; m < 4; ++m) _Pragma("unroll") for (int n = 0; n < 2; ++n) _Pragma("unroll") for (int k = 0; k < 2; ++k) \
;         acc[ai][bj][m][n] = __builtin_amdgcn_mfma_f32_16x16x32_bf16(Bt[n][k], At[m][k], acc[ai][bj][m][n], 0, 0, 0); __builtin_amdgcn_s_setprio(0); } while (0)
; #define PG8_WAIT_V(n) asm volatile("s_waitcnt vmcnt(" #n ")" ::: "memory")
; #define PG8_WAIT_L(n) asm volatile("s_waitcnt lgkmcnt(" #n ")" ::: "memory")
; #define PG8_BAR __builtin_amdgcn_s_barrier()
; #define PG8_SCHED __builtin_amdgcn_sched_barrier(0)
; template <class Epi, class Sched>
; __device__ __forceinline__ void gemm_phase(PG8_LAS unsigned char* lds, const Gemm g, const Sched& S, const Epi& E) {
;     ...
;         for (int t = 0; t < nt; t += 2) {
;             const bool last = (t == nt - 2);
;             const char* a1 = cA + (size_t)(t + 1) * kstep;
;             const char* a2 = last ? nA : cA + (size_t)(t + 2) * kstep; const char* b2 = last ? nB : cB + (size_t)(t + 2) * kstep;
;             const char* a3 = a2 + kstep; const char* b3 = b2 + kstep;
;             PG8_LDB(B0, 0, 0); PG8_LDB(B1, 0, 1); PG8_SCHED; PG8_LDA(At, 0, 0); PG8_STAGE(PG8_SA(1, 1), a1 + hstepA, voffA);
;             PG8_WAIT_V(8); PG8_WAIT_L(0); PG8_BAR; PG8_MMA(0, 0, At, B0); PG8_MMA(0, 1, At, B1); PG8_BAR; PG8_SCHED;
;             PG8_LDA(At, 0, 1); PG8_STAGE(PG8_SB(0, 0), b2, voffB); PG8_STAGE(PG8_SB(0, 1), b2 + hstepB, voffB); PG8_STAGE(PG8_SA(0, 0), a2, voffA);
;             PG8_WAIT_V(8); PG8_WAIT_L(0); PG8_BAR; PG8_MMA(1, 0, At, B0); PG8_MMA(1, 1, At, B1); PG8_BAR; PG8_SCHED;
.LBB0_690:
	ds_read_b128 v[70:73], v211
	ds_read_b128 v[86:89], v211 offset:1024
	ds_read_b128 v[90:93], v211 offset:2048
	ds_read_b128 v[94:97], v211 offset:3072
	ds_read_b128 v[98:101], v212
	ds_read_b128 v[102:105], v212 offset:1024
	ds_read_b128 v[106:109], v212 offset:2048
	ds_read_b128 v[110:113], v212 offset:3072
	s_add_u32 s50, s10, 0xfff00080
	s_addc_u32 s51, s11, -1
	s_cmp_eq_u32 s1, 60
	s_cselect_b32 s53, s39, s51
	s_cselect_b32 s52, s97, s50
	s_cselect_b32 s51, s37, s0
	s_cselect_b32 s50, vcc_lo, vcc_hi
	v_lshl_add_u64 v[228:229], s[10:11], 0, v[182:183]
	s_add_i32 m0, s89, 0xc000
	ds_read_b128 v[162:165], v213
	ds_read_b128 v[166:169], v213 offset:1024
	ds_read_b128 v[192:195], v213 offset:2048
	ds_read_b128 v[198:201], v213 offset:3072
	ds_read_b128 v[202:205], v213 offset:4096
	ds_read_b128 v[216:219], v213 offset:5120
	ds_read_b128 v[220:223], v213 offset:6144
	ds_read_b128 v[224:227], v213 offset:7168
	global_load_lds_dwordx4 v[228:229], off
	v_lshl_add_u64 v[228:229], s[10:11], 0, v[184:185]
	s_add_i32 m0, s89, 0xe000
	s_nop 0
	global_load_lds_dwordx4 v[228:229], off
	s_waitcnt vmcnt(8)
	s_waitcnt lgkmcnt(0)
	s_barrier
	s_setprio 1
	s_waitcnt lgkmcnt(0)
	v_mfma_f32_16x16x32_bf16 v[154:157], v[70:73], v[162:165], v[154:157]
	v_mfma_f32_16x16x32_bf16 v[146:149], v[90:93], v[162:165], v[146:149]
	v_mfma_f32_16x16x32_bf16 v[142:145], v[70:73], v[192:195], v[142:145]
	v_mfma_f32_16x16x32_bf16 v[130:133], v[90:93], v[192:195], v[130:133]
	v_mfma_f32_16x16x32_bf16 v[126:129], v[70:73], v[202:205], v[126:129]
	v_mfma_f32_16x16x32_bf16 v[114:117], v[90:93], v[202:205], v[114:117]
	v_mfma_f32_16x16x32_bf16 v[82:85], v[70:73], v[220:223], v[82:85]
	v_mfma_f32_16x16x32_bf16 v[66:69], v[90:93], v[220:223], v[66:69]
	v_mfma_f32_16x16x32_bf16 v[154:157], v[86:89], v[166:169], v[154:157]
	v_mfma_f32_16x16x32_bf16 v[146:149], v[94:97], v[166:169], v[146:149]
	v_mfma_f32_16x16x32_bf16 v[142:145], v[86:89], v[198:201], v[142:145]
	v_mfma_f32_16x16x32_bf16 v[130:133], v[94:97], v[198:201], v[130:133]
	v_mfma_f32_16x16x32_bf16 v[126:129], v[86:89], v[216:219], v[126:129]
	v_mfma_f32_16x16x32_bf16 v[114:117], v[94:97], v[216:219], v[114:117]
	v_mfma_f32_16x16x32_bf16 v[82:85], v[86:89], v[224:227], v[82:85]
	v_mfma_f32_16x16x32_bf16 v[66:69], v[94:97], v[224:227], v[66:69]
	s_setprio 0
	s_setprio 1
	v_mfma_f32_16x16x32_bf16 v[158:161], v[98:101], v[162:165], v[158:161]
	v_mfma_f32_16x16x32_bf16 v[150:153], v[106:109], v[162:165], v[150:153]
	v_mfma_f32_16x16x32_bf16 v[138:141], v[98:101], v[192:195], v[138:141]
	v_mfma_f32_16x16x32_bf16 v[134:137], v[106:109], v[192:195], v[134:137]
	v_mfma_f32_16x16x32_bf16 v[122:125], v[98:101], v[202:205], v[122:125]
	v_mfma_f32_16x16x32_bf16 v[118:121], v[106:109], v[202:205], v[118:121]
	v_mfma_f32_16x16x32_bf16 v[78:81], v[98:101], v[220:223], v[78:81]
	v_mfma_f32_16x16x32_bf16 v[74:77], v[106:109], v[220:223], v[74:77]
	v_mfma_f32_16x16x32_bf16 v[158:161], v[102:105], v[166:169], v[158:161]
	v_mfma_f32_16x16x32_bf16 v[150:153], v[110:113], v[166:169], v[150:153]
	v_mfma_f32_16x16x32_bf16 v[138:141], v[102:105], v[198:201], v[138:141]
	v_mfma_f32_16x16x32_bf16 v[134:137], v[110:113], v[198:201], v[134:137]
	v_mfma_f32_16x16x32_bf16 v[122:125], v[102:105], v[216:219], v[122:125]
	v_mfma_f32_16x16x32_bf16 v[118:121], v[110:113], v[216:219], v[118:121]
	v_mfma_f32_16x16x32_bf16 v[78:81], v[102:105], v[224:227], v[78:81]
	v_mfma_f32_16x16x32_bf16 v[74:77], v[110:113], v[224:227], v[74:77]
	s_setprio 0
	s_barrier
	s_add_i32 s68, s94, s66
	v_lshl_add_u64 v[228:229], s[50:51], 0, v[174:175]
	s_mov_b32 m0, s68
	ds_read_b128 v[162:165], v213 offset:16384
	ds_read_b128 v[166:169], v213 offset:17408
	ds_read_b128 v[192:195], v213 offset:18432
	ds_read_b128 v[198:201], v213 offset:19456
	ds_read_b128 v[202:205], v213 offset:20480
	ds_read_b128 v[216:219], v213 offset:21504
	ds_read_b128 v[220:223], v213 offset:22528
	ds_read_b128 v[224:227], v213 offset:23552
	global_load_lds_dwordx4 v[228:229], off
	s_add_i32 m0, s68, 0x2000
	s_add_u32 s68, s50, 0x100000
	v_lshl_add_u64 v[230:231], s[50:51], 0, v[170:171]
	s_addc_u32 s69, s51, 0
	s_add_i32 s70, s95, s66
	global_load_lds_dwordx4 v[230:231], off
	v_lshl_add_u64 v[232:233], s[68:69], 0, v[174:175]
	s_mov_b32 m0, s70
	v_lshl_add_u64 v[234:235], s[52:53], 0, v[172:173]
	global_load_lds_dwordx4 v[232:233], off
	v_lshl_add_u64 v[232:233], s[68:69], 0, v[170:171]
	s_add_i32 m0, s70, 0x2000
	s_nop 0
	global_load_lds_dwordx4 v[232:233], off
	v_lshl_add_u64 v[232:233], s[52:53], 0, v[176:177]
	s_mov_b32 m0, s89
	s_nop 0
	global_load_lds_dwordx4 v[232:233], off
	s_mov_b32 m0, s33
	s_nop 0
	global_load_lds_dwordx4 v[234:235], off
	s_waitcnt vmcnt(8)
	s_waitcnt lgkmcnt(0)
	s_barrier
; #define PG8_STAGE(bufoff, gbase, voff) do { _Pragma("unroll") for (int _i = 0; _i < 2; ++_i) \
;         __builtin_amdgcn_global_load_lds((const unsigned*)((const char*)(gbase) + (voff)[_i]), (PG8_LAS unsigned*)(lds + (bufoff) + ldsw + _i * 8192), 16, 0, 0); } while (0)
; #define PG8_LDA(dst, b, h) do { _Pragma("unroll") for (int m = 0; m < 4; ++m) _Pragma("unroll") for (int k = 0; k < 2; ++k) dst[m][k] = *(const PG8_LAS bf16x8*)(lds + PG8_SA(b, h) + aoff + m * 2048 + k * 1024); } while (0)
; #define PG8_LDB(dst, b, h) do { _Pragma("unroll") for (int n = 0; n < 2; ++n) _Pragma("unroll") for (int k = 0; k < 2; ++k) dst[n][k] = *(const PG8_LAS bf16x8*)(lds + PG8_SB(b, h) + boff + n * 2048 + k * 1024); } while (0)
; #define PG8_MMA(ai, bj, At, Bt) do { __builtin_amdgcn_s_setprio(1); _Pragma("unroll") for (int m = 0; m < 4; ++m) _Pragma("unroll") for (int n = 0; n < 2; ++n) _Pragma("unroll") for (int k = 0; k < 2; ++k) \
;         acc[ai][bj][m][n] = __builtin_amdgcn_mfma_f32_16x16x32_bf16(Bt[n][k], At[m][k], acc[ai][bj][m][n], 0, 0, 0); __builtin_amdgcn_s_setprio(0); } while (0)
; #define PG8_WAIT_V(n) asm volatile("s_waitcnt vmcnt(" #n ")" ::: "memory")
; #define PG8_WAIT_L(n) asm volatile("s_waitcnt lgkmcnt(" #n ")" ::: "memory")
; #define PG8_BAR __builtin_amdgcn_s_barrier()
; #define PG8_SCHED __builtin_amdgcn_sched_barrier(0)
; template <class Epi, class Sched>
; __device__ __forceinline__ void gemm_phase(PG8_LAS unsigned char* lds, const Gemm g, const Sched& S, const Epi& E) {
;     ...
;             PG8_WAIT_V(8); PG8_WAIT_L(0); PG8_BAR; PG8_MMA(1, 0, At, B0); PG8_MMA(1, 1, At, B1); PG8_BAR; PG8_SCHED;
;             PG8_LDB(B0, 1, 0); PG8_LDB(B1, 1, 1); PG8_SCHED; PG8_LDA(At, 1, 0); PG8_STAGE(PG8_SA(0, 1), a2 + hstepA, voffA);
;             PG8_WAIT_V(8); PG8_WAIT_L(0); PG8_BAR; PG8_MMA(0, 0, At, B0); PG8_MMA(0, 1, At, B1); PG8_BAR; PG8_SCHED;
	s_setprio 1
	s_waitcnt lgkmcnt(0)
	v_mfma_f32_16x16x32_bf16 v[62:65], v[70:73], v[162:165], v[62:65]
	v_mfma_f32_16x16x32_bf16 v[50:53], v[90:93], v[162:165], v[50:53]
	v_mfma_f32_16x16x32_bf16 v[46:49], v[70:73], v[192:195], v[46:49]
	v_mfma_f32_16x16x32_bf16 v[34:37], v[90:93], v[192:195], v[34:37]
	v_mfma_f32_16x16x32_bf16 v[30:33], v[70:73], v[202:205], v[30:33]
	v_mfma_f32_16x16x32_bf16 v[18:21], v[90:93], v[202:205], v[18:21]
	v_mfma_f32_16x16x32_bf16 v[14:17], v[70:73], v[220:223], v[14:17]
	v_mfma_f32_16x16x32_bf16 v[2:5], v[90:93], v[220:223], v[2:5]
	v_mfma_f32_16x16x32_bf16 v[62:65], v[86:89], v[166:169], v[62:65]
	v_mfma_f32_16x16x32_bf16 v[50:53], v[94:97], v[166:169], v[50:53]
	v_mfma_f32_16x16x32_bf16 v[46:49], v[86:89], v[198:201], v[46:49]
	v_mfma_f32_16x16x32_bf16 v[34:37], v[94:97], v[198:201], v[34:37]
	v_mfma_f32_16x16x32_bf16 v[30:33], v[86:89], v[216:219], v[30:33]
	v_mfma_f32_16x16x32_bf16 v[18:21], v[94:97], v[216:219], v[18:21]
	v_mfma_f32_16x16x32_bf16 v[14:17], v[86:89], v[224:227], v[14:17]
	v_mfma_f32_16x16x32_bf16 v[2:5], v[94:97], v[224:227], v[2:5]
	s_setprio 0
	s_setprio 1
	v_mfma_f32_16x16x32_bf16 v[58:61], v[98:101], v[162:165], v[58:61]
	v_mfma_f32_16x16x32_bf16 v[54:57], v[106:109], v[162:165], v[54:57]
	v_mfma_f32_16x16x32_bf16 v[42:45], v[98:101], v[192:195], v[42:45]
	v_mfma_f32_16x16x32_bf16 v[38:41], v[106:109], v[192:195], v[38:41]
	v_mfma_f32_16x16x32_bf16 v[26:29], v[98:101], v[202:205], v[26:29]
	v_mfma_f32_16x16x32_bf16 v[22:25], v[106:109], v[202:205], v[22:25]
	v_mfma_f32_16x16x32_bf16 v[10:13], v[98:101], v[220:223], v[10:13]
	v_mfma_f32_16x16x32_bf16 v[6:9], v[106:109], v[220:223], v[6:9]
	v_mfma_f32_16x16x32_bf16 v[58:61], v[102:105], v[166:169], v[58:61]
	v_mfma_f32_16x16x32_bf16 v[54:57], v[110:113], v[166:169], v[54:57]
	v_mfma_f32_16x16x32_bf16 v[42:45], v[102:105], v[198:201], v[42:45]
	v_mfma_f32_16x16x32_bf16 v[38:41], v[110:113], v[198:201], v[38:41]
	v_mfma_f32_16x16x32_bf16 v[26:29], v[102:105], v[216:219], v[26:29]
	v_mfma_f32_16x16x32_bf16 v[22:25], v[110:113], v[216:219], v[22:25]
	v_mfma_f32_16x16x32_bf16 v[10:13], v[102:105], v[224:227], v[10:13]
	v_mfma_f32_16x16x32_bf16 v[6:9], v[110:113], v[224:227], v[6:9]
	s_setprio 0
	s_barrier
	s_add_i32 s68, 0, 0x18000
	s_add_i32 s69, 0, 0x1c000
	v_add_u32_e32 v94, s68, v191
	v_add_u32_e32 v110, s69, v191
	ds_read_b128 v[70:73], v94
	ds_read_b128 v[86:89], v94 offset:1024
	ds_read_b128 v[90:93], v94 offset:2048
	ds_read_b128 v[94:97], v94 offset:3072
	ds_read_b128 v[98:101], v110
	ds_read_b128 v[102:105], v110 offset:1024
	ds_read_b128 v[106:109], v110 offset:2048
	ds_read_b128 v[110:113], v110 offset:3072
	s_add_u32 s52, s52, 0x100000
	s_addc_u32 s53, s53, 0
	s_mov_b32 m0, s44
	v_lshl_add_u64 v[236:237], s[52:53], 0, v[176:177]
	ds_read_b128 v[162:165], v213 offset:32768
	ds_read_b128 v[166:169], v213 offset:33792
	ds_read_b128 v[192:195], v213 offset:34816
	ds_read_b128 v[198:201], v213 offset:35840
	ds_read_b128 v[202:205], v213 offset:36864
	ds_read_b128 v[216:219], v213 offset:37888
	ds_read_b128 v[220:223], v213 offset:38912
	ds_read_b128 v[224:227], v213 offset:39936
	global_load_lds_dwordx4 v[236:237], off
	v_lshl_add_u64 v[236:237], s[52:53], 0, v[172:173]
	s_mov_b32 m0, s45
	s_nop 0
	global_load_lds_dwordx4 v[236:237], off
	s_waitcnt vmcnt(8)
	s_waitcnt lgkmcnt(0)
	s_barrier
	s_setprio 1
	s_waitcnt lgkmcnt(0)
	v_mfma_f32_16x16x32_bf16 v[154:157], v[70:73], v[162:165], v[154:157]
	v_mfma_f32_16x16x32_bf16 v[146:149], v[90:93], v[162:165], v[146:149]
	v_mfma_f32_16x16x32_bf16 v[142:145], v[70:73], v[192:195], v[142:145]
	v_mfma_f32_16x16x32_bf16 v[130:133], v[90:93], v[192:195], v[130:133]
	v_mfma_f32_16x16x32_bf16 v[126:129], v[70:73], v[202:205], v[126:129]
	v_mfma_f32_16x16x32_bf16 v[114:117], v[90:93], v[202:205], v[114:117]
	v_mfma_f32_16x16x32_bf16 v[82:85], v[70:73], v[220:223], v[82:85]
	v_mfma_f32_16x16x32_bf16 v[66:69], v[90:93], v[220:223], v[66:69]
	v_mfma_f32_16x16x32_bf16 v[154:157], v[86:89], v[166:169], v[154:157]
	v_mfma_f32_16x16x32_bf16 v[146:149], v[94:97], v[166:169], v[146:149]
	v_mfma_f32_16x16x32_bf16 v[142:145], v[86:89], v[198:201], v[142:145]
	v_mfma_f32_16x16x32_bf16 v[130:133], v[94:97], v[198:201], v[130:133]
	v_mfma_f32_16x16x32_bf16 v[126:129], v[86:89], v[216:219], v[126:129]
	v_mfma_f32_16x16x32_bf16 v[114:117], v[94:97], v[216:219], v[114:117]
	v_mfma_f32_16x16x32_bf16 v[82:85], v[86:89], v[224:227], v[82:85]
	v_mfma_f32_16x16x32_bf16 v[66:69], v[94:97], v[224:227], v[66:69]
	s_setprio 0
	s_setprio 1
	v_mfma_f32_16x16x32_bf16 v[158:161], v[98:101], v[162:165], v[158:161]
	v_mfma_f32_16x16x32_bf16 v[150:153], v[106:109], v[162:165], v[150:153]
	v_mfma_f32_16x16x32_bf16 v[138:141], v[98:101], v[192:195], v[138:141]
	v_mfma_f32_16x16x32_bf16 v[134:137], v[106:109], v[192:195], v[134:137]
	v_mfma_f32_16x16x32_bf16 v[122:125], v[98:101], v[202:205], v[122:125]
	v_mfma_f32_16x16x32_bf16 v[118:121], v[106:109], v[202:205], v[118:121]
	v_mfma_f32_16x16x32_bf16 v[78:81], v[98:101], v[220:223], v[78:81]
	v_mfma_f32_16x16x32_bf16 v[74:77], v[106:109], v[220:223], v[74:77]
	v_mfma_f32_16x16x32_bf16 v[158:161], v[102:105], v[166:169], v[158:161]
	v_mfma_f32_16x16x32_bf16 v[150:153], v[110:113], v[166:169], v[150:153]
	v_mfma_f32_16x16x32_bf16 v[138:141], v[102:105], v[198:201], v[138:141]
	v_mfma_f32_16x16x32_bf16 v[134:137], v[110:113], v[198:201], v[134:137]
	v_mfma_f32_16x16x32_bf16 v[122:125], v[102:105], v[216:219], v[122:125]
	v_mfma_f32_16x16x32_bf16 v[118:121], v[110:113], v[216:219], v[118:121]
	v_mfma_f32_16x16x32_bf16 v[78:81], v[102:105], v[224:227], v[78:81]
	v_mfma_f32_16x16x32_bf16 v[74:77], v[110:113], v[224:227], v[74:77]
	s_setprio 0
	s_barrier
; #define PG8_STAGE(bufoff, gbase, voff) do { _Pragma("unroll") for (int _i = 0; _i < 2; ++_i) \
;         __builtin_amdgcn_global_load_lds((const unsigned*)((const char*)(gbase) + (voff)[_i]), (PG8_LAS unsigned*)(lds + (bufoff) + ldsw + _i * 8192), 16, 0, 0); } while (0)
; #define PG8_LDA(dst, b, h) do { _Pragma("unroll") for (int m = 0; m < 4; ++m) _Pragma("unroll") for (int k = 0; k < 2; ++k) dst[m][k] = *(const PG8_LAS bf16x8*)(lds + PG8_SA(b, h) + aoff + m * 2048 + k * 1024); } while (0)
; #define PG8_MMA(ai, bj, At, Bt) do { __builtin_amdgcn_s_setprio(1); _Pragma("unroll") for (int m = 0; m < 4; ++m) _Pragma("unroll") for (int n = 0; n < 2; ++n) _Pragma("unroll") for (int k = 0; k < 2; ++k) \
;         acc[ai][bj][m][n] = __builtin_amdgcn_mfma_f32_16x16x32_bf16(Bt[n][k], At[m][k], acc[ai][bj][m][n], 0, 0, 0); __builtin_amdgcn_s_setprio(0); } while (0)
; #define PG8_WAIT_V(n) asm volatile("s_waitcnt vmcnt(" #n ")" ::: "memory")
; #define PG8_WAIT_L(n) asm volatile("s_waitcnt lgkmcnt(" #n ")" ::: "memory")
; #define PG8_BAR __builtin_amdgcn_s_barrier()
; #define PG8_SCHED __builtin_amdgcn_sched_barrier(0)
; template <class Epi, class Sched>
; __device__ __forceinline__ void gemm_phase(PG8_LAS unsigned char* lds, const Gemm g, const Sched& S, const Epi& E) {
;     ...
;         for (int t = 0; t < nt; t += 2) {
;     ...
;             PG8_LDA(At, 1, 1); PG8_STAGE(PG8_SB(1, 0), b3, voffB); PG8_STAGE(PG8_SB(1, 1), b3 + hstepB, voffB); PG8_STAGE(PG8_SA(1, 0), a3, voffA);
;             PG8_WAIT_V(8); PG8_WAIT_L(0); PG8_BAR; PG8_MMA(1, 0, At, B0); PG8_MMA(1, 1, At, B1); PG8_BAR; PG8_SCHED;
;         }
;         if (wr == 0) PG8_BAR;
	s_add_i32 s52, s68, s66
	v_lshl_add_u64 v[228:229], v[228:229], 0, s[20:21]
	s_mov_b32 m0, s52
	ds_read_b128 v[162:165], v213 offset:49152
	ds_read_b128 v[166:169], v213 offset:50176
	ds_read_b128 v[192:195], v213 offset:51200
	ds_read_b128 v[198:201], v213 offset:52224
	ds_read_b128 v[202:205], v213 offset:53248
	ds_read_b128 v[216:219], v213 offset:54272
	ds_read_b128 v[220:223], v213 offset:55296
	ds_read_b128 v[224:227], v213 offset:56320
	global_load_lds_dwordx4 v[228:229], off
	s_add_i32 m0, s52, 0x2000
	s_add_u32 s50, s50, 0x100080
	v_lshl_add_u64 v[228:229], v[230:231], 0, s[20:21]
	s_addc_u32 s51, s51, 0
	s_add_i32 s52, s69, s66
	global_load_lds_dwordx4 v[228:229], off
	v_lshl_add_u64 v[228:229], s[50:51], 0, v[174:175]
	s_mov_b32 m0, s52
	s_nop 0
	global_load_lds_dwordx4 v[228:229], off
	v_lshl_add_u64 v[228:229], s[50:51], 0, v[170:171]
	s_add_i32 m0, s52, 0x2000
	s_nop 0
	global_load_lds_dwordx4 v[228:229], off
	v_lshl_add_u64 v[228:229], v[232:233], 0, s[20:21]
	s_mov_b32 m0, s91
	s_nop 0
	global_load_lds_dwordx4 v[228:229], off
	v_lshl_add_u64 v[228:229], v[234:235], 0, s[20:21]
	s_mov_b32 m0, s92
	s_nop 0
	global_load_lds_dwordx4 v[228:229], off
	s_waitcnt vmcnt(8)
	s_waitcnt lgkmcnt(0)
	s_barrier
	s_setprio 1
	s_waitcnt lgkmcnt(0)
	v_mfma_f32_16x16x32_bf16 v[62:65], v[70:73], v[162:165], v[62:65]
	v_mfma_f32_16x16x32_bf16 v[50:53], v[90:93], v[162:165], v[50:53]
	v_mfma_f32_16x16x32_bf16 v[46:49], v[70:73], v[192:195], v[46:49]
	v_mfma_f32_16x16x32_bf16 v[34:37], v[90:93], v[192:195], v[34:37]
	v_mfma_f32_16x16x32_bf16 v[30:33], v[70:73], v[202:205], v[30:33]
	v_mfma_f32_16x16x32_bf16 v[18:21], v[90:93], v[202:205], v[18:21]
	v_mfma_f32_16x16x32_bf16 v[14:17], v[70:73], v[220:223], v[14:17]
	v_mfma_f32_16x16x32_bf16 v[2:5], v[90:93], v[220:223], v[2:5]
	v_mfma_f32_16x16x32_bf16 v[62:65], v[86:89], v[166:169], v[62:65]
	v_mfma_f32_16x16x32_bf16 v[50:53], v[94:97], v[166:169], v[50:53]
	v_mfma_f32_16x16x32_bf16 v[46:49], v[86:89], v[198:201], v[46:49]
	v_mfma_f32_16x16x32_bf16 v[34:37], v[94:97], v[198:201], v[34:37]
	v_mfma_f32_16x16x32_bf16 v[30:33], v[86:89], v[216:219], v[30:33]
	v_mfma_f32_16x16x32_bf16 v[18:21], v[94:97], v[216:219], v[18:21]
	v_mfma_f32_16x16x32_bf16 v[14:17], v[86:89], v[224:227], v[14:17]
	v_mfma_f32_16x16x32_bf16 v[2:5], v[94:97], v[224:227], v[2:5]
	s_setprio 0
	s_setprio 1
	v_mfma_f32_16x16x32_bf16 v[58:61], v[98:101], v[162:165], v[58:61]
	v_mfma_f32_16x16x32_bf16 v[54:57], v[106:109], v[162:165], v[54:57]
	v_mfma_f32_16x16x32_bf16 v[42:45], v[98:101], v[192:195], v[42:45]
	v_mfma_f32_16x16x32_bf16 v[38:41], v[106:109], v[192:195], v[38:41]
	v_mfma_f32_16x16x32_bf16 v[26:29], v[98:101], v[202:205], v[26:29]
	v_mfma_f32_16x16x32_bf16 v[22:25], v[106:109], v[202:205], v[22:25]
	v_mfma_f32_16x16x32_bf16 v[10:13], v[98:101], v[220:223], v[10:13]
	v_mfma_f32_16x16x32_bf16 v[6:9], v[106:109], v[220:223], v[6:9]
	v_mfma_f32_16x16x32_bf16 v[58:61], v[102:105], v[166:169], v[58:61]
	v_mfma_f32_16x16x32_bf16 v[54:57], v[110:113], v[166:169], v[54:57]
	v_mfma_f32_16x16x32_bf16 v[42:45], v[102:105], v[198:201], v[42:45]
	v_mfma_f32_16x16x32_bf16 v[38:41], v[110:113], v[198:201], v[38:41]
	v_mfma_f32_16x16x32_bf16 v[26:29], v[102:105], v[216:219], v[26:29]
	v_mfma_f32_16x16x32_bf16 v[22:25], v[110:113], v[216:219], v[22:25]
	v_mfma_f32_16x16x32_bf16 v[10:13], v[102:105], v[224:227], v[10:13]
	v_mfma_f32_16x16x32_bf16 v[6:9], v[110:113], v[224:227], v[6:9]
	s_setprio 0
	s_add_i32 s1, s1, 2
	s_add_u32 s10, s10, 0x100
	s_addc_u32 s11, s11, 0
	s_add_u32 vcc_hi, vcc_hi, 0x100
	s_addc_u32 s0, s0, 0
	s_cmp_gt_u32 s1, 61
	s_barrier
	s_cbranch_scc0 .LBB0_690
	s_and_b64 vcc, exec, s[22:23]
	s_cbranch_vccz .LBB0_693
	s_barrier

; #define PG8_STAGE(bufoff, gbase, voff) do { _Pragma("unroll") for (int _i = 0; _i < 2; ++_i) \
;         __builtin_amdgcn_global_load_lds((const unsigned*)((const char*)(gbase) + (voff)[_i]), (PG8_LAS unsigned*)(lds + (bufoff) + ldsw + _i * 8192), 16, 0, 0); } while (0)
; #define PG8_LDA(dst, b, h) do { _Pragma("unroll") for (int m = 0; m < 4; ++m) _Pragma("unroll") for (int k = 0; k < 2; ++k) dst[m][k] = *(const PG8_LAS bf16x8*)(lds + PG8_SA(b, h) + aoff + m * 2048 + k * 1024); } while (0)
; #define PG8_LDB(dst, b, h) do { _Pragma("unroll") for (int n = 0; n < 2; ++n) _Pragma("unroll") for (int k = 0; k < 2; ++k) dst[n][k] = *(const PG8_LAS bf16x8*)(lds + PG8_SB(b, h) + boff + n * 2048 + k * 1024); } while (0)
; #define PG8_MMA(ai, bj, At, Bt) do { __builtin_amdgcn_s_setprio(1); _Pragma("unroll") for (int m = 0; m < 4; ++m) _Pragma("unroll") for (int n = 0; n < 2; ++n) _Pragma("unroll") for (int k = 0; k < 2; ++k) \
;         acc[ai][bj][m][n] = __builtin_amdgcn_mfma_f32_16x16x32_bf16(Bt[n][k], At[m][k], acc[ai][bj][m][n], 0, 0, 0); __builtin_amdgcn_s_setprio(0); } while (0)
; #define PG8_WAIT_V(n) asm volatile("s_waitcnt vmcnt(" #n ")" ::: "memory")
; #define PG8_WAIT_L(n) asm volatile("s_waitcnt lgkmcnt(" #n ")" ::: "memory")
; #define PG8_BAR __builtin_amdgcn_s_barrier()
; #define PG8_SCHED __builtin_amdgcn_sched_barrier(0)
; template <class Epi, class Sched>
; __device__ __forceinline__ void gemm_phase(PG8_LAS unsigned char* lds, const Gemm g, const Sched& S, const Epi& E) {
;     ...
;         for (int t = 0; t < nt; t += 2) {
;             const bool last = (t == nt - 2);
;             const char* a1 = cA + (size_t)(t + 1) * kstep;
;             const char* a2 = last ? nA : cA + (size_t)(t + 2) * kstep; const char* b2 = last ? nB : cB + (size_t)(t + 2) * kstep;
;             const char* a3 = a2 + kstep; const char* b3 = b2 + kstep;
;             PG8_LDB(B0, 0, 0); PG8_LDB(B1, 0, 1); PG8_SCHED; PG8_LDA(At, 0, 0); PG8_STAGE(PG8_SA(1, 1), a1 + hstepA, voffA);
;             PG8_WAIT_V(8); PG8_WAIT_L(0); PG8_BAR; PG8_MMA(0, 0, At, B0); PG8_MMA(0, 1, At, B1); PG8_BAR; PG8_SCHED;
;             PG8_LDA(At, 0, 1); PG8_STAGE(PG8_SB(0, 0), b2, voffB); PG8_STAGE(PG8_SB(0, 1), b2 + hstepB, voffB); PG8_STAGE(PG8_SA(0, 0), a2, voffA);
;             PG8_WAIT_V(8); PG8_WAIT_L(0); PG8_BAR; PG8_MMA(1, 0, At, B0); PG8_MMA(1, 1, At, B1); PG8_BAR; PG8_SCHED;
.LBB0_962:
	ds_read_b128 v[146:149], v154
	ds_read_b128 v[158:161], v154 offset:1024
	ds_read_b128 v[162:165], v154 offset:2048
	ds_read_b128 v[166:169], v154 offset:3072
	ds_read_b128 v[170:173], v155
	ds_read_b128 v[174:177], v155 offset:1024
	ds_read_b128 v[178:181], v155 offset:2048
	ds_read_b128 v[182:185], v155 offset:3072
	s_add_u32 s24, s22, 0xffd50080
	s_addc_u32 s25, s23, -1
	s_cmpk_eq_i32 s52, 0xa8
	s_cselect_b32 s27, s7, s25
	s_cselect_b32 s26, s6, s24
	s_cselect_b32 s25, s21, s51
	s_cselect_b32 s24, s20, s50
	v_lshl_add_u64 v[150:151], s[22:23], 0, v[138:139]
	s_add_i32 m0, s34, 0xc000
	ds_read_b128 v[186:189], v156
	ds_read_b128 v[190:193], v156 offset:1024
	ds_read_b128 v[194:197], v156 offset:2048
	ds_read_b128 v[198:201], v156 offset:3072
	ds_read_b128 v[202:205], v156 offset:4096
	ds_read_b128 v[210:213], v156 offset:5120
	ds_read_b128 v[214:217], v156 offset:6144
	ds_read_b128 v[218:221], v156 offset:7168
	global_load_lds_dwordx4 v[150:151], off
	v_lshl_add_u64 v[150:151], s[22:23], 0, v[140:141]
	s_add_i32 m0, s34, 0xe000
	s_nop 0
	global_load_lds_dwordx4 v[150:151], off
	s_waitcnt vmcnt(8)
	s_waitcnt lgkmcnt(0)
	s_barrier
	s_setprio 1
	s_waitcnt lgkmcnt(0)
	v_mfma_f32_16x16x32_bf16 v[126:129], v[146:149], v[186:189], v[126:129]
	v_mfma_f32_16x16x32_bf16 v[122:125], v[162:165], v[186:189], v[122:125]
	v_mfma_f32_16x16x32_bf16 v[110:113], v[146:149], v[194:197], v[110:113]
	v_mfma_f32_16x16x32_bf16 v[106:109], v[162:165], v[194:197], v[106:109]
	v_mfma_f32_16x16x32_bf16 v[94:97], v[146:149], v[202:205], v[94:97]
	v_mfma_f32_16x16x32_bf16 v[90:93], v[162:165], v[202:205], v[90:93]
	v_mfma_f32_16x16x32_bf16 v[78:81], v[146:149], v[214:217], v[78:81]
	v_mfma_f32_16x16x32_bf16 v[74:77], v[162:165], v[214:217], v[74:77]
	v_mfma_f32_16x16x32_bf16 v[126:129], v[158:161], v[190:193], v[126:129]
	v_mfma_f32_16x16x32_bf16 v[122:125], v[166:169], v[190:193], v[122:125]
	v_mfma_f32_16x16x32_bf16 v[110:113], v[158:161], v[198:201], v[110:113]
	v_mfma_f32_16x16x32_bf16 v[106:109], v[166:169], v[198:201], v[106:109]
	v_mfma_f32_16x16x32_bf16 v[94:97], v[158:161], v[210:213], v[94:97]
	v_mfma_f32_16x16x32_bf16 v[90:93], v[166:169], v[210:213], v[90:93]
	v_mfma_f32_16x16x32_bf16 v[78:81], v[158:161], v[218:221], v[78:81]
	v_mfma_f32_16x16x32_bf16 v[74:77], v[166:169], v[218:221], v[74:77]
	s_setprio 0
	s_setprio 1
	v_mfma_f32_16x16x32_bf16 v[118:121], v[170:173], v[186:189], v[118:121]
	v_mfma_f32_16x16x32_bf16 v[114:117], v[178:181], v[186:189], v[114:117]
	v_mfma_f32_16x16x32_bf16 v[102:105], v[170:173], v[194:197], v[102:105]
	v_mfma_f32_16x16x32_bf16 v[98:101], v[178:181], v[194:197], v[98:101]
	v_mfma_f32_16x16x32_bf16 v[86:89], v[170:173], v[202:205], v[86:89]
	v_mfma_f32_16x16x32_bf16 v[82:85], v[178:181], v[202:205], v[82:85]
	v_mfma_f32_16x16x32_bf16 v[70:73], v[170:173], v[214:217], v[70:73]
	v_mfma_f32_16x16x32_bf16 v[66:69], v[178:181], v[214:217], v[66:69]
	v_mfma_f32_16x16x32_bf16 v[118:121], v[174:177], v[190:193], v[118:121]
	v_mfma_f32_16x16x32_bf16 v[114:117], v[182:185], v[190:193], v[114:117]
	v_mfma_f32_16x16x32_bf16 v[102:105], v[174:177], v[198:201], v[102:105]
	v_mfma_f32_16x16x32_bf16 v[98:101], v[182:185], v[198:201], v[98:101]
	v_mfma_f32_16x16x32_bf16 v[86:89], v[174:177], v[210:213], v[86:89]
	v_mfma_f32_16x16x32_bf16 v[82:85], v[182:185], v[210:213], v[82:85]
	v_mfma_f32_16x16x32_bf16 v[70:73], v[174:177], v[218:221], v[70:73]
	v_mfma_f32_16x16x32_bf16 v[66:69], v[182:185], v[218:221], v[66:69]
	s_setprio 0
	s_barrier
	s_add_i32 s53, s43, s33
	v_lshl_add_u64 v[150:151], s[24:25], 0, v[132:133]
	s_mov_b32 m0, s53
	ds_read_b128 v[186:189], v156 offset:16384
	ds_read_b128 v[190:193], v156 offset:17408
	ds_read_b128 v[194:197], v156 offset:18432
	ds_read_b128 v[198:201], v156 offset:19456
	ds_read_b128 v[202:205], v156 offset:20480
	ds_read_b128 v[210:213], v156 offset:21504
	ds_read_b128 v[214:217], v156 offset:22528
	ds_read_b128 v[218:221], v156 offset:23552
	global_load_lds_dwordx4 v[150:151], off
	s_add_i32 m0, s53, 0x2000
	s_add_u32 s54, s24, 0x2b0000
	v_lshl_add_u64 v[206:207], s[24:25], 0, v[136:137]
	s_addc_u32 s55, s25, 0
	s_add_i32 s53, s44, s33
	global_load_lds_dwordx4 v[206:207], off
	v_lshl_add_u64 v[222:223], s[54:55], 0, v[132:133]
	s_mov_b32 m0, s53
	v_lshl_add_u64 v[224:225], s[26:27], 0, v[134:135]
	global_load_lds_dwordx4 v[222:223], off
	v_lshl_add_u64 v[222:223], s[54:55], 0, v[136:137]
	s_add_i32 m0, s53, 0x2000
	s_nop 0
	global_load_lds_dwordx4 v[222:223], off
	v_lshl_add_u64 v[222:223], s[26:27], 0, v[130:131]
	s_mov_b32 m0, s34
	s_nop 0
	global_load_lds_dwordx4 v[222:223], off
	s_mov_b32 m0, s35
	s_nop 0
	global_load_lds_dwordx4 v[224:225], off
	s_waitcnt vmcnt(8)
	s_waitcnt lgkmcnt(0)
	s_barrier
; #define PG8_STAGE(bufoff, gbase, voff) do { _Pragma("unroll") for (int _i = 0; _i < 2; ++_i) \
;         __builtin_amdgcn_global_load_lds((const unsigned*)((const char*)(gbase) + (voff)[_i]), (PG8_LAS unsigned*)(lds + (bufoff) + ldsw + _i * 8192), 16, 0, 0); } while (0)
; #define PG8_LDA(dst, b, h) do { _Pragma("unroll") for (int m = 0; m < 4; ++m) _Pragma("unroll") for (int k = 0; k < 2; ++k) dst[m][k] = *(const PG8_LAS bf16x8*)(lds + PG8_SA(b, h) + aoff + m * 2048 + k * 1024); } while (0)
; #define PG8_LDB(dst, b, h) do { _Pragma("unroll") for (int n = 0; n < 2; ++n) _Pragma("unroll") for (int k = 0; k < 2; ++k) dst[n][k] = *(const PG8_LAS bf16x8*)(lds + PG8_SB(b, h) + boff + n * 2048 + k * 1024); } while (0)
; #define PG8_MMA(ai, bj, At, Bt) do { __builtin_amdgcn_s_setprio(1); _Pragma("unroll") for (int m = 0; m < 4; ++m) _Pragma("unroll") for (int n = 0; n < 2; ++n) _Pragma("unroll") for (int k = 0; k < 2; ++k) \
;         acc[ai][bj][m][n] = __builtin_amdgcn_mfma_f32_16x16x32_bf16(Bt[n][k], At[m][k], acc[ai][bj][m][n], 0, 0, 0); __builtin_amdgcn_s_setprio(0); } while (0)
; #define PG8_WAIT_V(n) asm volatile("s_waitcnt vmcnt(" #n ")" ::: "memory")
; #define PG8_WAIT_L(n) asm volatile("s_waitcnt lgkmcnt(" #n ")" ::: "memory")
; #define PG8_BAR __builtin_amdgcn_s_barrier()
; #define PG8_SCHED __builtin_amdgcn_sched_barrier(0)
; template <class Epi, class Sched>
; __device__ __forceinline__ void gemm_phase(PG8_LAS unsigned char* lds, const Gemm g, const Sched& S, const Epi& E) {
;     ...
;             PG8_WAIT_V(8); PG8_WAIT_L(0); PG8_BAR; PG8_MMA(1, 0, At, B0); PG8_MMA(1, 1, At, B1); PG8_BAR; PG8_SCHED;
;             PG8_LDB(B0, 1, 0); PG8_LDB(B1, 1, 1); PG8_SCHED; PG8_LDA(At, 1, 0); PG8_STAGE(PG8_SA(0, 1), a2 + hstepA, voffA);
;             PG8_WAIT_V(8); PG8_WAIT_L(0); PG8_BAR; PG8_MMA(0, 0, At, B0); PG8_MMA(0, 1, At, B1); PG8_BAR; PG8_SCHED;
	s_setprio 1
	s_waitcnt lgkmcnt(0)
	v_mfma_f32_16x16x32_bf16 v[62:65], v[146:149], v[186:189], v[62:65]
	v_mfma_f32_16x16x32_bf16 v[58:61], v[162:165], v[186:189], v[58:61]
	v_mfma_f32_16x16x32_bf16 v[46:49], v[146:149], v[194:197], v[46:49]
	v_mfma_f32_16x16x32_bf16 v[42:45], v[162:165], v[194:197], v[42:45]
	v_mfma_f32_16x16x32_bf16 v[30:33], v[146:149], v[202:205], v[30:33]
	v_mfma_f32_16x16x32_bf16 v[26:29], v[162:165], v[202:205], v[26:29]
	v_mfma_f32_16x16x32_bf16 v[14:17], v[146:149], v[214:217], v[14:17]
	v_mfma_f32_16x16x32_bf16 v[10:13], v[162:165], v[214:217], v[10:13]
	v_mfma_f32_16x16x32_bf16 v[62:65], v[158:161], v[190:193], v[62:65]
	v_mfma_f32_16x16x32_bf16 v[58:61], v[166:169], v[190:193], v[58:61]
	v_mfma_f32_16x16x32_bf16 v[46:49], v[158:161], v[198:201], v[46:49]
	v_mfma_f32_16x16x32_bf16 v[42:45], v[166:169], v[198:201], v[42:45]
	v_mfma_f32_16x16x32_bf16 v[30:33], v[158:161], v[210:213], v[30:33]
	v_mfma_f32_16x16x32_bf16 v[26:29], v[166:169], v[210:213], v[26:29]
	v_mfma_f32_16x16x32_bf16 v[14:17], v[158:161], v[218:221], v[14:17]
	v_mfma_f32_16x16x32_bf16 v[10:13], v[166:169], v[218:221], v[10:13]
	s_setprio 0
	s_setprio 1
	v_mfma_f32_16x16x32_bf16 v[54:57], v[170:173], v[186:189], v[54:57]
	v_mfma_f32_16x16x32_bf16 v[50:53], v[178:181], v[186:189], v[50:53]
	v_mfma_f32_16x16x32_bf16 v[38:41], v[170:173], v[194:197], v[38:41]
	v_mfma_f32_16x16x32_bf16 v[34:37], v[178:181], v[194:197], v[34:37]
	v_mfma_f32_16x16x32_bf16 v[22:25], v[170:173], v[202:205], v[22:25]
	v_mfma_f32_16x16x32_bf16 v[18:21], v[178:181], v[202:205], v[18:21]
	v_mfma_f32_16x16x32_bf16 v[6:9], v[170:173], v[214:217], v[6:9]
	v_mfma_f32_16x16x32_bf16 v[2:5], v[178:181], v[214:217], v[2:5]
	v_mfma_f32_16x16x32_bf16 v[54:57], v[174:177], v[190:193], v[54:57]
	v_mfma_f32_16x16x32_bf16 v[50:53], v[182:185], v[190:193], v[50:53]
	v_mfma_f32_16x16x32_bf16 v[38:41], v[174:177], v[198:201], v[38:41]
	v_mfma_f32_16x16x32_bf16 v[34:37], v[182:185], v[198:201], v[34:37]
	v_mfma_f32_16x16x32_bf16 v[22:25], v[174:177], v[210:213], v[22:25]
	v_mfma_f32_16x16x32_bf16 v[18:21], v[182:185], v[210:213], v[18:21]
	v_mfma_f32_16x16x32_bf16 v[6:9], v[174:177], v[218:221], v[6:9]
	v_mfma_f32_16x16x32_bf16 v[2:5], v[182:185], v[218:221], v[2:5]
	s_setprio 0
	s_barrier
	s_add_i32 s53, 0, 0x18000
	s_add_i32 s54, 0, 0x1c000
	v_add_u32_e32 v166, s53, v152
	v_add_u32_e32 v182, s54, v152
	ds_read_b128 v[146:149], v166
	ds_read_b128 v[158:161], v166 offset:1024
	ds_read_b128 v[162:165], v166 offset:2048
	ds_read_b128 v[166:169], v166 offset:3072
	ds_read_b128 v[170:173], v182
	ds_read_b128 v[174:177], v182 offset:1024
	ds_read_b128 v[178:181], v182 offset:2048
	ds_read_b128 v[182:185], v182 offset:3072
	s_add_u32 s26, s26, 0x2b0000
	s_addc_u32 s27, s27, 0
	s_mov_b32 m0, s36
	v_lshl_add_u64 v[226:227], s[26:27], 0, v[130:131]
	ds_read_b128 v[186:189], v156 offset:32768
	ds_read_b128 v[190:193], v156 offset:33792
	ds_read_b128 v[194:197], v156 offset:34816
	ds_read_b128 v[198:201], v156 offset:35840
	ds_read_b128 v[202:205], v156 offset:36864
	ds_read_b128 v[210:213], v156 offset:37888
	ds_read_b128 v[214:217], v156 offset:38912
	ds_read_b128 v[218:221], v156 offset:39936
	global_load_lds_dwordx4 v[226:227], off
	v_lshl_add_u64 v[226:227], s[26:27], 0, v[134:135]
	s_mov_b32 m0, s37
	s_nop 0
	global_load_lds_dwordx4 v[226:227], off
	s_waitcnt vmcnt(8)
	s_waitcnt lgkmcnt(0)
	s_barrier
	s_setprio 1
	s_waitcnt lgkmcnt(0)
	v_mfma_f32_16x16x32_bf16 v[126:129], v[146:149], v[186:189], v[126:129]
	v_mfma_f32_16x16x32_bf16 v[122:125], v[162:165], v[186:189], v[122:125]
	v_mfma_f32_16x16x32_bf16 v[110:113], v[146:149], v[194:197], v[110:113]
	v_mfma_f32_16x16x32_bf16 v[106:109], v[162:165], v[194:197], v[106:109]
	v_mfma_f32_16x16x32_bf16 v[94:97], v[146:149], v[202:205], v[94:97]
	v_mfma_f32_16x16x32_bf16 v[90:93], v[162:165], v[202:205], v[90:93]
	v_mfma_f32_16x16x32_bf16 v[78:81], v[146:149], v[214:217], v[78:81]
	v_mfma_f32_16x16x32_bf16 v[74:77], v[162:165], v[214:217], v[74:77]
	v_mfma_f32_16x16x32_bf16 v[126:129], v[158:161], v[190:193], v[126:129]
	v_mfma_f32_16x16x32_bf16 v[122:125], v[166:169], v[190:193], v[122:125]
	v_mfma_f32_16x16x32_bf16 v[110:113], v[158:161], v[198:201], v[110:113]
	v_mfma_f32_16x16x32_bf16 v[106:109], v[166:169], v[198:201], v[106:109]
	v_mfma_f32_16x16x32_bf16 v[94:97], v[158:161], v[210:213], v[94:97]
	v_mfma_f32_16x16x32_bf16 v[90:93], v[166:169], v[210:213], v[90:93]
	v_mfma_f32_16x16x32_bf16 v[78:81], v[158:161], v[218:221], v[78:81]
	v_mfma_f32_16x16x32_bf16 v[74:77], v[166:169], v[218:221], v[74:77]
	s_setprio 0
	s_setprio 1
	v_mfma_f32_16x16x32_bf16 v[118:121], v[170:173], v[186:189], v[118:121]
	v_mfma_f32_16x16x32_bf16 v[114:117], v[178:181], v[186:189], v[114:117]
	v_mfma_f32_16x16x32_bf16 v[102:105], v[170:173], v[194:197], v[102:105]
	v_mfma_f32_16x16x32_bf16 v[98:101], v[178:181], v[194:197], v[98:101]
	v_mfma_f32_16x16x32_bf16 v[86:89], v[170:173], v[202:205], v[86:89]
	v_mfma_f32_16x16x32_bf16 v[82:85], v[178:181], v[202:205], v[82:85]
	v_mfma_f32_16x16x32_bf16 v[70:73], v[170:173], v[214:217], v[70:73]
	v_mfma_f32_16x16x32_bf16 v[66:69], v[178:181], v[214:217], v[66:69]
	v_mfma_f32_16x16x32_bf16 v[118:121], v[174:177], v[190:193], v[118:121]
	v_mfma_f32_16x16x32_bf16 v[114:117], v[182:185], v[190:193], v[114:117]
	v_mfma_f32_16x16x32_bf16 v[102:105], v[174:177], v[198:201], v[102:105]
	v_mfma_f32_16x16x32_bf16 v[98:101], v[182:185], v[198:201], v[98:101]
	v_mfma_f32_16x16x32_bf16 v[86:89], v[174:177], v[210:213], v[86:89]
	v_mfma_f32_16x16x32_bf16 v[82:85], v[182:185], v[210:213], v[82:85]
	v_mfma_f32_16x16x32_bf16 v[70:73], v[174:177], v[218:221], v[70:73]
	v_mfma_f32_16x16x32_bf16 v[66:69], v[182:185], v[218:221], v[66:69]
	s_setprio 0
	s_barrier
; #define PG8_STAGE(bufoff, gbase, voff) do { _Pragma("unroll") for (int _i = 0; _i < 2; ++_i) \
;         __builtin_amdgcn_global_load_lds((const unsigned*)((const char*)(gbase) + (voff)[_i]), (PG8_LAS unsigned*)(lds + (bufoff) + ldsw + _i * 8192), 16, 0, 0); } while (0)
; #define PG8_LDA(dst, b, h) do { _Pragma("unroll") for (int m = 0; m < 4; ++m) _Pragma("unroll") for (int k = 0; k < 2; ++k) dst[m][k] = *(const PG8_LAS bf16x8*)(lds + PG8_SA(b, h) + aoff + m * 2048 + k * 1024); } while (0)
; #define PG8_MMA(ai, bj, At, Bt) do { __builtin_amdgcn_s_setprio(1); _Pragma("unroll") for (int m = 0; m < 4; ++m) _Pragma("unroll") for (int n = 0; n < 2; ++n) _Pragma("unroll") for (int k = 0; k < 2; ++k) \
;         acc[ai][bj][m][n] = __builtin_amdgcn_mfma_f32_16x16x32_bf16(Bt[n][k], At[m][k], acc[ai][bj][m][n], 0, 0, 0); __builtin_amdgcn_s_setprio(0); } while (0)
; #define PG8_WAIT_V(n) asm volatile("s_waitcnt vmcnt(" #n ")" ::: "memory")
; #define PG8_WAIT_L(n) asm volatile("s_waitcnt lgkmcnt(" #n ")" ::: "memory")
; #define PG8_BAR __builtin_amdgcn_s_barrier()
; #define PG8_SCHED __builtin_amdgcn_sched_barrier(0)
; template <class Epi, class Sched>
; __device__ __forceinline__ void gemm_phase(PG8_LAS unsigned char* lds, const Gemm g, const Sched& S, const Epi& E) {
;     ...
;             PG8_LDA(At, 1, 1); PG8_STAGE(PG8_SB(1, 0), b3, voffB); PG8_STAGE(PG8_SB(1, 1), b3 + hstepB, voffB); PG8_STAGE(PG8_SA(1, 0), a3, voffA);
;             PG8_WAIT_V(8); PG8_WAIT_L(0); PG8_BAR; PG8_MMA(1, 0, At, B0); PG8_MMA(1, 1, At, B1); PG8_BAR; PG8_SCHED;
	s_add_i32 s26, s53, s33
	v_lshl_add_u64 v[150:151], v[150:151], 0, s[16:17]
	s_mov_b32 m0, s26
	ds_read_b128 v[186:189], v156 offset:49152
	ds_read_b128 v[190:193], v156 offset:50176
	ds_read_b128 v[194:197], v156 offset:51200
	ds_read_b128 v[198:201], v156 offset:52224
	ds_read_b128 v[202:205], v156 offset:53248
	ds_read_b128 v[210:213], v156 offset:54272
	ds_read_b128 v[214:217], v156 offset:55296
	ds_read_b128 v[218:221], v156 offset:56320
	global_load_lds_dwordx4 v[150:151], off
	s_add_i32 m0, s26, 0x2000
	s_add_u32 s24, s24, 0x2b0080
	v_lshl_add_u64 v[150:151], v[206:207], 0, s[16:17]
	s_addc_u32 s25, s25, 0
	s_add_i32 s26, s54, s33
	global_load_lds_dwordx4 v[150:151], off
	v_lshl_add_u64 v[150:151], s[24:25], 0, v[132:133]
	s_mov_b32 m0, s26
	s_nop 0
	global_load_lds_dwordx4 v[150:151], off
	v_lshl_add_u64 v[150:151], s[24:25], 0, v[136:137]
	s_add_i32 m0, s26, 0x2000
	s_nop 0
	global_load_lds_dwordx4 v[150:151], off
	v_lshl_add_u64 v[150:151], v[222:223], 0, s[16:17]
	s_mov_b32 m0, s39
	s_nop 0
	global_load_lds_dwordx4 v[150:151], off
	v_lshl_add_u64 v[150:151], v[224:225], 0, s[16:17]
	s_mov_b32 m0, s40
	s_nop 0
	global_load_lds_dwordx4 v[150:151], off
	s_waitcnt vmcnt(8)
	s_waitcnt lgkmcnt(0)
	s_barrier
	s_setprio 1
	s_waitcnt lgkmcnt(0)
	v_mfma_f32_16x16x32_bf16 v[62:65], v[146:149], v[186:189], v[62:65]
	v_mfma_f32_16x16x32_bf16 v[58:61], v[162:165], v[186:189], v[58:61]
	v_mfma_f32_16x16x32_bf16 v[46:49], v[146:149], v[194:197], v[46:49]
	v_mfma_f32_16x16x32_bf16 v[42:45], v[162:165], v[194:197], v[42:45]
	v_mfma_f32_16x16x32_bf16 v[30:33], v[146:149], v[202:205], v[30:33]
	v_mfma_f32_16x16x32_bf16 v[26:29], v[162:165], v[202:205], v[26:29]
	v_mfma_f32_16x16x32_bf16 v[14:17], v[146:149], v[214:217], v[14:17]
	v_mfma_f32_16x16x32_bf16 v[10:13], v[162:165], v[214:217], v[10:13]
	v_mfma_f32_16x16x32_bf16 v[62:65], v[158:161], v[190:193], v[62:65]
	v_mfma_f32_16x16x32_bf16 v[58:61], v[166:169], v[190:193], v[58:61]
	v_mfma_f32_16x16x32_bf16 v[46:49], v[158:161], v[198:201], v[46:49]
	v_mfma_f32_16x16x32_bf16 v[42:45], v[166:169], v[198:201], v[42:45]
	v_mfma_f32_16x16x32_bf16 v[30:33], v[158:161], v[210:213], v[30:33]
	v_mfma_f32_16x16x32_bf16 v[26:29], v[166:169], v[210:213], v[26:29]
	v_mfma_f32_16x16x32_bf16 v[14:17], v[158:161], v[218:221], v[14:17]
	v_mfma_f32_16x16x32_bf16 v[10:13], v[166:169], v[218:221], v[10:13]
	s_setprio 0
	s_setprio 1
	v_mfma_f32_16x16x32_bf16 v[54:57], v[170:173], v[186:189], v[54:57]
	v_mfma_f32_16x16x32_bf16 v[50:53], v[178:181], v[186:189], v[50:53]
	v_mfma_f32_16x16x32_bf16 v[38:41], v[170:173], v[194:197], v[38:41]
	v_mfma_f32_16x16x32_bf16 v[34:37], v[178:181], v[194:197], v[34:37]
	v_mfma_f32_16x16x32_bf16 v[22:25], v[170:173], v[202:205], v[22:25]
	v_mfma_f32_16x16x32_bf16 v[18:21], v[178:181], v[202:205], v[18:21]
	v_mfma_f32_16x16x32_bf16 v[6:9], v[170:173], v[214:217], v[6:9]
	v_mfma_f32_16x16x32_bf16 v[2:5], v[178:181], v[214:217], v[2:5]
	v_mfma_f32_16x16x32_bf16 v[54:57], v[174:177], v[190:193], v[54:57]
	v_mfma_f32_16x16x32_bf16 v[50:53], v[182:185], v[190:193], v[50:53]
	v_mfma_f32_16x16x32_bf16 v[38:41], v[174:177], v[198:201], v[38:41]
	v_mfma_f32_16x16x32_bf16 v[34:37], v[182:185], v[198:201], v[34:37]
	v_mfma_f32_16x16x32_bf16 v[22:25], v[174:177], v[210:213], v[22:25]
	v_mfma_f32_16x16x32_bf16 v[18:21], v[182:185], v[210:213], v[18:21]
	v_mfma_f32_16x16x32_bf16 v[6:9], v[174:177], v[218:221], v[6:9]
	v_mfma_f32_16x16x32_bf16 v[2:5], v[182:185], v[218:221], v[2:5]
	s_setprio 0
	s_add_i32 s52, s52, 2
	s_add_u32 s22, s22, 0x100
	s_addc_u32 s23, s23, 0
	s_add_u32 s50, s50, 0x100
	s_addc_u32 s51, s51, 0
	s_cmpk_gt_u32 s52, 0xa9
	s_barrier
	s_cbranch_scc0 .LBB0_962
	s_and_b64 vcc, exec, s[18:19]
	s_cbranch_vccz .LBB0_965
	s_barrier
